# diff-attn: second half of each tile's exp/rowsum/pack deferred into the next step's QK MFMA phase (VALU idle there); P5/P10 output stores write-through
# speedup vs baseline: 1.0307x; 1.0233x over previous
.LBB0_385:
	s_add_i32 s93, s76, -4
	s_add_i32 s92, s72, s76
	s_add_i32 s0, s76, -1
	s_cmp_lt_u32 s0, s82
	s_cselect_b32 s78, s0, s33
	s_add_i32 s91, s76, -2
	s_cmp_lt_u32 s91, s82
	v_mad_u64_u32 v[2:3], s[0:1], s78, v228, v[220:221]
	s_cselect_b32 s84, s91, s33
	s_and_b32 s0, s77, 0x6000
	s_add_i32 m0, s67, s0
	s_lshl_b64 s[0:1], s[84:85], 7
	s_add_u32 s0, s74, s0
	v_lshl_add_u64 v[2:3], v[2:3], 0, s[86:87]
	s_addc_u32 s1, s75, s1
	global_load_lds_dwordx4 v[2:3], off
	v_lshl_add_u64 v[2:3], s[0:1], 0, v[204:205]
	s_add_i32 s0, s2, 0xc000
	s_and_b32 s0, s0, 0xc000
	s_add_i32 s0, s67, s0
	s_add_i32 m0, s0, 0x8000
	s_nop 0
	global_load_lds_dwordx4 v[2:3], off
	v_lshl_add_u64 v[2:3], v[2:3], 0, s[88:89]
	s_add_i32 m0, s0, 0xa000
	s_and_b32 s0, s2, 0xc000
	global_load_lds_dwordx4 v[2:3], off
	s_cmp_le_u32 s93, s83
	v_add_u32_e32 v243, s0, v230
	s_cselect_b64 s[96:97], -1, 0
	s_cmp_gt_u32 s93, s83
	s_mov_b64 s[0:1], -1
	s_cbranch_scc1 .LBB0_389
	s_cmp_eq_u32 s93, 1
	s_cbranch_scc1 .Lmy_oddqk_first
	s_add_i32 s0, s77, 0xffffa000
	s_and_b32 s0, s0, 0x6000
	v_add_u32_e32 v244, s0, v229
	v_add_u32_e32 v245, v244, v232
	ds_read_b128 v[2:5], v245
	ds_read_b128 v[10:13], v241
	ds_read_b128 v[6:9], v245 offset:4096
	v_add_u32_e32 v245, v244, v234
	ds_read_b128 v[18:21], v245
	ds_read_b128 v[14:17], v241 offset:1024
	ds_read_b128 v[22:25], v245 offset:4096
	v_add_u32_e32 v245, v244, v236
	ds_read_b128 v[26:29], v245
	ds_read_b128 v[34:37], v241 offset:2048
	ds_read_b128 v[30:33], v245 offset:4096
	v_add_u32_e32 v245, v244, v238
	ds_read_b128 v[38:41], v245
	ds_read_b128 v[46:49], v241 offset:3072
	ds_read_b128 v[42:45], v245 offset:4096
	s_waitcnt lgkmcnt(10)
	v_mfma_f32_32x32x16_bf16 v[146:161], v[2:5], v[10:13], 0
	v_exp_f32_e32 v246, v50
	v_exp_f32_e32 v247, v51
	v_add_f32_e32 v242, v246, v242
	v_add_f32_e32 v242, v247, v242
	v_cvt_pk_bf16_f32 v170, v246, v247
	s_waitcnt lgkmcnt(9)
	v_mfma_f32_32x32x16_bf16 v[130:145], v[6:9], v[10:13], 0
	v_exp_f32_e32 v246, v52
	v_exp_f32_e32 v247, v53
	v_add_f32_e32 v242, v246, v242
	v_add_f32_e32 v242, v247, v242
	v_cvt_pk_bf16_f32 v171, v246, v247
	s_waitcnt lgkmcnt(7)
	v_mfma_f32_32x32x16_bf16 v[146:161], v[18:21], v[14:17], v[146:161]
	v_exp_f32_e32 v246, v54
	v_exp_f32_e32 v247, v55
	v_add_f32_e32 v242, v246, v242
	v_add_f32_e32 v242, v247, v242
	v_cvt_pk_bf16_f32 v172, v246, v247
	s_waitcnt lgkmcnt(6)
	v_mfma_f32_32x32x16_bf16 v[130:145], v[22:25], v[14:17], v[130:145]
	v_exp_f32_e32 v246, v56
	v_exp_f32_e32 v247, v57
	v_add_f32_e32 v242, v246, v242
	v_add_f32_e32 v242, v247, v242
	v_cvt_pk_bf16_f32 v173, v246, v247
	s_waitcnt lgkmcnt(4)
	v_mfma_f32_32x32x16_bf16 v[146:161], v[26:29], v[34:37], v[146:161]
	v_exp_f32_e32 v246, v58
	v_exp_f32_e32 v247, v59
	v_add_f32_e32 v242, v246, v242
	v_add_f32_e32 v242, v247, v242
	v_cvt_pk_bf16_f32 v174, v246, v247
	s_waitcnt lgkmcnt(3)
	v_mfma_f32_32x32x16_bf16 v[130:145], v[30:33], v[34:37], v[130:145]
	v_exp_f32_e32 v246, v60
	v_exp_f32_e32 v247, v61
	v_add_f32_e32 v242, v246, v242
	v_add_f32_e32 v242, v247, v242
	v_cvt_pk_bf16_f32 v175, v246, v247
	s_waitcnt lgkmcnt(1)
	v_mfma_f32_32x32x16_bf16 v[146:161], v[38:41], v[46:49], v[146:161]
	v_exp_f32_e32 v246, v62
	v_exp_f32_e32 v247, v63
	v_add_f32_e32 v242, v246, v242
	v_add_f32_e32 v242, v247, v242
	v_cvt_pk_bf16_f32 v176, v246, v247
	s_waitcnt lgkmcnt(0)
	v_mfma_f32_32x32x16_bf16 v[130:145], v[42:45], v[46:49], v[130:145]
	v_exp_f32_e32 v246, v64
	v_exp_f32_e32 v247, v65
	v_add_f32_e32 v242, v246, v242
	v_add_f32_e32 v242, v247, v242
	v_cvt_pk_bf16_f32 v177, v246, v247
	s_branch .Lmy_oddqk_join
.Lmy_oddqk_first:
	s_add_i32 s0, s77, 0xffffa000
	s_and_b32 s0, s0, 0x6000
	v_add_u32_e32 v244, s0, v229
	v_add_u32_e32 v245, v244, v232
	ds_read_b128 v[2:5], v245
	ds_read_b128 v[10:13], v241
	ds_read_b128 v[6:9], v245 offset:4096
	v_add_u32_e32 v245, v244, v234
	ds_read_b128 v[18:21], v245
	ds_read_b128 v[14:17], v241 offset:1024
	ds_read_b128 v[22:25], v245 offset:4096
	v_add_u32_e32 v245, v244, v236
	ds_read_b128 v[26:29], v245
	ds_read_b128 v[34:37], v241 offset:2048
	ds_read_b128 v[30:33], v245 offset:4096
	v_add_u32_e32 v245, v244, v238
	ds_read_b128 v[38:41], v245
	ds_read_b128 v[46:49], v241 offset:3072
	ds_read_b128 v[42:45], v245 offset:4096
	s_waitcnt lgkmcnt(10)
	v_mfma_f32_32x32x16_bf16 v[146:161], v[2:5], v[10:13], 0
	s_waitcnt lgkmcnt(9)
	v_mfma_f32_32x32x16_bf16 v[130:145], v[6:9], v[10:13], 0
	s_waitcnt lgkmcnt(7)
	v_mfma_f32_32x32x16_bf16 v[146:161], v[18:21], v[14:17], v[146:161]
	s_waitcnt lgkmcnt(6)
	v_mfma_f32_32x32x16_bf16 v[130:145], v[22:25], v[14:17], v[130:145]
	s_waitcnt lgkmcnt(4)
	v_mfma_f32_32x32x16_bf16 v[146:161], v[26:29], v[34:37], v[146:161]
	s_waitcnt lgkmcnt(3)
	v_mfma_f32_32x32x16_bf16 v[130:145], v[30:33], v[34:37], v[130:145]
	s_waitcnt lgkmcnt(1)
	v_mfma_f32_32x32x16_bf16 v[146:161], v[38:41], v[46:49], v[146:161]
	s_waitcnt lgkmcnt(0)
	v_mfma_f32_32x32x16_bf16 v[130:145], v[42:45], v[46:49], v[130:145]
.Lmy_oddqk_join:
	s_cmp_lg_u32 s92, 4
	s_cbranch_scc1 .LBB0_388
	v_mov_b32_e32 v0, v240
	s_nop 0
	v_cmp_gt_i32_e64 s[62:63], 22, v0
	v_cmp_gt_i32_e64 s[64:65], 23, v0
	v_cmp_gt_i32_e64 s[60:61], 21, v0
	s_and_b64 s[62:63], s[64:65], s[62:63]
	v_cmp_gt_i32_e64 s[58:59], 20, v0
	s_and_b64 s[60:61], s[62:63], s[60:61]
	v_cmp_gt_i32_e64 s[56:57], 19, v0
	s_and_b64 s[58:59], s[60:61], s[58:59]
	v_cmp_gt_i32_e64 s[54:55], 18, v0
	s_and_b64 s[56:57], s[58:59], s[56:57]
	v_cmp_gt_i32_e64 s[52:53], 17, v0
	s_and_b64 s[54:55], s[56:57], s[54:55]
	v_cmp_gt_i32_e64 s[50:51], 16, v0
	s_and_b64 s[52:53], s[54:55], s[52:53]
	v_cmp_gt_i32_e64 s[48:49], 7, v0
	s_and_b64 s[50:51], s[52:53], s[50:51]
	v_cmp_gt_i32_e64 s[46:47], 6, v0
	s_and_b64 s[48:49], s[50:51], s[48:49]
	v_cmp_gt_i32_e64 s[44:45], 5, v0
	s_and_b64 s[46:47], s[48:49], s[46:47]
	v_cmp_gt_i32_e64 s[42:43], 4, v0
	s_and_b64 s[44:45], s[46:47], s[44:45]
	v_cmp_gt_i32_e64 s[40:41], 3, v0
	s_and_b64 s[42:43], s[44:45], s[42:43]
	v_cmp_gt_i32_e64 s[38:39], 2, v0
	s_and_b64 s[40:41], s[42:43], s[40:41]
	v_cmp_gt_i32_e64 s[36:37], 1, v0
	s_and_b64 s[38:39], s[40:41], s[38:39]
	v_cmp_gt_i32_e64 s[34:35], 0, v0
	s_and_b64 s[36:37], s[38:39], s[36:37]
	s_and_b64 s[34:35], s[36:37], s[34:35]
	v_cmp_gt_i32_e64 s[30:31], 54, v0
	v_cndmask_b32_e64 v146, v146, v227, s[34:35]
	v_cmp_gt_i32_e64 s[34:35], 55, v0
	v_cmp_gt_i32_e64 s[28:29], 53, v0
	s_and_b64 s[30:31], s[34:35], s[30:31]
	v_cmp_gt_i32_e64 s[26:27], 52, v0
	s_and_b64 s[28:29], s[30:31], s[28:29]
	v_cmp_gt_i32_e64 s[24:25], 51, v0
	s_and_b64 s[26:27], s[28:29], s[26:27]
	v_cmp_gt_i32_e64 s[22:23], 50, v0
	s_and_b64 s[24:25], s[26:27], s[24:25]
	v_cmp_gt_i32_e64 s[20:21], 49, v0
	s_and_b64 s[22:23], s[24:25], s[22:23]
	v_cmp_gt_i32_e64 s[18:19], 48, v0
	s_and_b64 s[20:21], s[22:23], s[20:21]
	v_cmp_gt_i32_e64 s[16:17], 39, v0
	s_and_b64 s[18:19], s[20:21], s[18:19]
	v_cmp_gt_i32_e64 s[14:15], 38, v0
	s_and_b64 s[16:17], s[18:19], s[16:17]
	v_cmp_gt_i32_e64 s[12:13], 37, v0
	s_and_b64 s[14:15], s[16:17], s[14:15]
	v_cmp_gt_i32_e64 s[10:11], 36, v0
	s_and_b64 s[12:13], s[14:15], s[12:13]
	v_cmp_gt_i32_e64 s[8:9], 35, v0
	s_and_b64 s[10:11], s[12:13], s[10:11]
	v_cmp_gt_i32_e64 s[6:7], 34, v0
	s_and_b64 s[8:9], s[10:11], s[8:9]
	v_cmp_gt_i32_e64 s[0:1], 33, v0
	s_and_b64 s[6:7], s[8:9], s[6:7]
	v_cmp_gt_i32_e32 vcc, 32, v0
	s_and_b64 s[0:1], s[6:7], s[0:1]
	s_and_b64 vcc, s[0:1], vcc
	v_cndmask_b32_e64 v161, v161, v227, s[64:65]
	v_cndmask_b32_e64 v160, v160, v227, s[62:63]
	v_cndmask_b32_e64 v159, v159, v227, s[60:61]
	v_cndmask_b32_e64 v158, v158, v227, s[58:59]
	v_cndmask_b32_e64 v157, v157, v227, s[56:57]
	v_cndmask_b32_e64 v156, v156, v227, s[54:55]
	v_cndmask_b32_e64 v155, v155, v227, s[52:53]
	v_cndmask_b32_e64 v154, v154, v227, s[50:51]
	v_cndmask_b32_e64 v153, v153, v227, s[48:49]
	v_cndmask_b32_e64 v152, v152, v227, s[46:47]
	v_cndmask_b32_e64 v151, v151, v227, s[44:45]
	v_cndmask_b32_e64 v150, v150, v227, s[42:43]
	v_cndmask_b32_e64 v149, v149, v227, s[40:41]
	v_cndmask_b32_e64 v148, v148, v227, s[38:39]
	v_cndmask_b32_e64 v147, v147, v227, s[36:37]
	v_cndmask_b32_e64 v145, v145, v227, s[34:35]
	v_cndmask_b32_e64 v144, v144, v227, s[30:31]
	v_cndmask_b32_e64 v143, v143, v227, s[28:29]
	v_cndmask_b32_e64 v142, v142, v227, s[26:27]
	v_cndmask_b32_e64 v141, v141, v227, s[24:25]
	v_cndmask_b32_e64 v140, v140, v227, s[22:23]
	v_cndmask_b32_e64 v139, v139, v227, s[20:21]
	v_cndmask_b32_e64 v138, v138, v227, s[18:19]
	v_cndmask_b32_e64 v137, v137, v227, s[16:17]
	v_cndmask_b32_e64 v136, v136, v227, s[14:15]
	v_cndmask_b32_e64 v135, v135, v227, s[12:13]
	v_cndmask_b32_e64 v134, v134, v227, s[10:11]
	v_cndmask_b32_e64 v133, v133, v227, s[8:9]
	v_cndmask_b32_e64 v132, v132, v227, s[6:7]
	v_cndmask_b32_e64 v131, v131, v227, s[0:1]
	v_cndmask_b32_e32 v130, v130, v227, vcc
.LBB0_388:
	v_add_u32_e32 v18, v243, v233
	v_add_u32_e32 v19, v243, v235
	v_add_u32_e32 v20, v243, v237
	v_add_u32_e32 v21, v243, v239
	ds_read_b128 v[2:5], v18 offset:32768
	ds_read_b128 v[6:9], v18 offset:36864
	ds_read_b128 v[10:13], v18 offset:40960
	s_nop 5
	v_exp_f32_e32 v22, v146
	s_waitcnt lgkmcnt(2)
	v_mfma_f32_32x32x16_bf16 v[114:129], v[2:5], v[162:165], v[114:129]
	ds_read_b128 v[14:17], v18 offset:45056
	v_exp_f32_e32 v23, v147
	s_waitcnt lgkmcnt(2)
	v_mfma_f32_32x32x16_bf16 v[98:113], v[6:9], v[162:165], v[98:113]
	ds_read_b128 v[2:5], v19 offset:32768
	v_add_f32_e32 v24, v22, v23
	v_cvt_pk_bf16_f32 v178, v22, v23
	v_exp_f32_e32 v22, v148
	s_waitcnt lgkmcnt(2)
	v_mfma_f32_32x32x16_bf16 v[82:97], v[10:13], v[162:165], v[82:97]
	ds_read_b128 v[6:9], v19 offset:36864
	v_exp_f32_e32 v23, v149
	s_waitcnt lgkmcnt(2)
	v_mfma_f32_32x32x16_bf16 v[66:81], v[14:17], v[162:165], v[66:81]
	ds_read_b128 v[10:13], v19 offset:40960
	v_add_f32_e32 v24, v22, v24
	v_add_f32_e32 v24, v23, v24
	v_cvt_pk_bf16_f32 v179, v22, v23
	v_exp_f32_e32 v22, v150
	s_waitcnt lgkmcnt(2)
	v_mfma_f32_32x32x16_bf16 v[114:129], v[2:5], v[166:169], v[114:129]
	ds_read_b128 v[14:17], v19 offset:45056
	v_exp_f32_e32 v23, v151
	s_waitcnt lgkmcnt(2)
	v_mfma_f32_32x32x16_bf16 v[98:113], v[6:9], v[166:169], v[98:113]
	ds_read_b128 v[2:5], v20 offset:32768
	v_add_f32_e32 v24, v22, v24
	v_add_f32_e32 v24, v23, v24
	v_cvt_pk_bf16_f32 v180, v22, v23
	v_exp_f32_e32 v22, v152
	s_waitcnt lgkmcnt(2)
	v_mfma_f32_32x32x16_bf16 v[82:97], v[10:13], v[166:169], v[82:97]
	ds_read_b128 v[6:9], v20 offset:36864
	v_exp_f32_e32 v23, v153
	s_waitcnt lgkmcnt(2)
	v_mfma_f32_32x32x16_bf16 v[66:81], v[14:17], v[166:169], v[66:81]
	ds_read_b128 v[10:13], v20 offset:40960
	v_add_f32_e32 v24, v22, v24
	v_add_f32_e32 v24, v23, v24
	v_cvt_pk_bf16_f32 v181, v22, v23
	v_exp_f32_e32 v22, v154
	s_waitcnt lgkmcnt(2)
	v_mfma_f32_32x32x16_bf16 v[114:129], v[2:5], v[170:173], v[114:129]
	ds_read_b128 v[14:17], v20 offset:45056
	v_exp_f32_e32 v23, v155
	s_waitcnt lgkmcnt(2)
	v_mfma_f32_32x32x16_bf16 v[98:113], v[6:9], v[170:173], v[98:113]
	ds_read_b128 v[2:5], v21 offset:32768
	v_add_f32_e32 v24, v22, v24
	v_add_f32_e32 v24, v23, v24
	v_cvt_pk_bf16_f32 v146, v22, v23
	v_exp_f32_e32 v22, v156
	s_waitcnt lgkmcnt(2)
	v_mfma_f32_32x32x16_bf16 v[82:97], v[10:13], v[170:173], v[82:97]
	ds_read_b128 v[6:9], v21 offset:36864
	v_exp_f32_e32 v23, v157
	s_waitcnt lgkmcnt(2)
	v_mfma_f32_32x32x16_bf16 v[66:81], v[14:17], v[170:173], v[66:81]
	ds_read_b128 v[10:13], v21 offset:40960
	v_add_f32_e32 v24, v22, v24
	v_add_f32_e32 v24, v23, v24
	v_cvt_pk_bf16_f32 v147, v22, v23
	v_exp_f32_e32 v22, v158
	s_waitcnt lgkmcnt(2)
	v_mfma_f32_32x32x16_bf16 v[114:129], v[2:5], v[174:177], v[114:129]
	ds_read_b128 v[14:17], v21 offset:45056
	v_exp_f32_e32 v23, v159
	s_waitcnt lgkmcnt(2)
	v_mfma_f32_32x32x16_bf16 v[98:113], v[6:9], v[174:177], v[98:113]
	v_add_f32_e32 v24, v22, v24
	v_add_f32_e32 v24, v23, v24
	v_cvt_pk_bf16_f32 v148, v22, v23
	v_exp_f32_e32 v22, v160
	s_waitcnt lgkmcnt(1)
	v_mfma_f32_32x32x16_bf16 v[82:97], v[10:13], v[174:177], v[82:97]
	v_exp_f32_e32 v23, v161
	s_waitcnt lgkmcnt(0)
	v_mfma_f32_32x32x16_bf16 v[66:81], v[14:17], v[174:177], v[66:81]
	v_add_f32_e32 v24, v22, v24
	v_add_f32_e32 v24, v23, v24
	v_cvt_pk_bf16_f32 v149, v22, v23
	v_add_f32_e32 v0, v242, v24
	s_mov_b64 s[0:1], 0
.LBB0_389:
	s_and_b64 vcc, exec, s[0:1]
	s_cbranch_vccz .LBB0_393
	s_add_i32 s0, s76, -5
	s_cmp_gt_u32 s0, s83
	s_cbranch_scc1 .LBB0_392
	s_cmp_eq_u32 s93, 1
	s_cbranch_scc1 .Lmy_odddrain_skip
	v_exp_f32_e32 v246, v50
	v_exp_f32_e32 v247, v51
	v_add_f32_e32 v242, v246, v242
	v_add_f32_e32 v242, v247, v242
	v_cvt_pk_bf16_f32 v170, v246, v247
	v_exp_f32_e32 v246, v52
	v_exp_f32_e32 v247, v53
	v_add_f32_e32 v242, v246, v242
	v_add_f32_e32 v242, v247, v242
	v_cvt_pk_bf16_f32 v171, v246, v247
	v_exp_f32_e32 v246, v54
	v_exp_f32_e32 v247, v55
	v_add_f32_e32 v242, v246, v242
	v_add_f32_e32 v242, v247, v242
	v_cvt_pk_bf16_f32 v172, v246, v247
	v_exp_f32_e32 v246, v56
	v_exp_f32_e32 v247, v57
	v_add_f32_e32 v242, v246, v242
	v_add_f32_e32 v242, v247, v242
	v_cvt_pk_bf16_f32 v173, v246, v247
	v_exp_f32_e32 v246, v58
	v_exp_f32_e32 v247, v59
	v_add_f32_e32 v242, v246, v242
	v_add_f32_e32 v242, v247, v242
	v_cvt_pk_bf16_f32 v174, v246, v247
	v_exp_f32_e32 v246, v60
	v_exp_f32_e32 v247, v61
	v_add_f32_e32 v242, v246, v242
	v_add_f32_e32 v242, v247, v242
	v_cvt_pk_bf16_f32 v175, v246, v247
	v_exp_f32_e32 v246, v62
	v_exp_f32_e32 v247, v63
	v_add_f32_e32 v242, v246, v242
	v_add_f32_e32 v242, v247, v242
	v_cvt_pk_bf16_f32 v176, v246, v247
	v_exp_f32_e32 v246, v64
	v_exp_f32_e32 v247, v65
	v_add_f32_e32 v242, v246, v242
	v_add_f32_e32 v242, v247, v242
	v_cvt_pk_bf16_f32 v177, v246, v247
.Lmy_odddrain_skip:
	v_add_u32_e32 v0, v243, v233
	ds_read_b128 v[2:5], v0 offset:32768
	s_waitcnt lgkmcnt(0)
	v_mfma_f32_32x32x16_bf16 v[114:129], v[2:5], v[162:165], v[114:129]
	ds_read_b128 v[2:5], v0 offset:36864
	s_waitcnt lgkmcnt(0)
	v_mfma_f32_32x32x16_bf16 v[98:113], v[2:5], v[162:165], v[98:113]
	ds_read_b128 v[2:5], v0 offset:40960
	s_waitcnt lgkmcnt(0)
	v_mfma_f32_32x32x16_bf16 v[82:97], v[2:5], v[162:165], v[82:97]
	ds_read_b128 v[2:5], v0 offset:45056
	s_waitcnt lgkmcnt(0)
	v_mfma_f32_32x32x16_bf16 v[66:81], v[2:5], v[162:165], v[66:81]
	v_add_u32_e32 v0, v243, v235
	ds_read_b128 v[2:5], v0 offset:32768
	s_waitcnt lgkmcnt(0)
	v_mfma_f32_32x32x16_bf16 v[114:129], v[2:5], v[166:169], v[114:129]
	ds_read_b128 v[2:5], v0 offset:36864
	s_waitcnt lgkmcnt(0)
	v_mfma_f32_32x32x16_bf16 v[98:113], v[2:5], v[166:169], v[98:113]
	ds_read_b128 v[2:5], v0 offset:40960
	s_waitcnt lgkmcnt(0)
	v_mfma_f32_32x32x16_bf16 v[82:97], v[2:5], v[166:169], v[82:97]
	ds_read_b128 v[2:5], v0 offset:45056
	s_waitcnt lgkmcnt(0)
	v_mfma_f32_32x32x16_bf16 v[66:81], v[2:5], v[166:169], v[66:81]
	v_add_u32_e32 v0, v243, v237
	ds_read_b128 v[2:5], v0 offset:32768
	s_waitcnt lgkmcnt(0)
	v_mfma_f32_32x32x16_bf16 v[114:129], v[2:5], v[170:173], v[114:129]
	ds_read_b128 v[2:5], v0 offset:36864
	s_waitcnt lgkmcnt(0)
	v_mfma_f32_32x32x16_bf16 v[98:113], v[2:5], v[170:173], v[98:113]
	ds_read_b128 v[2:5], v0 offset:40960
	s_waitcnt lgkmcnt(0)
	v_mfma_f32_32x32x16_bf16 v[82:97], v[2:5], v[170:173], v[82:97]
	ds_read_b128 v[2:5], v0 offset:45056
	s_waitcnt lgkmcnt(0)
	v_mfma_f32_32x32x16_bf16 v[66:81], v[2:5], v[170:173], v[66:81]
	v_add_u32_e32 v0, v243, v239
	ds_read_b128 v[2:5], v0 offset:32768
	s_waitcnt lgkmcnt(0)
	v_mfma_f32_32x32x16_bf16 v[114:129], v[2:5], v[174:177], v[114:129]
	ds_read_b128 v[2:5], v0 offset:36864
	s_waitcnt lgkmcnt(0)
	v_mfma_f32_32x32x16_bf16 v[98:113], v[2:5], v[174:177], v[98:113]
	ds_read_b128 v[2:5], v0 offset:40960
	s_waitcnt lgkmcnt(0)
	v_mfma_f32_32x32x16_bf16 v[82:97], v[2:5], v[174:177], v[82:97]
	ds_read_b128 v[2:5], v0 offset:45056
	s_waitcnt lgkmcnt(0)
	v_mfma_f32_32x32x16_bf16 v[66:81], v[2:5], v[174:177], v[66:81]

.LBB0_393:
	s_waitcnt vmcnt(6) lgkmcnt(0)
	s_cmp_ge_u32 s93, s82
	s_barrier
	s_cbranch_scc1 .LBB0_402
	s_cmp_lt_u32 s93, s73
	s_cselect_b32 s0, s76, s33
	v_mad_u64_u32 v[50:51], s[0:1], s0, v228, v[220:221]
	s_add_i32 s0, s77, 0xffffa000
	s_mov_b32 s79, s85
	s_and_b32 s0, s0, 0x6000
	s_add_i32 m0, s67, s0
	s_lshl_b64 s[0:1], s[78:79], 7
	s_add_u32 s0, s74, s0
	v_lshl_add_u64 v[50:51], v[50:51], 0, s[86:87]
	s_addc_u32 s1, s75, s1
	global_load_lds_dwordx4 v[50:51], off
	v_lshl_add_u64 v[50:51], s[0:1], 0, v[204:205]
	s_add_i32 s0, s2, 0x10000
	s_and_b32 s0, s0, 0xc000
	s_add_i32 s0, s67, s0
	s_add_i32 m0, s0, 0x8000
	s_nop 0
	global_load_lds_dwordx4 v[50:51], off
	v_lshl_add_u64 v[50:51], v[50:51], 0, s[88:89]
	s_add_i32 m0, s0, 0xa000
	s_add_i32 s0, s2, 0x4000
	global_load_lds_dwordx4 v[50:51], off
	s_and_b32 s0, s0, 0xc000
	v_add_u32_e32 v248, s0, v230
	s_cmp_ge_u32 s93, s83
	s_mov_b64 s[0:1], -1
	s_cbranch_scc0 .LBB0_398
	s_andn2_b64 vcc, exec, s[96:97]
	s_cbranch_vccnz .LBB0_397
	v_exp_f32_e32 v246, v130
	v_exp_f32_e32 v247, v131
	v_add_f32_e32 v0, v246, v0
	v_add_f32_e32 v0, v247, v0
	v_cvt_pk_bf16_f32 v150, v246, v247
	v_exp_f32_e32 v246, v132
	v_exp_f32_e32 v247, v133
	v_add_f32_e32 v0, v246, v0
	v_add_f32_e32 v0, v247, v0
	v_cvt_pk_bf16_f32 v151, v246, v247
	v_exp_f32_e32 v246, v134
	v_exp_f32_e32 v247, v135
	v_add_f32_e32 v0, v246, v0
	v_add_f32_e32 v0, v247, v0
	v_cvt_pk_bf16_f32 v152, v246, v247
	v_exp_f32_e32 v246, v136
	v_exp_f32_e32 v247, v137
	v_add_f32_e32 v0, v246, v0
	v_add_f32_e32 v0, v247, v0
	v_cvt_pk_bf16_f32 v153, v246, v247
	v_exp_f32_e32 v246, v138
	v_exp_f32_e32 v247, v139
	v_add_f32_e32 v0, v246, v0
	v_add_f32_e32 v0, v247, v0
	v_cvt_pk_bf16_f32 v130, v246, v247
	v_exp_f32_e32 v246, v140
	v_exp_f32_e32 v247, v141
	v_add_f32_e32 v0, v246, v0
	v_add_f32_e32 v0, v247, v0
	v_cvt_pk_bf16_f32 v131, v246, v247
	v_exp_f32_e32 v246, v142
	v_exp_f32_e32 v247, v143
	v_add_f32_e32 v0, v246, v0
	v_add_f32_e32 v0, v247, v0
	v_cvt_pk_bf16_f32 v132, v246, v247
	v_exp_f32_e32 v246, v144
	v_exp_f32_e32 v247, v145
	v_add_f32_e32 v0, v246, v0
	v_add_f32_e32 v0, v247, v0
	v_cvt_pk_bf16_f32 v133, v246, v247
	v_add_u32_e32 v10, v248, v233
	ds_read_b128 v[2:5], v10 offset:32768
	ds_read_b128 v[6:9], v10 offset:36864
	s_waitcnt lgkmcnt(0)
	v_mfma_f32_32x32x16_bf16 v[114:129], v[2:5], v[178:181], v[114:129]
	ds_read_b128 v[2:5], v10 offset:40960
	ds_read_b128 v[136:139], v10 offset:45056
	v_mfma_f32_32x32x16_bf16 v[98:113], v[6:9], v[178:181], v[98:113]
	s_waitcnt lgkmcnt(0)
	v_mfma_f32_32x32x16_bf16 v[82:97], v[2:5], v[178:181], v[82:97]
	v_mfma_f32_32x32x16_bf16 v[66:81], v[136:139], v[178:181], v[66:81]
	v_add_u32_e32 v135, v248, v235
	ds_read_b128 v[136:139], v135 offset:32768
	s_waitcnt lgkmcnt(0)
	v_mfma_f32_32x32x16_bf16 v[114:129], v[136:139], v[146:149], v[114:129]
	ds_read_b128 v[136:139], v135 offset:36864
	s_waitcnt lgkmcnt(0)
	v_mfma_f32_32x32x16_bf16 v[98:113], v[136:139], v[146:149], v[98:113]
	ds_read_b128 v[136:139], v135 offset:40960
	s_waitcnt lgkmcnt(0)
	v_mfma_f32_32x32x16_bf16 v[82:97], v[136:139], v[146:149], v[82:97]
	ds_read_b128 v[136:139], v135 offset:45056
	s_waitcnt lgkmcnt(0)
	v_mfma_f32_32x32x16_bf16 v[66:81], v[136:139], v[146:149], v[66:81]
	v_add_u32_e32 v135, v248, v237
	ds_read_b128 v[136:139], v135 offset:32768
	s_waitcnt lgkmcnt(0)
	v_mfma_f32_32x32x16_bf16 v[114:129], v[136:139], v[150:153], v[114:129]
	ds_read_b128 v[136:139], v135 offset:36864
	s_waitcnt lgkmcnt(0)
	v_mfma_f32_32x32x16_bf16 v[98:113], v[136:139], v[150:153], v[98:113]
	ds_read_b128 v[136:139], v135 offset:40960
	s_waitcnt lgkmcnt(0)
	v_mfma_f32_32x32x16_bf16 v[82:97], v[136:139], v[150:153], v[82:97]
	ds_read_b128 v[136:139], v135 offset:45056
	s_waitcnt lgkmcnt(0)
	v_mfma_f32_32x32x16_bf16 v[66:81], v[136:139], v[150:153], v[66:81]
	v_add_u32_e32 v135, v248, v239
	ds_read_b128 v[136:139], v135 offset:32768
	s_waitcnt lgkmcnt(0)
	v_mfma_f32_32x32x16_bf16 v[114:129], v[136:139], v[130:133], v[114:129]
	ds_read_b128 v[136:139], v135 offset:36864
	s_waitcnt lgkmcnt(0)
	v_mfma_f32_32x32x16_bf16 v[98:113], v[136:139], v[130:133], v[98:113]
	ds_read_b128 v[136:139], v135 offset:40960
	s_waitcnt lgkmcnt(0)
	v_mfma_f32_32x32x16_bf16 v[82:97], v[136:139], v[130:133], v[82:97]
	ds_read_b128 v[136:139], v135 offset:45056
	s_waitcnt lgkmcnt(0)
	v_mfma_f32_32x32x16_bf16 v[66:81], v[136:139], v[130:133], v[66:81]

.LBB0_398:
	s_andn2_b64 vcc, exec, s[0:1]
	s_cbranch_vccnz .LBB0_403
	s_add_i32 s0, s77, 0xffffc000
	s_and_b32 s0, s0, 0x6000
	v_add_u32_e32 v244, s0, v229
	v_add_u32_e32 v245, v244, v232
	ds_read_b128 v[2:5], v245
	ds_read_b128 v[162:165], v241
	ds_read_b128 v[6:9], v245 offset:4096
	v_add_u32_e32 v245, v244, v234
	ds_read_b128 v[10:13], v245
	ds_read_b128 v[166:169], v241 offset:1024
	ds_read_b128 v[14:17], v245 offset:4096
	v_add_u32_e32 v245, v244, v236
	ds_read_b128 v[18:21], v245
	ds_read_b128 v[170:173], v241 offset:2048
	ds_read_b128 v[22:25], v245 offset:4096
	v_add_u32_e32 v245, v244, v238
	ds_read_b128 v[26:29], v245
	ds_read_b128 v[174:177], v241 offset:3072
	ds_read_b128 v[30:33], v245 offset:4096
	s_waitcnt lgkmcnt(10)
	v_mfma_f32_32x32x16_bf16 v[34:49], v[2:5], v[162:165], 0
	v_exp_f32_e32 v246, v130
	v_exp_f32_e32 v247, v131
	v_add_f32_e32 v0, v246, v0
	v_add_f32_e32 v0, v247, v0
	v_cvt_pk_bf16_f32 v150, v246, v247
	s_waitcnt lgkmcnt(9)
	v_mfma_f32_32x32x16_bf16 v[50:65], v[6:9], v[162:165], 0
	v_exp_f32_e32 v246, v132
	v_exp_f32_e32 v247, v133
	v_add_f32_e32 v0, v246, v0
	v_add_f32_e32 v0, v247, v0
	v_cvt_pk_bf16_f32 v151, v246, v247
	s_waitcnt lgkmcnt(7)
	v_mfma_f32_32x32x16_bf16 v[34:49], v[10:13], v[166:169], v[34:49]
	v_exp_f32_e32 v246, v134
	v_exp_f32_e32 v247, v135
	v_add_f32_e32 v0, v246, v0
	v_add_f32_e32 v0, v247, v0
	v_cvt_pk_bf16_f32 v152, v246, v247
	s_waitcnt lgkmcnt(6)
	v_mfma_f32_32x32x16_bf16 v[50:65], v[14:17], v[166:169], v[50:65]
	v_exp_f32_e32 v246, v136
	v_exp_f32_e32 v247, v137
	v_add_f32_e32 v0, v246, v0
	v_add_f32_e32 v0, v247, v0
	v_cvt_pk_bf16_f32 v153, v246, v247
	s_waitcnt lgkmcnt(4)
	v_mfma_f32_32x32x16_bf16 v[34:49], v[18:21], v[170:173], v[34:49]
	v_exp_f32_e32 v246, v138
	v_exp_f32_e32 v247, v139
	v_add_f32_e32 v0, v246, v0
	v_add_f32_e32 v0, v247, v0
	v_cvt_pk_bf16_f32 v130, v246, v247
	s_waitcnt lgkmcnt(3)
	v_mfma_f32_32x32x16_bf16 v[50:65], v[22:25], v[170:173], v[50:65]
	v_exp_f32_e32 v246, v140
	v_exp_f32_e32 v247, v141
	v_add_f32_e32 v0, v246, v0
	v_add_f32_e32 v0, v247, v0
	v_cvt_pk_bf16_f32 v131, v246, v247
	s_waitcnt lgkmcnt(1)
	v_mfma_f32_32x32x16_bf16 v[34:49], v[26:29], v[174:177], v[34:49]
	v_exp_f32_e32 v246, v142
	v_exp_f32_e32 v247, v143
	v_add_f32_e32 v0, v246, v0
	v_add_f32_e32 v0, v247, v0
	v_cvt_pk_bf16_f32 v132, v246, v247
	s_waitcnt lgkmcnt(0)
	v_mfma_f32_32x32x16_bf16 v[50:65], v[30:33], v[174:177], v[50:65]
	v_exp_f32_e32 v246, v144
	v_exp_f32_e32 v247, v145
	v_add_f32_e32 v0, v246, v0
	v_add_f32_e32 v0, v247, v0
	v_cvt_pk_bf16_f32 v133, v246, v247
	s_cmp_lg_u32 s92, 3
	s_cbranch_scc1 .LBB0_401
	v_mov_b32_e32 v18, v240
	s_nop 0
	v_cmp_gt_i32_e64 s[62:63], 22, v18
	v_cmp_gt_i32_e64 s[64:65], 23, v18
	v_cmp_gt_i32_e64 s[60:61], 21, v18
	s_and_b64 s[62:63], s[64:65], s[62:63]
	v_cmp_gt_i32_e64 s[58:59], 20, v18
	s_and_b64 s[60:61], s[62:63], s[60:61]
	v_cmp_gt_i32_e64 s[56:57], 19, v18
	s_and_b64 s[58:59], s[60:61], s[58:59]
	v_cmp_gt_i32_e64 s[54:55], 18, v18
	s_and_b64 s[56:57], s[58:59], s[56:57]
	v_cmp_gt_i32_e64 s[52:53], 17, v18
	s_and_b64 s[54:55], s[56:57], s[54:55]
	v_cmp_gt_i32_e64 s[50:51], 16, v18
	s_and_b64 s[52:53], s[54:55], s[52:53]
	v_cmp_gt_i32_e64 s[48:49], 7, v18
	s_and_b64 s[50:51], s[52:53], s[50:51]
	v_cmp_gt_i32_e64 s[46:47], 6, v18
	s_and_b64 s[48:49], s[50:51], s[48:49]
	v_cmp_gt_i32_e64 s[44:45], 5, v18
	s_and_b64 s[46:47], s[48:49], s[46:47]
	v_cmp_gt_i32_e64 s[42:43], 4, v18
	s_and_b64 s[44:45], s[46:47], s[44:45]
	v_cmp_gt_i32_e64 s[40:41], 3, v18
	s_and_b64 s[42:43], s[44:45], s[42:43]
	v_cmp_gt_i32_e64 s[38:39], 2, v18
	s_and_b64 s[40:41], s[42:43], s[40:41]
	v_cmp_gt_i32_e64 s[36:37], 1, v18
	s_and_b64 s[38:39], s[40:41], s[38:39]
	v_cmp_gt_i32_e64 s[34:35], 0, v18
	s_and_b64 s[36:37], s[38:39], s[36:37]
	s_and_b64 s[34:35], s[36:37], s[34:35]
	v_cmp_gt_i32_e64 s[30:31], 54, v18
	v_cndmask_b32_e64 v34, v34, v227, s[34:35]
	v_cmp_gt_i32_e64 s[34:35], 55, v18
	v_cmp_gt_i32_e64 s[28:29], 53, v18
	s_and_b64 s[30:31], s[34:35], s[30:31]
	v_cmp_gt_i32_e64 s[26:27], 52, v18
	s_and_b64 s[28:29], s[30:31], s[28:29]
	v_cmp_gt_i32_e64 s[24:25], 51, v18
	s_and_b64 s[26:27], s[28:29], s[26:27]
	v_cmp_gt_i32_e64 s[22:23], 50, v18
	s_and_b64 s[24:25], s[26:27], s[24:25]
	v_cmp_gt_i32_e64 s[20:21], 49, v18
	s_and_b64 s[22:23], s[24:25], s[22:23]
	v_cmp_gt_i32_e64 s[18:19], 48, v18
	s_and_b64 s[20:21], s[22:23], s[20:21]
	v_cmp_gt_i32_e64 s[16:17], 39, v18
	s_and_b64 s[18:19], s[20:21], s[18:19]
	v_cmp_gt_i32_e64 s[14:15], 38, v18
	s_and_b64 s[16:17], s[18:19], s[16:17]
	v_cmp_gt_i32_e64 s[12:13], 37, v18
	s_and_b64 s[14:15], s[16:17], s[14:15]
	v_cmp_gt_i32_e64 s[10:11], 36, v18
	s_and_b64 s[12:13], s[14:15], s[12:13]
	v_cmp_gt_i32_e64 s[8:9], 35, v18
	s_and_b64 s[10:11], s[12:13], s[10:11]
	v_cmp_gt_i32_e64 s[6:7], 34, v18
	s_and_b64 s[8:9], s[10:11], s[8:9]
	v_cmp_gt_i32_e64 s[0:1], 33, v18
	s_and_b64 s[6:7], s[8:9], s[6:7]
	v_cmp_gt_i32_e32 vcc, 32, v18
	s_and_b64 s[0:1], s[6:7], s[0:1]
	s_and_b64 vcc, s[0:1], vcc
	v_cndmask_b32_e64 v49, v49, v227, s[64:65]
	v_cndmask_b32_e64 v48, v48, v227, s[62:63]
	v_cndmask_b32_e64 v47, v47, v227, s[60:61]
	v_cndmask_b32_e64 v46, v46, v227, s[58:59]
	v_cndmask_b32_e64 v45, v45, v227, s[56:57]
	v_cndmask_b32_e64 v44, v44, v227, s[54:55]
	v_cndmask_b32_e64 v43, v43, v227, s[52:53]
	v_cndmask_b32_e64 v42, v42, v227, s[50:51]
	v_cndmask_b32_e64 v41, v41, v227, s[48:49]
	v_cndmask_b32_e64 v40, v40, v227, s[46:47]
	v_cndmask_b32_e64 v39, v39, v227, s[44:45]
	v_cndmask_b32_e64 v38, v38, v227, s[42:43]
	v_cndmask_b32_e64 v37, v37, v227, s[40:41]
	v_cndmask_b32_e64 v36, v36, v227, s[38:39]
	v_cndmask_b32_e64 v35, v35, v227, s[36:37]
	v_cndmask_b32_e64 v65, v65, v227, s[34:35]
	v_cndmask_b32_e64 v64, v64, v227, s[30:31]
	v_cndmask_b32_e64 v63, v63, v227, s[28:29]
	v_cndmask_b32_e64 v62, v62, v227, s[26:27]
	v_cndmask_b32_e64 v61, v61, v227, s[24:25]
	v_cndmask_b32_e64 v60, v60, v227, s[22:23]
	v_cndmask_b32_e64 v59, v59, v227, s[20:21]
	v_cndmask_b32_e64 v58, v58, v227, s[18:19]
	v_cndmask_b32_e64 v57, v57, v227, s[16:17]
	v_cndmask_b32_e64 v56, v56, v227, s[14:15]
	v_cndmask_b32_e64 v55, v55, v227, s[12:13]
	v_cndmask_b32_e64 v54, v54, v227, s[10:11]
	v_cndmask_b32_e64 v53, v53, v227, s[8:9]
	v_cndmask_b32_e64 v52, v52, v227, s[6:7]
	v_cndmask_b32_e64 v51, v51, v227, s[0:1]
	v_cndmask_b32_e32 v50, v50, v227, vcc
.LBB0_401:
	v_add_u32_e32 v18, v248, v233
	v_add_u32_e32 v19, v248, v235
	v_add_u32_e32 v20, v248, v237
	v_add_u32_e32 v21, v248, v239
	ds_read_b128 v[2:5], v18 offset:32768
	ds_read_b128 v[6:9], v18 offset:36864
	ds_read_b128 v[10:13], v18 offset:40960
	s_nop 5
	v_exp_f32_e32 v22, v34
	s_waitcnt lgkmcnt(2)
	v_mfma_f32_32x32x16_bf16 v[114:129], v[2:5], v[178:181], v[114:129]
	ds_read_b128 v[14:17], v18 offset:45056
	v_exp_f32_e32 v23, v35
	s_waitcnt lgkmcnt(2)
	v_mfma_f32_32x32x16_bf16 v[98:113], v[6:9], v[178:181], v[98:113]
	ds_read_b128 v[2:5], v19 offset:32768
	v_add_f32_e32 v24, v22, v23
	v_cvt_pk_bf16_f32 v162, v22, v23
	v_exp_f32_e32 v22, v36
	s_waitcnt lgkmcnt(2)
	v_mfma_f32_32x32x16_bf16 v[82:97], v[10:13], v[178:181], v[82:97]
	ds_read_b128 v[6:9], v19 offset:36864
	v_exp_f32_e32 v23, v37
	s_waitcnt lgkmcnt(2)
	v_mfma_f32_32x32x16_bf16 v[66:81], v[14:17], v[178:181], v[66:81]
	ds_read_b128 v[10:13], v19 offset:40960
	v_add_f32_e32 v24, v22, v24
	v_add_f32_e32 v24, v23, v24
	v_cvt_pk_bf16_f32 v163, v22, v23
	v_exp_f32_e32 v22, v38
	s_waitcnt lgkmcnt(2)
	v_mfma_f32_32x32x16_bf16 v[114:129], v[2:5], v[146:149], v[114:129]
	ds_read_b128 v[14:17], v19 offset:45056
	v_exp_f32_e32 v23, v39
	s_waitcnt lgkmcnt(2)
	v_mfma_f32_32x32x16_bf16 v[98:113], v[6:9], v[146:149], v[98:113]
	ds_read_b128 v[2:5], v20 offset:32768
	v_add_f32_e32 v24, v22, v24
	v_add_f32_e32 v24, v23, v24
	v_cvt_pk_bf16_f32 v164, v22, v23
	v_exp_f32_e32 v22, v40
	s_waitcnt lgkmcnt(2)
	v_mfma_f32_32x32x16_bf16 v[82:97], v[10:13], v[146:149], v[82:97]
	ds_read_b128 v[6:9], v20 offset:36864
	v_exp_f32_e32 v23, v41
	s_waitcnt lgkmcnt(2)
	v_mfma_f32_32x32x16_bf16 v[66:81], v[14:17], v[146:149], v[66:81]
	ds_read_b128 v[10:13], v20 offset:40960
	v_add_f32_e32 v24, v22, v24
	v_add_f32_e32 v24, v23, v24
	v_cvt_pk_bf16_f32 v165, v22, v23
	v_exp_f32_e32 v22, v42
	s_waitcnt lgkmcnt(2)
	v_mfma_f32_32x32x16_bf16 v[114:129], v[2:5], v[150:153], v[114:129]
	ds_read_b128 v[14:17], v20 offset:45056
	v_exp_f32_e32 v23, v43
	s_waitcnt lgkmcnt(2)
	v_mfma_f32_32x32x16_bf16 v[98:113], v[6:9], v[150:153], v[98:113]
	ds_read_b128 v[2:5], v21 offset:32768
	v_add_f32_e32 v24, v22, v24
	v_add_f32_e32 v24, v23, v24
	v_cvt_pk_bf16_f32 v166, v22, v23
	v_exp_f32_e32 v22, v44
	s_waitcnt lgkmcnt(2)
	v_mfma_f32_32x32x16_bf16 v[82:97], v[10:13], v[150:153], v[82:97]
	ds_read_b128 v[6:9], v21 offset:36864
	v_exp_f32_e32 v23, v45
	s_waitcnt lgkmcnt(2)
	v_mfma_f32_32x32x16_bf16 v[66:81], v[14:17], v[150:153], v[66:81]
	ds_read_b128 v[10:13], v21 offset:40960
	v_add_f32_e32 v24, v22, v24
	v_add_f32_e32 v24, v23, v24
	v_cvt_pk_bf16_f32 v167, v22, v23
	v_exp_f32_e32 v22, v46
	s_waitcnt lgkmcnt(2)
	v_mfma_f32_32x32x16_bf16 v[114:129], v[2:5], v[130:133], v[114:129]
	ds_read_b128 v[14:17], v21 offset:45056
	v_exp_f32_e32 v23, v47
	s_waitcnt lgkmcnt(2)
	v_mfma_f32_32x32x16_bf16 v[98:113], v[6:9], v[130:133], v[98:113]
	v_add_f32_e32 v24, v22, v24
	v_add_f32_e32 v24, v23, v24
	v_cvt_pk_bf16_f32 v168, v22, v23
	v_exp_f32_e32 v22, v48
	s_waitcnt lgkmcnt(1)
	v_mfma_f32_32x32x16_bf16 v[82:97], v[10:13], v[130:133], v[82:97]
	v_exp_f32_e32 v23, v49
	s_waitcnt lgkmcnt(0)
	v_mfma_f32_32x32x16_bf16 v[66:81], v[14:17], v[130:133], v[66:81]
	v_add_f32_e32 v24, v22, v24
	v_add_f32_e32 v24, v23, v24
	v_cvt_pk_bf16_f32 v169, v22, v23
	v_add_f32_e32 v242, v0, v24
	s_branch .LBB0_404

;     __device__ __forceinline__ void operator()(const f32x4 (&acc)[2][2][4][2], const Unit& u, int wr, int wc, int fr, int fq) const {
;         const int hi8 = fr >> 3;
;         const int rowA = u.pm * BM + wr * 64 + (fr & 7), rowB = rowA + 8; const int col0 = u.pn * BM + wc * 32 + 16 * hi8 + 4 * fq;
;         const size_t bofs = (size_t)((u.pm * BM) / 8192) * 3072 + col0;
;         f32x4 gs[2], av[2];
; #pragma unroll
;         for (int bj = 0; bj < 2; ++bj) { gs[bj] = *(const f32x4*)(gate + bofs + bj * HALF); av[bj] = *(const f32x4*)(ng + col0 + bj * HALF) * (*(const f32x4*)(scl + bofs + bj * HALF) + 1.f); }
; #pragma unroll
;         for (int ai = 0; ai < 2; ++ai)
; #pragma unroll
;             for (int m = 0; m < 4; ++m) { const int ra = rowA + ai * HALF + m * 16, rb = rowB + ai * HALF + m * 16; const size_t offA = (size_t)ra * 1024 + col0, offB = (size_t)rb * 1024 + col0;
;                 float ssa = 0.f, ssb = 0.f;
; #pragma unroll
;                 for (int bj = 0; bj < 2; ++bj) {
;                     const f32x4 x0 = acc[ai][bj][m][0], x1 = acc[ai][bj][m][1]; f32x4 za, zb;
; #pragma unroll
;                     for (int e = 0; e < 4; ++e) { const float s1 = __shfl_xor(x1[e], 8), s0 = __shfl_xor(x0[e], 8); za[e] = hi8 ? s1 : x0[e]; zb[e] = hi8 ? x1[e] : s0; }
;                     const f32x4 ba = *(const f32x4*)(base + offA + bj * HALF), bb = *(const f32x4*)(base + offB + bj * HALF);
;                     const f32x4 oa = ba + gs[bj] * za, ob = bb + gs[bj] * zb;
;                     *(f32x4*)(out + offA + bj * HALF) = oa; *(f32x4*)(out + offB + bj * HALF) = ob;
.LBB0_543:
	s_ashr_i32 s21, s28, 31
	v_lshl_add_u32 v150, s28, 8, v155
	s_lshr_b32 s21, s21, 27
	v_lshl_add_u32 v148, s30, 8, v156
	s_add_i32 s21, s28, s21
	v_or_b32_e32 v152, 8, v150
	v_readlane_b32 s52, v252, 18
	s_ashr_i32 s21, s21, 5
	v_ashrrev_i32_e32 v149, 31, v148
	v_ashrrev_i32_e32 v151, 31, v150
	v_ashrrev_i32_e32 v153, 31, v152
	v_readlane_b32 s53, v252, 19
	v_readlane_b32 s54, v252, 20
	v_readlane_b32 s55, v252, 21
	v_readlane_b32 s56, v252, 22
	v_readlane_b32 s57, v252, 23
	v_readlane_b32 s58, v252, 24
	v_readlane_b32 s59, v252, 25
	v_readlane_b32 s60, v252, 26
	v_readlane_b32 s61, v252, 27
	v_readlane_b32 s62, v252, 28
	v_readlane_b32 s63, v252, 29
	v_readlane_b32 s64, v252, 30
	v_readlane_b32 s65, v252, 31
	v_readlane_b32 s66, v252, 32
	v_readlane_b32 s67, v252, 33
	v_mad_i64_i32 v[48:49], s[28:29], s21, v161, v[148:149]
	v_lshlrev_b64 v[54:55], 10, v[150:151]
	v_lshlrev_b64 v[162:163], 10, v[152:153]
	s_mov_b64 s[36:37], s[52:53]
	v_readlane_b32 s52, v252, 2
	v_lshlrev_b64 v[48:49], 2, v[48:49]
	v_lshl_add_u64 v[54:55], v[54:55], 0, v[148:149]
	v_lshl_add_u64 v[186:187], v[162:163], 0, v[148:149]
	v_readlane_b32 s53, v252, 3
	v_readlane_b32 s56, v252, 6
	v_readlane_b32 s57, v252, 7
	v_lshl_add_u64 v[52:53], s[10:11], 0, v[48:49]
	v_lshlrev_b64 v[188:189], 2, v[54:55]
	v_lshlrev_b64 v[192:193], 2, v[186:187]
	s_mov_b64 s[52:53], s[56:57]
	v_lshl_add_u64 v[184:185], s[12:13], 0, v[48:49]
	global_load_dwordx4 v[48:51], v[52:53], off
	global_load_dwordx4 v[164:167], v[184:185], off
	v_lshl_add_u64 v[190:191], s[36:37], 0, v[188:189]
	v_lshl_add_u64 v[194:195], s[36:37], 0, v[192:193]
	v_lshl_add_u64 v[162:163], v[148:149], 2, s[52:53]
	global_load_dwordx4 v[168:171], v[190:191], off
	global_load_dwordx4 v[172:175], v[194:195], off
	global_load_dwordx4 v[176:179], v[162:163], off
	v_and_b32_e32 v181, 64, v160
	v_xor_b32_e32 v180, 8, v160
	v_add_u32_e32 v204, 64, v181
	v_cmp_lt_i32_e32 vcc, v180, v204
	v_readlane_b32 s62, v252, 12
	v_readlane_b32 s63, v252, 13
	v_cndmask_b32_e32 v196, v160, v180, vcc
	global_load_dwordx4 v[180:183], v[162:163], off offset:512
	v_lshlrev_b32_e32 v162, 2, v196
	ds_bpermute_b32 v163, v162, v128
	ds_bpermute_b32 v200, v162, v132
	ds_bpermute_b32 v201, v162, v129
	ds_bpermute_b32 v202, v162, v133
	ds_bpermute_b32 v203, v162, v130
	ds_bpermute_b32 v205, v162, v134
	ds_bpermute_b32 v206, v162, v131
	ds_bpermute_b32 v207, v162, v135
	v_readlane_b32 s66, v252, 16
	v_readlane_b32 s67, v252, 17
	s_waitcnt lgkmcnt(0)
	v_cndmask_b32_e64 v132, v163, v132, s[0:1]
	v_cndmask_b32_e64 v128, v128, v200, s[0:1]
	v_cndmask_b32_e64 v133, v201, v133, s[0:1]
	v_cndmask_b32_e64 v129, v129, v202, s[0:1]
	v_cndmask_b32_e64 v134, v203, v134, s[0:1]
	v_cndmask_b32_e64 v130, v130, v205, s[0:1]
	v_cndmask_b32_e64 v135, v206, v135, s[0:1]
	v_cndmask_b32_e64 v131, v131, v207, s[0:1]
	s_mov_b64 s[62:63], s[66:67]
	v_lshl_add_u64 v[196:197], v[54:55], 1, s[4:5]
	v_lshl_add_u64 v[188:189], s[62:63], 0, v[188:189]
	v_lshl_add_u64 v[198:199], v[186:187], 1, s[4:5]
	v_lshl_add_u64 v[192:193], s[62:63], 0, v[192:193]
	global_load_dwordx4 v[52:55], v[52:53], off offset:512
	s_nop 0
	global_load_dwordx4 v[184:187], v[184:185], off offset:512
	ds_bpermute_b32 v163, v162, v121
	v_readlane_b32 s54, v252, 4
	v_readlane_b32 s55, v252, 5
	v_readlane_b32 s58, v252, 8
	v_readlane_b32 s59, v252, 9
	v_readlane_b32 s60, v252, 10
	v_readlane_b32 s61, v252, 11
	v_readlane_b32 s64, v252, 14
	v_readlane_b32 s65, v252, 15
	s_waitcnt vmcnt(0)
	v_pk_add_f32 v[200:201], v[166:167], 1.0 op_sel_hi:[1,0]
	v_pk_add_f32 v[202:203], v[164:165], 1.0 op_sel_hi:[1,0]
	v_pk_fma_f32 v[166:167], v[50:51], v[134:135], v[170:171]
	v_pk_fma_f32 v[164:165], v[48:49], v[132:133], v[168:169]
	v_pk_fma_f32 v[170:171], v[50:51], v[130:131], v[174:175]
	v_pk_fma_f32 v[168:169], v[48:49], v[128:129], v[172:173]
	v_pk_mul_f32 v[128:129], v[178:179], v[200:201]
	v_pk_mul_f32 v[130:131], v[176:177], v[202:203]
	v_pk_mul_f32 v[132:133], v[128:129], v[166:167]
	v_pk_mul_f32 v[134:135], v[130:131], v[164:165]
	global_store_dwordx4 v[188:189], v[164:167], off sc1
	global_store_dwordx4 v[192:193], v[168:171], off sc1
	v_pk_mul_f32 v[172:173], v[128:129], v[170:171]
	v_pk_mul_f32 v[174:175], v[130:131], v[168:169]
	v_cvt_pk_bf16_f32 v134, v134, v135
	v_cvt_pk_bf16_f32 v135, v132, v133
	global_store_dwordx2 v[196:197], v[134:135], off
	v_cvt_pk_bf16_f32 v132, v174, v175
	v_cvt_pk_bf16_f32 v133, v172, v173
	global_store_dwordx2 v[198:199], v[132:133], off
	global_load_dwordx4 v[172:175], v[190:191], off offset:512
	global_load_dwordx4 v[176:179], v[194:195], off offset:512
	v_xor_b32_e32 v132, 16, v160
	v_xor_b32_e32 v133, 32, v160
	v_cmp_lt_i32_e32 vcc, v132, v204
	ds_bpermute_b32 v135, v162, v124
	ds_bpermute_b32 v190, v162, v125
	v_cndmask_b32_e32 v132, v160, v132, vcc
	v_cmp_lt_i32_e32 vcc, v133, v204
	ds_bpermute_b32 v191, v162, v122
	ds_bpermute_b32 v194, v162, v126
	v_cndmask_b32_e32 v134, v160, v133, vcc
	v_lshlrev_b32_e32 v133, 2, v132
	v_lshlrev_b32_e32 v132, 2, v134
	ds_bpermute_b32 v134, v162, v120
	ds_bpermute_b32 v195, v162, v123
	ds_bpermute_b32 v200, v162, v127
	s_waitcnt lgkmcnt(7)
	v_cndmask_b32_e64 v125, v163, v125, s[0:1]
	v_mul_f32_e32 v163, v165, v165
	v_mul_f32_e32 v165, v167, v167
	v_mul_f32_e32 v167, v169, v169
	v_mul_f32_e32 v169, v171, v171
	s_waitcnt lgkmcnt(2)
	v_cndmask_b32_e64 v124, v134, v124, s[0:1]
	v_cndmask_b32_e64 v134, v120, v135, s[0:1]
	v_cndmask_b32_e64 v135, v121, v190, s[0:1]
	v_cndmask_b32_e64 v126, v191, v126, s[0:1]
	v_cndmask_b32_e64 v190, v122, v194, s[0:1]
	s_waitcnt lgkmcnt(1)
	v_cndmask_b32_e64 v127, v195, v127, s[0:1]
	s_waitcnt lgkmcnt(0)
; __device__ __forceinline__ unsigned cvt_pk_bf16(float lo, float hi) { unsigned r; asm volatile("v_cvt_pk_bf16_f32 %0, %1, %2" : "=v"(r) : "v"(lo), "v"(hi)); return r; }
;     __device__ __forceinline__ void operator()(const f32x4 (&acc)[2][2][4][2], const Unit& u, int wr, int wc, int fr, int fq) const {
;     ...
;                     for (int e = 0; e < 4; ++e) { const float s1 = __shfl_xor(x1[e], 8), s0 = __shfl_xor(x0[e], 8); za[e] = hi8 ? s1 : x0[e]; zb[e] = hi8 ? x1[e] : s0; }
;                     const f32x4 ba = *(const f32x4*)(base + offA + bj * HALF), bb = *(const f32x4*)(base + offB + bj * HALF);
;                     const f32x4 oa = ba + gs[bj] * za, ob = bb + gs[bj] * zb;
;                     *(f32x4*)(out + offA + bj * HALF) = oa; *(f32x4*)(out + offB + bj * HALF) = ob;
;                     const f32x4 ha = oa * av[bj], hb = ob * av[bj];
;                     *(unsigned long long*)(Hn + offA + bj * HALF) = (unsigned long long)cvt_pk_bf16(ha[0], ha[1]) | ((unsigned long long)cvt_pk_bf16(ha[2], ha[3]) << 32);
;                     *(unsigned long long*)(Hn + offB + bj * HALF) = (unsigned long long)cvt_pk_bf16(hb[0], hb[1]) | ((unsigned long long)cvt_pk_bf16(hb[2], hb[3]) << 32);
;                     ssa += (oa[0] * oa[0] + oa[1] * oa[1]) + (oa[2] * oa[2] + oa[3] * oa[3]); ssb += (ob[0] * ob[0] + ob[1] * ob[1]) + (ob[2] * ob[2] + ob[3] * ob[3]); }
;                 ssa += __shfl_xor(ssa, 8); ssa += __shfl_xor(ssa, 16); ssa += __shfl_xor(ssa, 32);
;                 ssb += __shfl_xor(ssb, 8); ssb += __shfl_xor(ssb, 16); ssb += __shfl_xor(ssb, 32);
;                 if (fq == 0 && hi8 == 0) { atomicAdd(rowss + ra, ssa); atomicAdd(rowss + rb, ssb); } }
	v_cndmask_b32_e64 v191, v123, v200, s[0:1]
	v_fmac_f32_e32 v163, v164, v164
	v_fmac_f32_e32 v165, v166, v166
	v_fmac_f32_e32 v167, v168, v168
	v_fmac_f32_e32 v169, v170, v170
	v_add_f32_e32 v163, v163, v165
	v_add_f32_e32 v168, v167, v169
	v_pk_add_f32 v[120:121], v[186:187], 1.0 op_sel_hi:[1,0]
	v_pk_add_f32 v[184:185], v[184:185], 1.0 op_sel_hi:[1,0]
	v_pk_mul_f32 v[122:123], v[182:183], v[120:121]
	v_pk_mul_f32 v[120:121], v[180:181], v[184:185]
	s_waitcnt vmcnt(1)
	v_pk_fma_f32 v[126:127], v[54:55], v[126:127], v[174:175]
	v_pk_fma_f32 v[124:125], v[52:53], v[124:125], v[172:173]
	s_waitcnt vmcnt(0)
	v_pk_fma_f32 v[166:167], v[54:55], v[190:191], v[178:179]
	v_pk_fma_f32 v[164:165], v[52:53], v[134:135], v[176:177]
	v_mul_f32_e32 v134, v125, v125
	v_mul_f32_e32 v135, v127, v127
	v_mul_f32_e32 v169, v165, v165
	v_mul_f32_e32 v170, v167, v167
	v_fmac_f32_e32 v134, v124, v124
	v_fmac_f32_e32 v135, v126, v126
	v_fmac_f32_e32 v169, v164, v164
	v_fmac_f32_e32 v170, v166, v166
	v_add_f32_e32 v134, v134, v135
	v_add_f32_e32 v135, v169, v170
	v_add_f32_e32 v163, v163, v134
	v_add_f32_e32 v168, v168, v135
	ds_bpermute_b32 v169, v162, v163
	ds_bpermute_b32 v170, v162, v168
	global_store_dwordx4 v[188:189], v[124:127], off offset:512 sc1
	global_store_dwordx4 v[192:193], v[164:167], off offset:512 sc1
	v_pk_mul_f32 v[134:135], v[122:123], v[166:167]
	v_pk_mul_f32 v[124:125], v[120:121], v[124:125]
	s_waitcnt lgkmcnt(1)
	v_add_f32_e32 v163, v163, v169
	s_waitcnt lgkmcnt(0)
	v_add_f32_e32 v168, v168, v170
	ds_bpermute_b32 v169, v133, v163
	ds_bpermute_b32 v170, v133, v168
	v_pk_mul_f32 v[126:127], v[122:123], v[126:127]
	v_cvt_pk_bf16_f32 v166, v124, v125
	v_pk_mul_f32 v[164:165], v[120:121], v[164:165]
	s_waitcnt lgkmcnt(1)
	v_add_f32_e32 v124, v163, v169
	s_waitcnt lgkmcnt(0)
	v_add_f32_e32 v125, v168, v170
	v_cvt_pk_bf16_f32 v167, v126, v127
	ds_bpermute_b32 v126, v132, v124
	ds_bpermute_b32 v127, v132, v125
	global_store_dwordx2 v[196:197], v[166:167], off offset:256
	v_cvt_pk_bf16_f32 v164, v164, v165
	v_cvt_pk_bf16_f32 v165, v134, v135
	global_store_dwordx2 v[198:199], v[164:165], off offset:256
	s_and_saveexec_b64 s[28:29], s[18:19]
	s_cbranch_execz .LBB0_545
	v_lshl_add_u64 v[134:135], v[152:153], 2, s[68:69]
	v_lshl_add_u64 v[152:153], v[150:151], 2, s[68:69]
	s_waitcnt lgkmcnt(1)
	v_add_f32_e32 v124, v124, v126
	s_waitcnt lgkmcnt(0)
	v_add_f32_e32 v125, v125, v127
	global_atomic_add_f32 v[152:153], v124, off
	global_atomic_add_f32 v[134:135], v125, off
.LBB0_545:
	s_or_b64 exec, exec, s[28:29]
	v_or_b32_e32 v124, 16, v150
	s_waitcnt lgkmcnt(1)
	v_or_b32_e32 v126, 24, v150
	v_ashrrev_i32_e32 v125, 31, v124
	v_lshlrev_b64 v[134:135], 10, v[124:125]
	s_waitcnt lgkmcnt(0)
	v_ashrrev_i32_e32 v127, 31, v126
	v_readlane_b32 s52, v252, 18
	v_lshl_add_u64 v[134:135], v[134:135], 0, v[148:149]
	v_lshlrev_b64 v[152:153], 10, v[126:127]
	v_readlane_b32 s53, v252, 19
	v_lshl_add_u64 v[152:153], v[152:153], 0, v[148:149]
	v_lshlrev_b64 v[172:173], 2, v[134:135]
	s_mov_b64 s[36:37], s[52:53]
	v_lshl_add_u64 v[174:175], s[36:37], 0, v[172:173]
	v_lshlrev_b64 v[176:177], 2, v[152:153]
	global_load_dwordx4 v[164:167], v[174:175], off
	v_lshl_add_u64 v[178:179], s[36:37], 0, v[176:177]
	global_load_dwordx4 v[168:171], v[178:179], off
	ds_bpermute_b32 v151, v162, v112
	ds_bpermute_b32 v163, v162, v116
	ds_bpermute_b32 v181, v162, v113
	ds_bpermute_b32 v182, v162, v117
	ds_bpermute_b32 v183, v162, v114
	ds_bpermute_b32 v185, v162, v115
	ds_bpermute_b32 v184, v162, v118
	ds_bpermute_b32 v186, v162, v119
	v_readlane_b32 s54, v252, 20
	v_readlane_b32 s55, v252, 21
	v_readlane_b32 s56, v252, 22
	v_readlane_b32 s57, v252, 23
	v_readlane_b32 s58, v252, 24
	v_readlane_b32 s59, v252, 25
	v_readlane_b32 s60, v252, 26
	v_readlane_b32 s61, v252, 27
	v_readlane_b32 s62, v252, 28
	v_readlane_b32 s63, v252, 29
	v_readlane_b32 s64, v252, 30
	v_readlane_b32 s65, v252, 31
	v_readlane_b32 s66, v252, 32
	v_readlane_b32 s67, v252, 33
	v_readlane_b32 s52, v252, 2
	s_waitcnt lgkmcnt(7)
	v_cndmask_b32_e64 v116, v151, v116, s[0:1]
	s_waitcnt lgkmcnt(6)
	v_cndmask_b32_e64 v180, v112, v163, s[0:1]
	s_waitcnt lgkmcnt(5)
	v_cndmask_b32_e64 v117, v181, v117, s[0:1]
	s_waitcnt lgkmcnt(4)
	v_cndmask_b32_e64 v181, v113, v182, s[0:1]
	s_waitcnt lgkmcnt(3)
	v_cndmask_b32_e64 v112, v183, v118, s[0:1]
	s_waitcnt lgkmcnt(2)
	v_cndmask_b32_e64 v113, v185, v119, s[0:1]
	v_readlane_b32 s62, v252, 12
	v_readlane_b32 s63, v252, 13
	v_readlane_b32 s66, v252, 16
	v_readlane_b32 s67, v252, 17
	s_waitcnt lgkmcnt(1)
	v_cndmask_b32_e64 v118, v114, v184, s[0:1]
	s_waitcnt lgkmcnt(0)
	v_cndmask_b32_e64 v119, v115, v186, s[0:1]
	s_mov_b64 s[62:63], s[66:67]
	v_lshl_add_u64 v[134:135], v[134:135], 1, s[4:5]
	v_lshl_add_u64 v[152:153], v[152:153], 1, s[4:5]
	v_lshl_add_u64 v[172:173], s[62:63], 0, v[172:173]
	v_lshl_add_u64 v[176:177], s[62:63], 0, v[176:177]
	ds_bpermute_b32 v163, v162, v108
	ds_bpermute_b32 v182, v162, v111
	ds_bpermute_b32 v151, v162, v104
	v_readlane_b32 s53, v252, 3
	v_readlane_b32 s54, v252, 4
	v_readlane_b32 s55, v252, 5
	v_readlane_b32 s56, v252, 6
	s_waitcnt lgkmcnt(0)
	v_cndmask_b32_e64 v108, v151, v108, s[0:1]
	v_readlane_b32 s57, v252, 7
	v_readlane_b32 s58, v252, 8
	v_readlane_b32 s59, v252, 9
	v_readlane_b32 s60, v252, 10
	v_readlane_b32 s61, v252, 11
	v_readlane_b32 s64, v252, 14
	v_readlane_b32 s65, v252, 15
	s_waitcnt vmcnt(1)
	v_pk_fma_f32 v[114:115], v[50:51], v[112:113], v[166:167]
	v_pk_fma_f32 v[112:113], v[48:49], v[116:117], v[164:165]
	s_waitcnt vmcnt(0)
; __device__ __forceinline__ unsigned cvt_pk_bf16(float lo, float hi) { unsigned r; asm volatile("v_cvt_pk_bf16_f32 %0, %1, %2" : "=v"(r) : "v"(lo), "v"(hi)); return r; }
;     __device__ __forceinline__ void operator()(const f32x4 (&acc)[2][2][4][2], const Unit& u, int wr, int wc, int fr, int fq) const {
;     ...
;             for (int m = 0; m < 4; ++m) { const int ra = rowA + ai * HALF + m * 16, rb = rowB + ai * HALF + m * 16; const size_t offA = (size_t)ra * 1024 + col0, offB = (size_t)rb * 1024 + col0;
;                 float ssa = 0.f, ssb = 0.f;
; #pragma unroll
;                 for (int bj = 0; bj < 2; ++bj) {
;                     const f32x4 x0 = acc[ai][bj][m][0], x1 = acc[ai][bj][m][1]; f32x4 za, zb;
; #pragma unroll
;                     for (int e = 0; e < 4; ++e) { const float s1 = __shfl_xor(x1[e], 8), s0 = __shfl_xor(x0[e], 8); za[e] = hi8 ? s1 : x0[e]; zb[e] = hi8 ? x1[e] : s0; }
;                     const f32x4 ba = *(const f32x4*)(base + offA + bj * HALF), bb = *(const f32x4*)(base + offB + bj * HALF);
;                     const f32x4 oa = ba + gs[bj] * za, ob = bb + gs[bj] * zb;
;                     *(f32x4*)(out + offA + bj * HALF) = oa; *(f32x4*)(out + offB + bj * HALF) = ob;
;                     const f32x4 ha = oa * av[bj], hb = ob * av[bj];
;                     *(unsigned long long*)(Hn + offA + bj * HALF) = (unsigned long long)cvt_pk_bf16(ha[0], ha[1]) | ((unsigned long long)cvt_pk_bf16(ha[2], ha[3]) << 32);
;                     *(unsigned long long*)(Hn + offB + bj * HALF) = (unsigned long long)cvt_pk_bf16(hb[0], hb[1]) | ((unsigned long long)cvt_pk_bf16(hb[2], hb[3]) << 32);
;                     ssa += (oa[0] * oa[0] + oa[1] * oa[1]) + (oa[2] * oa[2] + oa[3] * oa[3]); ssb += (ob[0] * ob[0] + ob[1] * ob[1]) + (ob[2] * ob[2] + ob[3] * ob[3]); }
;                 ssa += __shfl_xor(ssa, 8); ssa += __shfl_xor(ssa, 16); ssa += __shfl_xor(ssa, 32);
;                 ssb += __shfl_xor(ssb, 8); ssb += __shfl_xor(ssb, 16); ssb += __shfl_xor(ssb, 32);
;                 if (fq == 0 && hi8 == 0) { atomicAdd(rowss + ra, ssa); atomicAdd(rowss + rb, ssb); } }
	v_pk_fma_f32 v[118:119], v[50:51], v[118:119], v[170:171]
	v_pk_fma_f32 v[116:117], v[48:49], v[180:181], v[168:169]
	v_pk_mul_f32 v[164:165], v[128:129], v[114:115]
	v_pk_mul_f32 v[166:167], v[130:131], v[112:113]
	global_store_dwordx4 v[172:173], v[112:115], off sc1
	global_store_dwordx4 v[176:177], v[116:119], off sc1
	v_pk_mul_f32 v[168:169], v[128:129], v[118:119]
	v_pk_mul_f32 v[170:171], v[130:131], v[116:117]
	v_cvt_pk_bf16_f32 v166, v166, v167
	v_cvt_pk_bf16_f32 v167, v164, v165
	global_store_dwordx2 v[134:135], v[166:167], off
	v_cvt_pk_bf16_f32 v164, v170, v171
	v_cvt_pk_bf16_f32 v165, v168, v169
	global_store_dwordx2 v[152:153], v[164:165], off
	global_load_dwordx4 v[164:167], v[174:175], off offset:512
	s_nop 0
	global_load_dwordx4 v[168:171], v[178:179], off offset:512
	ds_bpermute_b32 v175, v162, v105
	ds_bpermute_b32 v178, v162, v109
	ds_bpermute_b32 v179, v162, v106
	ds_bpermute_b32 v180, v162, v110
	ds_bpermute_b32 v181, v162, v107
	v_cndmask_b32_e64 v174, v104, v163, s[0:1]
	s_waitcnt lgkmcnt(4)
	v_cndmask_b32_e64 v109, v175, v109, s[0:1]
	s_waitcnt lgkmcnt(3)
	v_cndmask_b32_e64 v175, v105, v178, s[0:1]
	s_waitcnt lgkmcnt(2)
	v_cndmask_b32_e64 v104, v179, v110, s[0:1]
	s_waitcnt lgkmcnt(1)
	v_cndmask_b32_e64 v110, v106, v180, s[0:1]
	s_waitcnt lgkmcnt(0)
	v_cndmask_b32_e64 v105, v181, v111, s[0:1]
	v_cndmask_b32_e64 v111, v107, v182, s[0:1]
	v_mul_f32_e32 v106, v113, v113
	v_mul_f32_e32 v107, v115, v115
	v_mul_f32_e32 v113, v117, v117
	v_mul_f32_e32 v115, v119, v119
	v_fmac_f32_e32 v106, v112, v112
	v_fmac_f32_e32 v107, v114, v114
	v_fmac_f32_e32 v113, v116, v116
	v_fmac_f32_e32 v115, v118, v118
	v_add_f32_e32 v112, v106, v107
	v_add_f32_e32 v113, v113, v115
	s_waitcnt vmcnt(1)
	v_pk_fma_f32 v[106:107], v[54:55], v[104:105], v[166:167]
	v_pk_fma_f32 v[104:105], v[52:53], v[108:109], v[164:165]
	s_waitcnt vmcnt(0)
	v_pk_fma_f32 v[110:111], v[54:55], v[110:111], v[170:171]
	v_pk_fma_f32 v[108:109], v[52:53], v[174:175], v[168:169]
	v_mul_f32_e32 v114, v105, v105
	v_mul_f32_e32 v115, v107, v107
	v_mul_f32_e32 v116, v109, v109
	v_mul_f32_e32 v117, v111, v111
	v_fmac_f32_e32 v114, v104, v104
	v_fmac_f32_e32 v115, v106, v106
	v_fmac_f32_e32 v116, v108, v108
	v_fmac_f32_e32 v117, v110, v110
	v_add_f32_e32 v114, v114, v115
	v_add_f32_e32 v115, v116, v117
	v_add_f32_e32 v112, v112, v114
	v_add_f32_e32 v113, v113, v115
	ds_bpermute_b32 v114, v162, v112
	ds_bpermute_b32 v115, v162, v113
	global_store_dwordx4 v[172:173], v[104:107], off offset:512 sc1
	global_store_dwordx4 v[176:177], v[108:111], off offset:512 sc1
	s_waitcnt lgkmcnt(1)
	v_add_f32_e32 v114, v112, v114
	s_waitcnt lgkmcnt(0)
	v_add_f32_e32 v115, v113, v115
	ds_bpermute_b32 v116, v133, v114
	ds_bpermute_b32 v117, v133, v115
	v_pk_mul_f32 v[104:105], v[120:121], v[104:105]
	v_pk_mul_f32 v[106:107], v[122:123], v[106:107]
	v_cvt_pk_bf16_f32 v112, v104, v105
	s_waitcnt lgkmcnt(1)
	v_add_f32_e32 v104, v114, v116
	s_waitcnt lgkmcnt(0)
	v_add_f32_e32 v105, v115, v117
	v_cvt_pk_bf16_f32 v113, v106, v107
	ds_bpermute_b32 v106, v132, v104
	ds_bpermute_b32 v107, v132, v105
	v_pk_mul_f32 v[108:109], v[120:121], v[108:109]
	v_pk_mul_f32 v[110:111], v[122:123], v[110:111]
	global_store_dwordx2 v[134:135], v[112:113], off offset:256
	v_cvt_pk_bf16_f32 v108, v108, v109
	v_cvt_pk_bf16_f32 v109, v110, v111
	global_store_dwordx2 v[152:153], v[108:109], off offset:256
	s_and_saveexec_b64 s[28:29], s[18:19]
	s_cbranch_execz .LBB0_547
	v_lshl_add_u64 v[110:111], v[124:125], 2, s[68:69]
	s_waitcnt lgkmcnt(1)
	v_add_f32_e32 v104, v104, v106
	v_lshl_add_u64 v[108:109], v[126:127], 2, s[68:69]
	s_waitcnt lgkmcnt(0)
	v_add_f32_e32 v105, v105, v107
	global_atomic_add_f32 v[110:111], v104, off
	global_atomic_add_f32 v[108:109], v105, off
.LBB0_547:
	s_or_b64 exec, exec, s[28:29]
	v_or_b32_e32 v104, 32, v150
	s_waitcnt lgkmcnt(1)
	v_or_b32_e32 v106, 40, v150
	v_ashrrev_i32_e32 v105, 31, v104
	v_lshlrev_b64 v[108:109], 10, v[104:105]
	s_waitcnt lgkmcnt(0)
	v_ashrrev_i32_e32 v107, 31, v106
	v_readlane_b32 s52, v252, 18
	v_lshl_add_u64 v[116:117], v[108:109], 0, v[148:149]
	v_lshlrev_b64 v[108:109], 10, v[106:107]
	v_readlane_b32 s53, v252, 19
	v_lshl_add_u64 v[118:119], v[108:109], 0, v[148:149]
	v_lshlrev_b64 v[124:125], 2, v[116:117]
	s_mov_b64 s[36:37], s[52:53]
	v_lshl_add_u64 v[126:127], s[36:37], 0, v[124:125]
	v_lshlrev_b64 v[134:135], 2, v[118:119]
	global_load_dwordx4 v[108:111], v[126:127], off
	v_lshl_add_u64 v[152:153], s[36:37], 0, v[134:135]
	global_load_dwordx4 v[112:115], v[152:153], off
	ds_bpermute_b32 v151, v162, v96
	ds_bpermute_b32 v163, v162, v100
	ds_bpermute_b32 v165, v162, v97
	ds_bpermute_b32 v166, v162, v101
	ds_bpermute_b32 v167, v162, v98
	ds_bpermute_b32 v169, v162, v99
	ds_bpermute_b32 v168, v162, v102
	ds_bpermute_b32 v170, v162, v103
	v_readlane_b32 s54, v252, 20
	v_readlane_b32 s55, v252, 21
	v_readlane_b32 s56, v252, 22
	v_readlane_b32 s57, v252, 23
	v_readlane_b32 s58, v252, 24
	v_readlane_b32 s59, v252, 25
	v_readlane_b32 s60, v252, 26
	v_readlane_b32 s61, v252, 27
	v_readlane_b32 s62, v252, 28
	v_readlane_b32 s63, v252, 29
	v_readlane_b32 s64, v252, 30
	v_readlane_b32 s65, v252, 31
	v_readlane_b32 s66, v252, 32
	v_readlane_b32 s67, v252, 33
	v_readlane_b32 s52, v252, 2
	s_waitcnt lgkmcnt(7)
	v_cndmask_b32_e64 v100, v151, v100, s[0:1]
	s_waitcnt lgkmcnt(6)
	v_cndmask_b32_e64 v164, v96, v163, s[0:1]
	s_waitcnt lgkmcnt(5)
	v_cndmask_b32_e64 v101, v165, v101, s[0:1]
	s_waitcnt lgkmcnt(4)
	v_cndmask_b32_e64 v165, v97, v166, s[0:1]
	s_waitcnt lgkmcnt(3)
	v_cndmask_b32_e64 v96, v167, v102, s[0:1]
	s_waitcnt lgkmcnt(2)
; __device__ __forceinline__ unsigned cvt_pk_bf16(float lo, float hi) { unsigned r; asm volatile("v_cvt_pk_bf16_f32 %0, %1, %2" : "=v"(r) : "v"(lo), "v"(hi)); return r; }
;     __device__ __forceinline__ void operator()(const f32x4 (&acc)[2][2][4][2], const Unit& u, int wr, int wc, int fr, int fq) const {
;     ...
;             for (int m = 0; m < 4; ++m) { const int ra = rowA + ai * HALF + m * 16, rb = rowB + ai * HALF + m * 16; const size_t offA = (size_t)ra * 1024 + col0, offB = (size_t)rb * 1024 + col0;
;                 float ssa = 0.f, ssb = 0.f;
; #pragma unroll
;                 for (int bj = 0; bj < 2; ++bj) {
;                     const f32x4 x0 = acc[ai][bj][m][0], x1 = acc[ai][bj][m][1]; f32x4 za, zb;
; #pragma unroll
;                     for (int e = 0; e < 4; ++e) { const float s1 = __shfl_xor(x1[e], 8), s0 = __shfl_xor(x0[e], 8); za[e] = hi8 ? s1 : x0[e]; zb[e] = hi8 ? x1[e] : s0; }
;                     const f32x4 ba = *(const f32x4*)(base + offA + bj * HALF), bb = *(const f32x4*)(base + offB + bj * HALF);
;                     const f32x4 oa = ba + gs[bj] * za, ob = bb + gs[bj] * zb;
;                     *(f32x4*)(out + offA + bj * HALF) = oa; *(f32x4*)(out + offB + bj * HALF) = ob;
;                     const f32x4 ha = oa * av[bj], hb = ob * av[bj];
;                     *(unsigned long long*)(Hn + offA + bj * HALF) = (unsigned long long)cvt_pk_bf16(ha[0], ha[1]) | ((unsigned long long)cvt_pk_bf16(ha[2], ha[3]) << 32);
;                     *(unsigned long long*)(Hn + offB + bj * HALF) = (unsigned long long)cvt_pk_bf16(hb[0], hb[1]) | ((unsigned long long)cvt_pk_bf16(hb[2], hb[3]) << 32);
;                     ssa += (oa[0] * oa[0] + oa[1] * oa[1]) + (oa[2] * oa[2] + oa[3] * oa[3]); ssb += (ob[0] * ob[0] + ob[1] * ob[1]) + (ob[2] * ob[2] + ob[3] * ob[3]); }
;                 ssa += __shfl_xor(ssa, 8); ssa += __shfl_xor(ssa, 16); ssa += __shfl_xor(ssa, 32);
;                 ssb += __shfl_xor(ssb, 8); ssb += __shfl_xor(ssb, 16); ssb += __shfl_xor(ssb, 32);
;                 if (fq == 0 && hi8 == 0) { atomicAdd(rowss + ra, ssa); atomicAdd(rowss + rb, ssb); } }
	v_cndmask_b32_e64 v97, v169, v103, s[0:1]
	v_readlane_b32 s62, v252, 12
	v_readlane_b32 s63, v252, 13
	v_readlane_b32 s66, v252, 16
	v_readlane_b32 s67, v252, 17
	s_waitcnt lgkmcnt(1)
	v_cndmask_b32_e64 v102, v98, v168, s[0:1]
	s_waitcnt lgkmcnt(0)
	v_cndmask_b32_e64 v103, v99, v170, s[0:1]
	s_mov_b64 s[62:63], s[66:67]
	v_lshl_add_u64 v[116:117], v[116:117], 1, s[4:5]
	v_lshl_add_u64 v[118:119], v[118:119], 1, s[4:5]
	v_lshl_add_u64 v[124:125], s[62:63], 0, v[124:125]
	v_lshl_add_u64 v[134:135], s[62:63], 0, v[134:135]
	ds_bpermute_b32 v163, v162, v94
	ds_bpermute_b32 v151, v162, v89
	v_readlane_b32 s53, v252, 3
	v_readlane_b32 s54, v252, 4
	v_readlane_b32 s55, v252, 5
	v_readlane_b32 s56, v252, 6
	v_readlane_b32 s57, v252, 7
	v_readlane_b32 s58, v252, 8
	v_readlane_b32 s59, v252, 9
	v_readlane_b32 s60, v252, 10
	v_readlane_b32 s61, v252, 11
	v_readlane_b32 s64, v252, 14
	v_readlane_b32 s65, v252, 15
	s_waitcnt vmcnt(1)
	v_pk_fma_f32 v[98:99], v[50:51], v[96:97], v[110:111]
	v_pk_fma_f32 v[96:97], v[48:49], v[100:101], v[108:109]
	s_waitcnt vmcnt(0)
	v_pk_fma_f32 v[102:103], v[50:51], v[102:103], v[114:115]
	v_pk_fma_f32 v[100:101], v[48:49], v[164:165], v[112:113]
	v_pk_mul_f32 v[108:109], v[128:129], v[98:99]
	v_pk_mul_f32 v[110:111], v[130:131], v[96:97]
	global_store_dwordx4 v[124:125], v[96:99], off sc1
	global_store_dwordx4 v[134:135], v[100:103], off sc1
	v_pk_mul_f32 v[112:113], v[128:129], v[102:103]
	v_pk_mul_f32 v[114:115], v[130:131], v[100:101]
	v_cvt_pk_bf16_f32 v110, v110, v111
	v_cvt_pk_bf16_f32 v111, v108, v109
	global_store_dwordx2 v[116:117], v[110:111], off
	v_cvt_pk_bf16_f32 v108, v114, v115
	v_cvt_pk_bf16_f32 v109, v112, v113
	global_store_dwordx2 v[118:119], v[108:109], off
	global_load_dwordx4 v[108:111], v[126:127], off offset:512
	s_nop 0
	global_load_dwordx4 v[112:115], v[152:153], off offset:512
	ds_bpermute_b32 v126, v162, v88
	ds_bpermute_b32 v127, v162, v92
	ds_bpermute_b32 v152, v162, v93
	ds_bpermute_b32 v153, v162, v90
	ds_bpermute_b32 v164, v162, v91
	ds_bpermute_b32 v165, v162, v95
	s_waitcnt lgkmcnt(5)
	v_cndmask_b32_e64 v92, v126, v92, s[0:1]
	s_waitcnt lgkmcnt(4)
	v_cndmask_b32_e64 v126, v88, v127, s[0:1]
	s_waitcnt lgkmcnt(3)
	v_cndmask_b32_e64 v127, v89, v152, s[0:1]
	s_waitcnt lgkmcnt(2)
	v_cndmask_b32_e64 v88, v153, v94, s[0:1]
	v_cndmask_b32_e64 v94, v90, v163, s[0:1]
	s_waitcnt lgkmcnt(1)
	v_cndmask_b32_e64 v89, v164, v95, s[0:1]
	s_waitcnt lgkmcnt(0)
	v_cndmask_b32_e64 v95, v91, v165, s[0:1]
	v_mul_f32_e32 v90, v97, v97
	v_mul_f32_e32 v91, v99, v99
	v_cndmask_b32_e64 v93, v151, v93, s[0:1]
	v_mul_f32_e32 v97, v101, v101
	v_mul_f32_e32 v99, v103, v103
	v_fmac_f32_e32 v90, v96, v96
	v_fmac_f32_e32 v91, v98, v98
	v_fmac_f32_e32 v97, v100, v100
	v_fmac_f32_e32 v99, v102, v102
	v_add_f32_e32 v96, v90, v91
	v_add_f32_e32 v97, v97, v99
	s_waitcnt vmcnt(1)
	v_pk_fma_f32 v[90:91], v[54:55], v[88:89], v[110:111]
	v_pk_fma_f32 v[88:89], v[52:53], v[92:93], v[108:109]
	s_waitcnt vmcnt(0)
	v_pk_fma_f32 v[94:95], v[54:55], v[94:95], v[114:115]
	v_pk_fma_f32 v[92:93], v[52:53], v[126:127], v[112:113]
	v_mul_f32_e32 v98, v89, v89
	v_mul_f32_e32 v99, v91, v91
	v_mul_f32_e32 v100, v93, v93
	v_mul_f32_e32 v101, v95, v95
	v_fmac_f32_e32 v98, v88, v88
	v_fmac_f32_e32 v99, v90, v90
	v_fmac_f32_e32 v100, v92, v92
	v_fmac_f32_e32 v101, v94, v94
	v_add_f32_e32 v98, v98, v99
	v_add_f32_e32 v99, v100, v101
	v_add_f32_e32 v96, v96, v98
	v_add_f32_e32 v97, v97, v99
	ds_bpermute_b32 v98, v162, v96
	ds_bpermute_b32 v99, v162, v97
	global_store_dwordx4 v[124:125], v[88:91], off offset:512 sc1
	global_store_dwordx4 v[134:135], v[92:95], off offset:512 sc1
	s_waitcnt lgkmcnt(1)
	v_add_f32_e32 v98, v96, v98
	s_waitcnt lgkmcnt(0)
	v_add_f32_e32 v99, v97, v99
	ds_bpermute_b32 v100, v133, v98
	ds_bpermute_b32 v101, v133, v99
	v_pk_mul_f32 v[88:89], v[120:121], v[88:89]
	v_pk_mul_f32 v[90:91], v[122:123], v[90:91]
	v_cvt_pk_bf16_f32 v96, v88, v89
	s_waitcnt lgkmcnt(1)
	v_add_f32_e32 v88, v98, v100
	s_waitcnt lgkmcnt(0)
	v_add_f32_e32 v89, v99, v101
	v_cvt_pk_bf16_f32 v97, v90, v91
	ds_bpermute_b32 v90, v132, v88
	ds_bpermute_b32 v91, v132, v89
	v_pk_mul_f32 v[92:93], v[120:121], v[92:93]
	v_pk_mul_f32 v[94:95], v[122:123], v[94:95]
	global_store_dwordx2 v[116:117], v[96:97], off offset:256
	v_cvt_pk_bf16_f32 v92, v92, v93
	v_cvt_pk_bf16_f32 v93, v94, v95
	global_store_dwordx2 v[118:119], v[92:93], off offset:256
	s_and_saveexec_b64 s[28:29], s[18:19]
	s_cbranch_execz .LBB0_549
	v_lshl_add_u64 v[94:95], v[104:105], 2, s[68:69]
	s_waitcnt lgkmcnt(1)
	v_add_f32_e32 v88, v88, v90
	v_lshl_add_u64 v[92:93], v[106:107], 2, s[68:69]
	s_waitcnt lgkmcnt(0)
	v_add_f32_e32 v89, v89, v91
	global_atomic_add_f32 v[94:95], v88, off
	global_atomic_add_f32 v[92:93], v89, off
; __device__ __forceinline__ unsigned cvt_pk_bf16(float lo, float hi) { unsigned r; asm volatile("v_cvt_pk_bf16_f32 %0, %1, %2" : "=v"(r) : "v"(lo), "v"(hi)); return r; }
;     __device__ __forceinline__ void operator()(const f32x4 (&acc)[2][2][4][2], const Unit& u, int wr, int wc, int fr, int fq) const {
;     ...
;             for (int m = 0; m < 4; ++m) { const int ra = rowA + ai * HALF + m * 16, rb = rowB + ai * HALF + m * 16; const size_t offA = (size_t)ra * 1024 + col0, offB = (size_t)rb * 1024 + col0;
;                 float ssa = 0.f, ssb = 0.f;
; #pragma unroll
;                 for (int bj = 0; bj < 2; ++bj) {
;                     const f32x4 x0 = acc[ai][bj][m][0], x1 = acc[ai][bj][m][1]; f32x4 za, zb;
; #pragma unroll
;                     for (int e = 0; e < 4; ++e) { const float s1 = __shfl_xor(x1[e], 8), s0 = __shfl_xor(x0[e], 8); za[e] = hi8 ? s1 : x0[e]; zb[e] = hi8 ? x1[e] : s0; }
;                     const f32x4 ba = *(const f32x4*)(base + offA + bj * HALF), bb = *(const f32x4*)(base + offB + bj * HALF);
;                     const f32x4 oa = ba + gs[bj] * za, ob = bb + gs[bj] * zb;
;                     *(f32x4*)(out + offA + bj * HALF) = oa; *(f32x4*)(out + offB + bj * HALF) = ob;
;                     const f32x4 ha = oa * av[bj], hb = ob * av[bj];
;                     *(unsigned long long*)(Hn + offA + bj * HALF) = (unsigned long long)cvt_pk_bf16(ha[0], ha[1]) | ((unsigned long long)cvt_pk_bf16(ha[2], ha[3]) << 32);
;                     *(unsigned long long*)(Hn + offB + bj * HALF) = (unsigned long long)cvt_pk_bf16(hb[0], hb[1]) | ((unsigned long long)cvt_pk_bf16(hb[2], hb[3]) << 32);
;                     ssa += (oa[0] * oa[0] + oa[1] * oa[1]) + (oa[2] * oa[2] + oa[3] * oa[3]); ssb += (ob[0] * ob[0] + ob[1] * ob[1]) + (ob[2] * ob[2] + ob[3] * ob[3]); }
;                 ssa += __shfl_xor(ssa, 8); ssa += __shfl_xor(ssa, 16); ssa += __shfl_xor(ssa, 32);
;                 ssb += __shfl_xor(ssb, 8); ssb += __shfl_xor(ssb, 16); ssb += __shfl_xor(ssb, 32);
;                 if (fq == 0 && hi8 == 0) { atomicAdd(rowss + ra, ssa); atomicAdd(rowss + rb, ssb); } }
.LBB0_549:
	s_or_b64 exec, exec, s[28:29]
	v_or_b32_e32 v88, 48, v150
	s_waitcnt lgkmcnt(1)
	v_or_b32_e32 v90, 56, v150
	v_ashrrev_i32_e32 v89, 31, v88
	v_lshlrev_b64 v[92:93], 10, v[88:89]
	s_waitcnt lgkmcnt(0)
	v_ashrrev_i32_e32 v91, 31, v90
	v_readlane_b32 s52, v252, 18
	v_lshl_add_u64 v[100:101], v[92:93], 0, v[148:149]
	v_lshlrev_b64 v[92:93], 10, v[90:91]
	v_readlane_b32 s53, v252, 19
	v_lshl_add_u64 v[102:103], v[92:93], 0, v[148:149]
	v_lshlrev_b64 v[104:105], 2, v[100:101]
	s_mov_b64 s[36:37], s[52:53]
	v_lshl_add_u64 v[106:107], s[36:37], 0, v[104:105]
	v_lshlrev_b64 v[108:109], 2, v[102:103]
	global_load_dwordx4 v[92:95], v[106:107], off
	v_lshl_add_u64 v[110:111], s[36:37], 0, v[108:109]
	global_load_dwordx4 v[96:99], v[110:111], off
	ds_bpermute_b32 v112, v162, v80
	ds_bpermute_b32 v113, v162, v84
	ds_bpermute_b32 v114, v162, v81
	ds_bpermute_b32 v115, v162, v85
	ds_bpermute_b32 v116, v162, v82
	ds_bpermute_b32 v118, v162, v83
	ds_bpermute_b32 v117, v162, v86
	ds_bpermute_b32 v119, v162, v87
	v_readlane_b32 s54, v252, 20
	v_readlane_b32 s55, v252, 21
	v_readlane_b32 s56, v252, 22
	v_readlane_b32 s57, v252, 23
	v_readlane_b32 s58, v252, 24
	v_readlane_b32 s59, v252, 25
	v_readlane_b32 s60, v252, 26
	v_readlane_b32 s61, v252, 27
	v_readlane_b32 s62, v252, 28
	v_readlane_b32 s63, v252, 29
	v_readlane_b32 s64, v252, 30
	v_readlane_b32 s65, v252, 31
	v_readlane_b32 s66, v252, 32
	v_readlane_b32 s67, v252, 33
	v_readlane_b32 s52, v252, 2
	s_waitcnt lgkmcnt(7)
	v_cndmask_b32_e64 v84, v112, v84, s[0:1]
	s_waitcnt lgkmcnt(6)
	v_cndmask_b32_e64 v112, v80, v113, s[0:1]
	s_waitcnt lgkmcnt(5)
	v_cndmask_b32_e64 v85, v114, v85, s[0:1]
	s_waitcnt lgkmcnt(4)
	v_cndmask_b32_e64 v113, v81, v115, s[0:1]
	s_waitcnt lgkmcnt(3)
	v_cndmask_b32_e64 v80, v116, v86, s[0:1]
	s_waitcnt lgkmcnt(2)
	v_cndmask_b32_e64 v81, v118, v87, s[0:1]
	v_readlane_b32 s62, v252, 12
	v_readlane_b32 s63, v252, 13
	v_readlane_b32 s66, v252, 16
	v_readlane_b32 s67, v252, 17
	s_waitcnt lgkmcnt(1)
	v_cndmask_b32_e64 v86, v82, v117, s[0:1]
	s_waitcnt lgkmcnt(0)
	v_cndmask_b32_e64 v87, v83, v119, s[0:1]
	s_mov_b64 s[62:63], s[66:67]
	v_lshl_add_u64 v[100:101], v[100:101], 1, s[4:5]
	v_lshl_add_u64 v[102:103], v[102:103], 1, s[4:5]
	v_lshl_add_u64 v[104:105], s[62:63], 0, v[104:105]
	v_lshl_add_u64 v[108:109], s[62:63], 0, v[108:109]
	ds_bpermute_b32 v114, v162, v75
	ds_bpermute_b32 v115, v162, v79
	v_readlane_b32 s53, v252, 3
	v_readlane_b32 s54, v252, 4
	v_readlane_b32 s55, v252, 5
	v_readlane_b32 s56, v252, 6
	v_readlane_b32 s57, v252, 7
	v_readlane_b32 s58, v252, 8
	v_readlane_b32 s59, v252, 9
	v_readlane_b32 s60, v252, 10
	v_readlane_b32 s61, v252, 11
	v_readlane_b32 s64, v252, 14
	v_readlane_b32 s65, v252, 15
	s_waitcnt vmcnt(1)
	v_pk_fma_f32 v[82:83], v[50:51], v[80:81], v[94:95]
	v_pk_fma_f32 v[80:81], v[48:49], v[84:85], v[92:93]
	s_waitcnt vmcnt(0)
	v_pk_fma_f32 v[86:87], v[50:51], v[86:87], v[98:99]
	v_pk_fma_f32 v[84:85], v[48:49], v[112:113], v[96:97]
	v_pk_mul_f32 v[92:93], v[128:129], v[82:83]
	v_pk_mul_f32 v[94:95], v[130:131], v[80:81]
	global_store_dwordx4 v[104:105], v[80:83], off sc1
	global_store_dwordx4 v[108:109], v[84:87], off sc1
	v_pk_mul_f32 v[96:97], v[128:129], v[86:87]
	v_pk_mul_f32 v[98:99], v[130:131], v[84:85]
	v_cvt_pk_bf16_f32 v94, v94, v95
	v_cvt_pk_bf16_f32 v95, v92, v93
	global_store_dwordx2 v[100:101], v[94:95], off
	v_cvt_pk_bf16_f32 v92, v98, v99
	v_cvt_pk_bf16_f32 v93, v96, v97
	global_store_dwordx2 v[102:103], v[92:93], off
	global_load_dwordx4 v[92:95], v[106:107], off offset:512
	s_nop 0
	global_load_dwordx4 v[96:99], v[110:111], off offset:512
	ds_bpermute_b32 v106, v162, v72
	ds_bpermute_b32 v107, v162, v76
	ds_bpermute_b32 v111, v162, v77
	ds_bpermute_b32 v112, v162, v74
	ds_bpermute_b32 v113, v162, v78
	ds_bpermute_b32 v110, v162, v73
	s_waitcnt lgkmcnt(5)
	v_cndmask_b32_e64 v76, v106, v76, s[0:1]
	s_waitcnt lgkmcnt(4)
	v_cndmask_b32_e64 v106, v72, v107, s[0:1]
	s_waitcnt lgkmcnt(3)
	v_cndmask_b32_e64 v107, v73, v111, s[0:1]
	s_waitcnt lgkmcnt(2)
	v_cndmask_b32_e64 v72, v112, v78, s[0:1]
	s_waitcnt lgkmcnt(1)
	v_cndmask_b32_e64 v78, v74, v113, s[0:1]
	v_cndmask_b32_e64 v73, v114, v79, s[0:1]
	v_cndmask_b32_e64 v79, v75, v115, s[0:1]
	v_mul_f32_e32 v74, v81, v81
	v_mul_f32_e32 v75, v83, v83
	s_waitcnt lgkmcnt(0)
	v_cndmask_b32_e64 v77, v110, v77, s[0:1]
	v_mul_f32_e32 v81, v85, v85
	v_mul_f32_e32 v83, v87, v87
	v_fmac_f32_e32 v74, v80, v80
	v_fmac_f32_e32 v75, v82, v82
	v_fmac_f32_e32 v81, v84, v84
	v_fmac_f32_e32 v83, v86, v86
	v_add_f32_e32 v80, v74, v75
	v_add_f32_e32 v81, v81, v83
	s_waitcnt vmcnt(1)
	v_pk_fma_f32 v[74:75], v[54:55], v[72:73], v[94:95]
	v_pk_fma_f32 v[72:73], v[52:53], v[76:77], v[92:93]
	s_waitcnt vmcnt(0)
	v_pk_fma_f32 v[78:79], v[54:55], v[78:79], v[98:99]
	v_pk_fma_f32 v[76:77], v[52:53], v[106:107], v[96:97]
	v_mul_f32_e32 v82, v73, v73
	v_mul_f32_e32 v83, v75, v75
	v_mul_f32_e32 v84, v77, v77
	v_mul_f32_e32 v85, v79, v79
	v_fmac_f32_e32 v82, v72, v72
	v_fmac_f32_e32 v83, v74, v74
	v_fmac_f32_e32 v84, v76, v76
	v_fmac_f32_e32 v85, v78, v78
	v_add_f32_e32 v82, v82, v83
	v_add_f32_e32 v83, v84, v85
	v_add_f32_e32 v80, v80, v82
	v_add_f32_e32 v81, v81, v83
	ds_bpermute_b32 v82, v162, v80
	ds_bpermute_b32 v83, v162, v81
	global_store_dwordx4 v[104:105], v[72:75], off offset:512 sc1
	global_store_dwordx4 v[108:109], v[76:79], off offset:512 sc1
	s_waitcnt lgkmcnt(1)
	v_add_f32_e32 v82, v80, v82
	s_waitcnt lgkmcnt(0)
	v_add_f32_e32 v83, v81, v83
	ds_bpermute_b32 v84, v133, v82
	ds_bpermute_b32 v85, v133, v83
	v_pk_mul_f32 v[72:73], v[120:121], v[72:73]
	v_pk_mul_f32 v[74:75], v[122:123], v[74:75]
	v_cvt_pk_bf16_f32 v80, v72, v73
	s_waitcnt lgkmcnt(1)
	v_add_f32_e32 v72, v82, v84
	s_waitcnt lgkmcnt(0)
	v_add_f32_e32 v73, v83, v85
	v_cvt_pk_bf16_f32 v81, v74, v75
	ds_bpermute_b32 v74, v132, v72
	ds_bpermute_b32 v75, v132, v73
	v_pk_mul_f32 v[76:77], v[120:121], v[76:77]
	v_pk_mul_f32 v[78:79], v[122:123], v[78:79]
	global_store_dwordx2 v[100:101], v[80:81], off offset:256
	v_cvt_pk_bf16_f32 v76, v76, v77
	v_cvt_pk_bf16_f32 v77, v78, v79
	global_store_dwordx2 v[102:103], v[76:77], off offset:256
	s_and_saveexec_b64 s[28:29], s[18:19]
	s_cbranch_execz .LBB0_551
	v_lshl_add_u64 v[78:79], v[88:89], 2, s[68:69]
	s_waitcnt lgkmcnt(1)
	v_add_f32_e32 v72, v72, v74
	v_lshl_add_u64 v[76:77], v[90:91], 2, s[68:69]
	s_waitcnt lgkmcnt(0)
	v_add_f32_e32 v73, v73, v75
	global_atomic_add_f32 v[78:79], v72, off
	global_atomic_add_f32 v[76:77], v73, off
; __device__ __forceinline__ unsigned cvt_pk_bf16(float lo, float hi) { unsigned r; asm volatile("v_cvt_pk_bf16_f32 %0, %1, %2" : "=v"(r) : "v"(lo), "v"(hi)); return r; }
;     __device__ __forceinline__ void operator()(const f32x4 (&acc)[2][2][4][2], const Unit& u, int wr, int wc, int fr, int fq) const {
;     ...
;             for (int m = 0; m < 4; ++m) { const int ra = rowA + ai * HALF + m * 16, rb = rowB + ai * HALF + m * 16; const size_t offA = (size_t)ra * 1024 + col0, offB = (size_t)rb * 1024 + col0;
;                 float ssa = 0.f, ssb = 0.f;
; #pragma unroll
;                 for (int bj = 0; bj < 2; ++bj) {
;                     const f32x4 x0 = acc[ai][bj][m][0], x1 = acc[ai][bj][m][1]; f32x4 za, zb;
; #pragma unroll
;                     for (int e = 0; e < 4; ++e) { const float s1 = __shfl_xor(x1[e], 8), s0 = __shfl_xor(x0[e], 8); za[e] = hi8 ? s1 : x0[e]; zb[e] = hi8 ? x1[e] : s0; }
;                     const f32x4 ba = *(const f32x4*)(base + offA + bj * HALF), bb = *(const f32x4*)(base + offB + bj * HALF);
;                     const f32x4 oa = ba + gs[bj] * za, ob = bb + gs[bj] * zb;
;                     *(f32x4*)(out + offA + bj * HALF) = oa; *(f32x4*)(out + offB + bj * HALF) = ob;
;                     const f32x4 ha = oa * av[bj], hb = ob * av[bj];
;                     *(unsigned long long*)(Hn + offA + bj * HALF) = (unsigned long long)cvt_pk_bf16(ha[0], ha[1]) | ((unsigned long long)cvt_pk_bf16(ha[2], ha[3]) << 32);
;                     *(unsigned long long*)(Hn + offB + bj * HALF) = (unsigned long long)cvt_pk_bf16(hb[0], hb[1]) | ((unsigned long long)cvt_pk_bf16(hb[2], hb[3]) << 32);
;                     ssa += (oa[0] * oa[0] + oa[1] * oa[1]) + (oa[2] * oa[2] + oa[3] * oa[3]); ssb += (ob[0] * ob[0] + ob[1] * ob[1]) + (ob[2] * ob[2] + ob[3] * ob[3]); }
;                 ssa += __shfl_xor(ssa, 8); ssa += __shfl_xor(ssa, 16); ssa += __shfl_xor(ssa, 32);
;                 ssb += __shfl_xor(ssb, 8); ssb += __shfl_xor(ssb, 16); ssb += __shfl_xor(ssb, 32);
;                 if (fq == 0 && hi8 == 0) { atomicAdd(rowss + ra, ssa); atomicAdd(rowss + rb, ssb); } }
.LBB0_551:
	s_or_b64 exec, exec, s[28:29]
	v_add_u32_e32 v72, 0x80, v150
	s_waitcnt lgkmcnt(1)
	v_add_u32_e32 v74, 0x88, v150
	v_ashrrev_i32_e32 v73, 31, v72
	v_lshlrev_b64 v[76:77], 10, v[72:73]
	s_waitcnt lgkmcnt(0)
	v_ashrrev_i32_e32 v75, 31, v74
	v_readlane_b32 s52, v252, 18
	v_lshl_add_u64 v[84:85], v[76:77], 0, v[148:149]
	v_lshlrev_b64 v[76:77], 10, v[74:75]
	v_readlane_b32 s53, v252, 19
	v_lshl_add_u64 v[86:87], v[76:77], 0, v[148:149]
	v_lshlrev_b64 v[88:89], 2, v[84:85]
	s_mov_b64 s[36:37], s[52:53]
	v_lshl_add_u64 v[90:91], s[36:37], 0, v[88:89]
	v_lshlrev_b64 v[92:93], 2, v[86:87]
	global_load_dwordx4 v[76:79], v[90:91], off
	v_lshl_add_u64 v[94:95], s[36:37], 0, v[92:93]
	global_load_dwordx4 v[80:83], v[94:95], off
	ds_bpermute_b32 v96, v162, v64
	ds_bpermute_b32 v97, v162, v68
	ds_bpermute_b32 v98, v162, v65
	ds_bpermute_b32 v99, v162, v69
	ds_bpermute_b32 v100, v162, v66
	ds_bpermute_b32 v102, v162, v67
	ds_bpermute_b32 v101, v162, v70
	ds_bpermute_b32 v103, v162, v71
	v_readlane_b32 s54, v252, 20
	v_readlane_b32 s55, v252, 21
	v_readlane_b32 s56, v252, 22
	v_readlane_b32 s57, v252, 23
	v_readlane_b32 s58, v252, 24
	v_readlane_b32 s59, v252, 25
	v_readlane_b32 s60, v252, 26
	v_readlane_b32 s61, v252, 27
	v_readlane_b32 s62, v252, 28
	v_readlane_b32 s63, v252, 29
	v_readlane_b32 s64, v252, 30
	v_readlane_b32 s65, v252, 31
	v_readlane_b32 s66, v252, 32
	v_readlane_b32 s67, v252, 33
	v_readlane_b32 s52, v252, 2
	s_waitcnt lgkmcnt(7)
	v_cndmask_b32_e64 v68, v96, v68, s[0:1]
	s_waitcnt lgkmcnt(6)
	v_cndmask_b32_e64 v96, v64, v97, s[0:1]
	s_waitcnt lgkmcnt(5)
	v_cndmask_b32_e64 v69, v98, v69, s[0:1]
	s_waitcnt lgkmcnt(4)
	v_cndmask_b32_e64 v97, v65, v99, s[0:1]
	s_waitcnt lgkmcnt(3)
	v_cndmask_b32_e64 v64, v100, v70, s[0:1]
	s_waitcnt lgkmcnt(2)
	v_cndmask_b32_e64 v65, v102, v71, s[0:1]
	v_readlane_b32 s62, v252, 12
	v_readlane_b32 s63, v252, 13
	v_readlane_b32 s66, v252, 16
	v_readlane_b32 s67, v252, 17
	s_waitcnt lgkmcnt(1)
	v_cndmask_b32_e64 v70, v66, v101, s[0:1]
	s_waitcnt lgkmcnt(0)
	v_cndmask_b32_e64 v71, v67, v103, s[0:1]
	s_mov_b64 s[62:63], s[66:67]
	v_lshl_add_u64 v[84:85], v[84:85], 1, s[4:5]
	v_lshl_add_u64 v[86:87], v[86:87], 1, s[4:5]
	v_lshl_add_u64 v[88:89], s[62:63], 0, v[88:89]
	v_lshl_add_u64 v[92:93], s[62:63], 0, v[92:93]
	ds_bpermute_b32 v98, v162, v59
	ds_bpermute_b32 v99, v162, v63
	v_readlane_b32 s53, v252, 3
	v_readlane_b32 s54, v252, 4
	v_readlane_b32 s55, v252, 5
	v_readlane_b32 s56, v252, 6
	v_readlane_b32 s57, v252, 7
	v_readlane_b32 s58, v252, 8
	v_readlane_b32 s59, v252, 9
	v_readlane_b32 s60, v252, 10
	v_readlane_b32 s61, v252, 11
	v_readlane_b32 s64, v252, 14
	v_readlane_b32 s65, v252, 15
	s_waitcnt vmcnt(1)
	v_pk_fma_f32 v[66:67], v[50:51], v[64:65], v[78:79]
	v_pk_fma_f32 v[64:65], v[48:49], v[68:69], v[76:77]
	s_waitcnt vmcnt(0)
	v_pk_fma_f32 v[70:71], v[50:51], v[70:71], v[82:83]
	v_pk_fma_f32 v[68:69], v[48:49], v[96:97], v[80:81]
	v_pk_mul_f32 v[76:77], v[128:129], v[66:67]
	v_pk_mul_f32 v[78:79], v[130:131], v[64:65]
	global_store_dwordx4 v[88:89], v[64:67], off sc1
	global_store_dwordx4 v[92:93], v[68:71], off sc1
	v_pk_mul_f32 v[80:81], v[128:129], v[70:71]
	v_pk_mul_f32 v[82:83], v[130:131], v[68:69]
	v_cvt_pk_bf16_f32 v78, v78, v79
	v_cvt_pk_bf16_f32 v79, v76, v77
	global_store_dwordx2 v[84:85], v[78:79], off
	v_cvt_pk_bf16_f32 v76, v82, v83
	v_cvt_pk_bf16_f32 v77, v80, v81
	global_store_dwordx2 v[86:87], v[76:77], off
	global_load_dwordx4 v[76:79], v[90:91], off offset:512
	s_nop 0
	global_load_dwordx4 v[80:83], v[94:95], off offset:512
	ds_bpermute_b32 v90, v162, v56
	ds_bpermute_b32 v91, v162, v60
	ds_bpermute_b32 v95, v162, v61
	ds_bpermute_b32 v96, v162, v58
	ds_bpermute_b32 v97, v162, v62
	ds_bpermute_b32 v94, v162, v57
	s_waitcnt lgkmcnt(5)
	v_cndmask_b32_e64 v60, v90, v60, s[0:1]
	s_waitcnt lgkmcnt(4)
	v_cndmask_b32_e64 v90, v56, v91, s[0:1]
	s_waitcnt lgkmcnt(3)
	v_cndmask_b32_e64 v91, v57, v95, s[0:1]
	s_waitcnt lgkmcnt(2)
	v_cndmask_b32_e64 v56, v96, v62, s[0:1]
	s_waitcnt lgkmcnt(1)
	v_cndmask_b32_e64 v62, v58, v97, s[0:1]
	v_cndmask_b32_e64 v57, v98, v63, s[0:1]
	v_cndmask_b32_e64 v63, v59, v99, s[0:1]
	v_mul_f32_e32 v58, v65, v65
	v_mul_f32_e32 v59, v67, v67
	s_waitcnt lgkmcnt(0)
	v_cndmask_b32_e64 v61, v94, v61, s[0:1]
	v_mul_f32_e32 v65, v69, v69
	v_mul_f32_e32 v67, v71, v71
	v_fmac_f32_e32 v58, v64, v64
	v_fmac_f32_e32 v59, v66, v66
	v_fmac_f32_e32 v65, v68, v68
	v_fmac_f32_e32 v67, v70, v70
	v_add_f32_e32 v64, v58, v59
	v_add_f32_e32 v65, v65, v67
	s_waitcnt vmcnt(1)
	v_pk_fma_f32 v[58:59], v[54:55], v[56:57], v[78:79]
	v_pk_fma_f32 v[56:57], v[52:53], v[60:61], v[76:77]
	s_waitcnt vmcnt(0)
	v_pk_fma_f32 v[62:63], v[54:55], v[62:63], v[82:83]
	v_pk_fma_f32 v[60:61], v[52:53], v[90:91], v[80:81]
	v_mul_f32_e32 v66, v57, v57
	v_mul_f32_e32 v67, v59, v59
	v_mul_f32_e32 v68, v61, v61
	v_mul_f32_e32 v69, v63, v63
	v_fmac_f32_e32 v66, v56, v56
	v_fmac_f32_e32 v67, v58, v58
	v_fmac_f32_e32 v68, v60, v60
	v_fmac_f32_e32 v69, v62, v62
	v_add_f32_e32 v66, v66, v67
	v_add_f32_e32 v67, v68, v69
	v_add_f32_e32 v64, v64, v66
	v_add_f32_e32 v65, v65, v67
	ds_bpermute_b32 v66, v162, v64
	ds_bpermute_b32 v67, v162, v65
	global_store_dwordx4 v[88:89], v[56:59], off offset:512 sc1
	global_store_dwordx4 v[92:93], v[60:63], off offset:512 sc1
	s_waitcnt lgkmcnt(1)
	v_add_f32_e32 v66, v64, v66
	s_waitcnt lgkmcnt(0)
	v_add_f32_e32 v67, v65, v67
	ds_bpermute_b32 v68, v133, v66
	ds_bpermute_b32 v69, v133, v67
	v_pk_mul_f32 v[56:57], v[120:121], v[56:57]
	v_pk_mul_f32 v[58:59], v[122:123], v[58:59]
	v_cvt_pk_bf16_f32 v64, v56, v57
	s_waitcnt lgkmcnt(1)
	v_add_f32_e32 v56, v66, v68
	s_waitcnt lgkmcnt(0)
	v_add_f32_e32 v57, v67, v69
	v_cvt_pk_bf16_f32 v65, v58, v59
	ds_bpermute_b32 v58, v132, v56
	ds_bpermute_b32 v59, v132, v57
	v_pk_mul_f32 v[60:61], v[120:121], v[60:61]
	v_pk_mul_f32 v[62:63], v[122:123], v[62:63]
	global_store_dwordx2 v[84:85], v[64:65], off offset:256
	v_cvt_pk_bf16_f32 v60, v60, v61
	v_cvt_pk_bf16_f32 v61, v62, v63
	global_store_dwordx2 v[86:87], v[60:61], off offset:256
	s_and_saveexec_b64 s[28:29], s[18:19]
	s_cbranch_execz .LBB0_553
	v_lshl_add_u64 v[62:63], v[72:73], 2, s[68:69]
	s_waitcnt lgkmcnt(1)
	v_add_f32_e32 v56, v56, v58
	v_lshl_add_u64 v[60:61], v[74:75], 2, s[68:69]
	s_waitcnt lgkmcnt(0)
	v_add_f32_e32 v57, v57, v59
	global_atomic_add_f32 v[62:63], v56, off
	global_atomic_add_f32 v[60:61], v57, off
; __device__ __forceinline__ unsigned cvt_pk_bf16(float lo, float hi) { unsigned r; asm volatile("v_cvt_pk_bf16_f32 %0, %1, %2" : "=v"(r) : "v"(lo), "v"(hi)); return r; }
;     __device__ __forceinline__ void operator()(const f32x4 (&acc)[2][2][4][2], const Unit& u, int wr, int wc, int fr, int fq) const {
;     ...
;             for (int m = 0; m < 4; ++m) { const int ra = rowA + ai * HALF + m * 16, rb = rowB + ai * HALF + m * 16; const size_t offA = (size_t)ra * 1024 + col0, offB = (size_t)rb * 1024 + col0;
;                 float ssa = 0.f, ssb = 0.f;
; #pragma unroll
;                 for (int bj = 0; bj < 2; ++bj) {
;                     const f32x4 x0 = acc[ai][bj][m][0], x1 = acc[ai][bj][m][1]; f32x4 za, zb;
; #pragma unroll
;                     for (int e = 0; e < 4; ++e) { const float s1 = __shfl_xor(x1[e], 8), s0 = __shfl_xor(x0[e], 8); za[e] = hi8 ? s1 : x0[e]; zb[e] = hi8 ? x1[e] : s0; }
;                     const f32x4 ba = *(const f32x4*)(base + offA + bj * HALF), bb = *(const f32x4*)(base + offB + bj * HALF);
;                     const f32x4 oa = ba + gs[bj] * za, ob = bb + gs[bj] * zb;
;                     *(f32x4*)(out + offA + bj * HALF) = oa; *(f32x4*)(out + offB + bj * HALF) = ob;
;                     const f32x4 ha = oa * av[bj], hb = ob * av[bj];
;                     *(unsigned long long*)(Hn + offA + bj * HALF) = (unsigned long long)cvt_pk_bf16(ha[0], ha[1]) | ((unsigned long long)cvt_pk_bf16(ha[2], ha[3]) << 32);
;                     *(unsigned long long*)(Hn + offB + bj * HALF) = (unsigned long long)cvt_pk_bf16(hb[0], hb[1]) | ((unsigned long long)cvt_pk_bf16(hb[2], hb[3]) << 32);
;                     ssa += (oa[0] * oa[0] + oa[1] * oa[1]) + (oa[2] * oa[2] + oa[3] * oa[3]); ssb += (ob[0] * ob[0] + ob[1] * ob[1]) + (ob[2] * ob[2] + ob[3] * ob[3]); }
;                 ssa += __shfl_xor(ssa, 8); ssa += __shfl_xor(ssa, 16); ssa += __shfl_xor(ssa, 32);
;                 ssb += __shfl_xor(ssb, 8); ssb += __shfl_xor(ssb, 16); ssb += __shfl_xor(ssb, 32);
;                 if (fq == 0 && hi8 == 0) { atomicAdd(rowss + ra, ssa); atomicAdd(rowss + rb, ssb); } }
.LBB0_553:
	s_or_b64 exec, exec, s[28:29]
	v_add_u32_e32 v56, 0x90, v150
	s_waitcnt lgkmcnt(1)
	v_add_u32_e32 v58, 0x98, v150
	v_ashrrev_i32_e32 v57, 31, v56
	v_lshlrev_b64 v[60:61], 10, v[56:57]
	s_waitcnt lgkmcnt(0)
	v_ashrrev_i32_e32 v59, 31, v58
	v_readlane_b32 s52, v252, 18
	v_lshl_add_u64 v[68:69], v[60:61], 0, v[148:149]
	v_lshlrev_b64 v[60:61], 10, v[58:59]
	v_readlane_b32 s53, v252, 19
	v_lshl_add_u64 v[70:71], v[60:61], 0, v[148:149]
	v_lshlrev_b64 v[72:73], 2, v[68:69]
	s_mov_b64 s[36:37], s[52:53]
	v_lshl_add_u64 v[74:75], s[36:37], 0, v[72:73]
	v_lshlrev_b64 v[76:77], 2, v[70:71]
	global_load_dwordx4 v[60:63], v[74:75], off
	v_lshl_add_u64 v[78:79], s[36:37], 0, v[76:77]
	global_load_dwordx4 v[64:67], v[78:79], off
	ds_bpermute_b32 v80, v162, v40
	ds_bpermute_b32 v81, v162, v44
	ds_bpermute_b32 v82, v162, v41
	ds_bpermute_b32 v83, v162, v45
	ds_bpermute_b32 v84, v162, v42
	ds_bpermute_b32 v86, v162, v43
	ds_bpermute_b32 v85, v162, v46
	ds_bpermute_b32 v87, v162, v47
	v_readlane_b32 s54, v252, 20
	v_readlane_b32 s55, v252, 21
	v_readlane_b32 s56, v252, 22
	v_readlane_b32 s57, v252, 23
	v_readlane_b32 s58, v252, 24
	v_readlane_b32 s59, v252, 25
	v_readlane_b32 s60, v252, 26
	v_readlane_b32 s61, v252, 27
	v_readlane_b32 s62, v252, 28
	v_readlane_b32 s63, v252, 29
	v_readlane_b32 s64, v252, 30
	v_readlane_b32 s65, v252, 31
	v_readlane_b32 s66, v252, 32
	v_readlane_b32 s67, v252, 33
	v_readlane_b32 s52, v252, 2
	s_waitcnt lgkmcnt(7)
	v_cndmask_b32_e64 v44, v80, v44, s[0:1]
	s_waitcnt lgkmcnt(6)
	v_cndmask_b32_e64 v80, v40, v81, s[0:1]
	s_waitcnt lgkmcnt(5)
	v_cndmask_b32_e64 v45, v82, v45, s[0:1]
	s_waitcnt lgkmcnt(4)
	v_cndmask_b32_e64 v81, v41, v83, s[0:1]
	s_waitcnt lgkmcnt(3)
	v_cndmask_b32_e64 v40, v84, v46, s[0:1]
	s_waitcnt lgkmcnt(2)
	v_cndmask_b32_e64 v41, v86, v47, s[0:1]
	v_readlane_b32 s62, v252, 12
	v_readlane_b32 s63, v252, 13
	v_readlane_b32 s66, v252, 16
	v_readlane_b32 s67, v252, 17
	s_waitcnt lgkmcnt(1)
	v_cndmask_b32_e64 v46, v42, v85, s[0:1]
	s_waitcnt lgkmcnt(0)
	v_cndmask_b32_e64 v47, v43, v87, s[0:1]
	s_mov_b64 s[62:63], s[66:67]
	v_lshl_add_u64 v[68:69], v[68:69], 1, s[4:5]
	v_lshl_add_u64 v[70:71], v[70:71], 1, s[4:5]
	v_lshl_add_u64 v[72:73], s[62:63], 0, v[72:73]
	v_lshl_add_u64 v[76:77], s[62:63], 0, v[76:77]
	ds_bpermute_b32 v82, v162, v35
	ds_bpermute_b32 v83, v162, v39
	v_readlane_b32 s53, v252, 3
	v_readlane_b32 s54, v252, 4
	v_readlane_b32 s55, v252, 5
	v_readlane_b32 s56, v252, 6
	v_readlane_b32 s57, v252, 7
	v_readlane_b32 s58, v252, 8
	v_readlane_b32 s59, v252, 9
	v_readlane_b32 s60, v252, 10
	v_readlane_b32 s61, v252, 11
	v_readlane_b32 s64, v252, 14
	v_readlane_b32 s65, v252, 15
	s_waitcnt vmcnt(1)
	v_pk_fma_f32 v[42:43], v[50:51], v[40:41], v[62:63]
	v_pk_fma_f32 v[40:41], v[48:49], v[44:45], v[60:61]
	s_waitcnt vmcnt(0)
	v_pk_fma_f32 v[46:47], v[50:51], v[46:47], v[66:67]
	v_pk_fma_f32 v[44:45], v[48:49], v[80:81], v[64:65]
	v_pk_mul_f32 v[60:61], v[128:129], v[42:43]
	v_pk_mul_f32 v[62:63], v[130:131], v[40:41]
	global_store_dwordx4 v[72:73], v[40:43], off sc1
	global_store_dwordx4 v[76:77], v[44:47], off sc1
	v_pk_mul_f32 v[64:65], v[128:129], v[46:47]
	v_pk_mul_f32 v[66:67], v[130:131], v[44:45]
	v_cvt_pk_bf16_f32 v62, v62, v63
	v_cvt_pk_bf16_f32 v63, v60, v61
	global_store_dwordx2 v[68:69], v[62:63], off
	v_cvt_pk_bf16_f32 v60, v66, v67
	v_cvt_pk_bf16_f32 v61, v64, v65
	global_store_dwordx2 v[70:71], v[60:61], off
	global_load_dwordx4 v[60:63], v[74:75], off offset:512
	s_nop 0
	global_load_dwordx4 v[64:67], v[78:79], off offset:512
	ds_bpermute_b32 v74, v162, v32
	ds_bpermute_b32 v75, v162, v36
	ds_bpermute_b32 v79, v162, v37
	ds_bpermute_b32 v80, v162, v34
	ds_bpermute_b32 v81, v162, v38
	ds_bpermute_b32 v78, v162, v33
	s_waitcnt lgkmcnt(5)
	v_cndmask_b32_e64 v36, v74, v36, s[0:1]
	s_waitcnt lgkmcnt(4)
	v_cndmask_b32_e64 v74, v32, v75, s[0:1]
	s_waitcnt lgkmcnt(3)
	v_cndmask_b32_e64 v75, v33, v79, s[0:1]
	s_waitcnt lgkmcnt(2)
	v_cndmask_b32_e64 v32, v80, v38, s[0:1]
	s_waitcnt lgkmcnt(1)
	v_cndmask_b32_e64 v38, v34, v81, s[0:1]
	v_cndmask_b32_e64 v33, v82, v39, s[0:1]
	v_cndmask_b32_e64 v39, v35, v83, s[0:1]
	v_mul_f32_e32 v34, v41, v41
	v_mul_f32_e32 v35, v43, v43
	s_waitcnt lgkmcnt(0)
	v_cndmask_b32_e64 v37, v78, v37, s[0:1]
	v_mul_f32_e32 v41, v45, v45
	v_mul_f32_e32 v43, v47, v47
	v_fmac_f32_e32 v34, v40, v40
	v_fmac_f32_e32 v35, v42, v42
	v_fmac_f32_e32 v41, v44, v44
	v_fmac_f32_e32 v43, v46, v46
	v_add_f32_e32 v40, v34, v35
	v_add_f32_e32 v41, v41, v43
	s_waitcnt vmcnt(1)
	v_pk_fma_f32 v[34:35], v[54:55], v[32:33], v[62:63]
	v_pk_fma_f32 v[32:33], v[52:53], v[36:37], v[60:61]
	s_waitcnt vmcnt(0)
	v_pk_fma_f32 v[38:39], v[54:55], v[38:39], v[66:67]
	v_pk_fma_f32 v[36:37], v[52:53], v[74:75], v[64:65]
	v_mul_f32_e32 v42, v33, v33
	v_mul_f32_e32 v43, v35, v35
	v_mul_f32_e32 v44, v37, v37
	v_mul_f32_e32 v45, v39, v39
	v_fmac_f32_e32 v42, v32, v32
	v_fmac_f32_e32 v43, v34, v34
	v_fmac_f32_e32 v44, v36, v36
	v_fmac_f32_e32 v45, v38, v38
	v_add_f32_e32 v42, v42, v43
	v_add_f32_e32 v43, v44, v45
	v_add_f32_e32 v40, v40, v42
	v_add_f32_e32 v41, v41, v43
	ds_bpermute_b32 v42, v162, v40
	ds_bpermute_b32 v43, v162, v41
	global_store_dwordx4 v[72:73], v[32:35], off offset:512 sc1
	global_store_dwordx4 v[76:77], v[36:39], off offset:512 sc1
	s_waitcnt lgkmcnt(1)
	v_add_f32_e32 v42, v40, v42
	s_waitcnt lgkmcnt(0)
	v_add_f32_e32 v43, v41, v43
	ds_bpermute_b32 v44, v133, v42
	ds_bpermute_b32 v45, v133, v43
	v_pk_mul_f32 v[32:33], v[120:121], v[32:33]
	v_pk_mul_f32 v[34:35], v[122:123], v[34:35]
	v_cvt_pk_bf16_f32 v40, v32, v33
	s_waitcnt lgkmcnt(1)
	v_add_f32_e32 v32, v42, v44
	s_waitcnt lgkmcnt(0)
	v_add_f32_e32 v33, v43, v45
	v_cvt_pk_bf16_f32 v41, v34, v35
	ds_bpermute_b32 v34, v132, v32
	ds_bpermute_b32 v35, v132, v33
	v_pk_mul_f32 v[36:37], v[120:121], v[36:37]
	v_pk_mul_f32 v[38:39], v[122:123], v[38:39]
	global_store_dwordx2 v[68:69], v[40:41], off offset:256
	v_cvt_pk_bf16_f32 v36, v36, v37
	v_cvt_pk_bf16_f32 v37, v38, v39
	global_store_dwordx2 v[70:71], v[36:37], off offset:256
	s_and_saveexec_b64 s[28:29], s[18:19]
	s_cbranch_execz .LBB0_555
	v_lshl_add_u64 v[38:39], v[56:57], 2, s[68:69]
	s_waitcnt lgkmcnt(1)
	v_add_f32_e32 v32, v32, v34
	v_lshl_add_u64 v[36:37], v[58:59], 2, s[68:69]
	s_waitcnt lgkmcnt(0)
	v_add_f32_e32 v33, v33, v35
	global_atomic_add_f32 v[38:39], v32, off
	global_atomic_add_f32 v[36:37], v33, off
; __device__ __forceinline__ unsigned cvt_pk_bf16(float lo, float hi) { unsigned r; asm volatile("v_cvt_pk_bf16_f32 %0, %1, %2" : "=v"(r) : "v"(lo), "v"(hi)); return r; }
;     __device__ __forceinline__ void operator()(const f32x4 (&acc)[2][2][4][2], const Unit& u, int wr, int wc, int fr, int fq) const {
;     ...
;             for (int m = 0; m < 4; ++m) { const int ra = rowA + ai * HALF + m * 16, rb = rowB + ai * HALF + m * 16; const size_t offA = (size_t)ra * 1024 + col0, offB = (size_t)rb * 1024 + col0;
;                 float ssa = 0.f, ssb = 0.f;
; #pragma unroll
;                 for (int bj = 0; bj < 2; ++bj) {
;                     const f32x4 x0 = acc[ai][bj][m][0], x1 = acc[ai][bj][m][1]; f32x4 za, zb;
; #pragma unroll
;                     for (int e = 0; e < 4; ++e) { const float s1 = __shfl_xor(x1[e], 8), s0 = __shfl_xor(x0[e], 8); za[e] = hi8 ? s1 : x0[e]; zb[e] = hi8 ? x1[e] : s0; }
;                     const f32x4 ba = *(const f32x4*)(base + offA + bj * HALF), bb = *(const f32x4*)(base + offB + bj * HALF);
;                     const f32x4 oa = ba + gs[bj] * za, ob = bb + gs[bj] * zb;
;                     *(f32x4*)(out + offA + bj * HALF) = oa; *(f32x4*)(out + offB + bj * HALF) = ob;
;                     const f32x4 ha = oa * av[bj], hb = ob * av[bj];
;                     *(unsigned long long*)(Hn + offA + bj * HALF) = (unsigned long long)cvt_pk_bf16(ha[0], ha[1]) | ((unsigned long long)cvt_pk_bf16(ha[2], ha[3]) << 32);
;                     *(unsigned long long*)(Hn + offB + bj * HALF) = (unsigned long long)cvt_pk_bf16(hb[0], hb[1]) | ((unsigned long long)cvt_pk_bf16(hb[2], hb[3]) << 32);
;                     ssa += (oa[0] * oa[0] + oa[1] * oa[1]) + (oa[2] * oa[2] + oa[3] * oa[3]); ssb += (ob[0] * ob[0] + ob[1] * ob[1]) + (ob[2] * ob[2] + ob[3] * ob[3]); }
;                 ssa += __shfl_xor(ssa, 8); ssa += __shfl_xor(ssa, 16); ssa += __shfl_xor(ssa, 32);
;                 ssb += __shfl_xor(ssb, 8); ssb += __shfl_xor(ssb, 16); ssb += __shfl_xor(ssb, 32);
;                 if (fq == 0 && hi8 == 0) { atomicAdd(rowss + ra, ssa); atomicAdd(rowss + rb, ssb); } }
.LBB0_555:
	s_or_b64 exec, exec, s[28:29]
	v_add_u32_e32 v32, 0xa0, v150
	s_waitcnt lgkmcnt(1)
	v_add_u32_e32 v34, 0xa8, v150
	v_ashrrev_i32_e32 v33, 31, v32
	v_lshlrev_b64 v[36:37], 10, v[32:33]
	s_waitcnt lgkmcnt(0)
	v_ashrrev_i32_e32 v35, 31, v34
	v_readlane_b32 s52, v252, 18
	v_lshl_add_u64 v[44:45], v[36:37], 0, v[148:149]
	v_lshlrev_b64 v[36:37], 10, v[34:35]
	v_readlane_b32 s53, v252, 19
	v_lshl_add_u64 v[46:47], v[36:37], 0, v[148:149]
	v_lshlrev_b64 v[56:57], 2, v[44:45]
	s_mov_b64 s[36:37], s[52:53]
	v_lshl_add_u64 v[58:59], s[36:37], 0, v[56:57]
	v_lshlrev_b64 v[60:61], 2, v[46:47]
	global_load_dwordx4 v[36:39], v[58:59], off
	v_lshl_add_u64 v[62:63], s[36:37], 0, v[60:61]
	global_load_dwordx4 v[40:43], v[62:63], off
	ds_bpermute_b32 v64, v162, v24
	ds_bpermute_b32 v65, v162, v28
	ds_bpermute_b32 v66, v162, v25
	ds_bpermute_b32 v67, v162, v29
	ds_bpermute_b32 v68, v162, v26
	ds_bpermute_b32 v70, v162, v27
	ds_bpermute_b32 v69, v162, v30
	ds_bpermute_b32 v71, v162, v31
	v_readlane_b32 s54, v252, 20
	v_readlane_b32 s55, v252, 21
	v_readlane_b32 s56, v252, 22
	v_readlane_b32 s57, v252, 23
	v_readlane_b32 s58, v252, 24
	v_readlane_b32 s59, v252, 25
	v_readlane_b32 s60, v252, 26
	v_readlane_b32 s61, v252, 27
	v_readlane_b32 s62, v252, 28
	v_readlane_b32 s63, v252, 29
	v_readlane_b32 s64, v252, 30
	v_readlane_b32 s65, v252, 31
	v_readlane_b32 s66, v252, 32
	v_readlane_b32 s67, v252, 33
	v_readlane_b32 s52, v252, 2
	s_waitcnt lgkmcnt(7)
	v_cndmask_b32_e64 v28, v64, v28, s[0:1]
	s_waitcnt lgkmcnt(6)
	v_cndmask_b32_e64 v64, v24, v65, s[0:1]
	s_waitcnt lgkmcnt(5)
	v_cndmask_b32_e64 v29, v66, v29, s[0:1]
	s_waitcnt lgkmcnt(4)
	v_cndmask_b32_e64 v65, v25, v67, s[0:1]
	s_waitcnt lgkmcnt(3)
	v_cndmask_b32_e64 v24, v68, v30, s[0:1]
	s_waitcnt lgkmcnt(2)
	v_cndmask_b32_e64 v25, v70, v31, s[0:1]
	v_readlane_b32 s62, v252, 12
	v_readlane_b32 s63, v252, 13
	v_readlane_b32 s66, v252, 16
	v_readlane_b32 s67, v252, 17
	s_waitcnt lgkmcnt(1)
	v_cndmask_b32_e64 v30, v26, v69, s[0:1]
	s_waitcnt lgkmcnt(0)
	v_cndmask_b32_e64 v31, v27, v71, s[0:1]
	s_mov_b64 s[62:63], s[66:67]
	v_lshl_add_u64 v[44:45], v[44:45], 1, s[4:5]
	v_lshl_add_u64 v[46:47], v[46:47], 1, s[4:5]
	v_lshl_add_u64 v[56:57], s[62:63], 0, v[56:57]
	v_lshl_add_u64 v[60:61], s[62:63], 0, v[60:61]
	ds_bpermute_b32 v66, v162, v19
	ds_bpermute_b32 v67, v162, v23
	v_readlane_b32 s53, v252, 3
	v_readlane_b32 s54, v252, 4
	v_readlane_b32 s55, v252, 5
	v_readlane_b32 s56, v252, 6
	v_readlane_b32 s57, v252, 7
	v_readlane_b32 s58, v252, 8
	v_readlane_b32 s59, v252, 9
	v_readlane_b32 s60, v252, 10
	v_readlane_b32 s61, v252, 11
	v_readlane_b32 s64, v252, 14
	v_readlane_b32 s65, v252, 15
	s_waitcnt vmcnt(1)
	v_pk_fma_f32 v[26:27], v[50:51], v[24:25], v[38:39]
	v_pk_fma_f32 v[24:25], v[48:49], v[28:29], v[36:37]
	s_waitcnt vmcnt(0)
	v_pk_fma_f32 v[30:31], v[50:51], v[30:31], v[42:43]
	v_pk_fma_f32 v[28:29], v[48:49], v[64:65], v[40:41]
	v_pk_mul_f32 v[36:37], v[128:129], v[26:27]
	v_pk_mul_f32 v[38:39], v[130:131], v[24:25]
	global_store_dwordx4 v[56:57], v[24:27], off sc1
	global_store_dwordx4 v[60:61], v[28:31], off sc1
	v_pk_mul_f32 v[40:41], v[128:129], v[30:31]
	v_pk_mul_f32 v[42:43], v[130:131], v[28:29]
	v_cvt_pk_bf16_f32 v38, v38, v39
	v_cvt_pk_bf16_f32 v39, v36, v37
	global_store_dwordx2 v[44:45], v[38:39], off
	v_cvt_pk_bf16_f32 v36, v42, v43
	v_cvt_pk_bf16_f32 v37, v40, v41
	global_store_dwordx2 v[46:47], v[36:37], off
	global_load_dwordx4 v[36:39], v[58:59], off offset:512
	s_nop 0
	global_load_dwordx4 v[40:43], v[62:63], off offset:512
	ds_bpermute_b32 v58, v162, v16
	ds_bpermute_b32 v59, v162, v20
	ds_bpermute_b32 v63, v162, v21
	ds_bpermute_b32 v64, v162, v18
	ds_bpermute_b32 v65, v162, v22
	ds_bpermute_b32 v62, v162, v17
	s_waitcnt lgkmcnt(5)
	v_cndmask_b32_e64 v20, v58, v20, s[0:1]
	s_waitcnt lgkmcnt(4)
	v_cndmask_b32_e64 v58, v16, v59, s[0:1]
	s_waitcnt lgkmcnt(3)
	v_cndmask_b32_e64 v59, v17, v63, s[0:1]
	s_waitcnt lgkmcnt(2)
	v_cndmask_b32_e64 v16, v64, v22, s[0:1]
	s_waitcnt lgkmcnt(1)
	v_cndmask_b32_e64 v22, v18, v65, s[0:1]
	v_cndmask_b32_e64 v17, v66, v23, s[0:1]
	v_cndmask_b32_e64 v23, v19, v67, s[0:1]
	v_mul_f32_e32 v18, v25, v25
	v_mul_f32_e32 v19, v27, v27
	s_waitcnt lgkmcnt(0)
	v_cndmask_b32_e64 v21, v62, v21, s[0:1]
	v_mul_f32_e32 v25, v29, v29
	v_mul_f32_e32 v27, v31, v31
	v_fmac_f32_e32 v18, v24, v24
	v_fmac_f32_e32 v19, v26, v26
	v_fmac_f32_e32 v25, v28, v28
	v_fmac_f32_e32 v27, v30, v30
	v_add_f32_e32 v24, v18, v19
	v_add_f32_e32 v25, v25, v27
	s_waitcnt vmcnt(1)
	v_pk_fma_f32 v[18:19], v[54:55], v[16:17], v[38:39]
	v_pk_fma_f32 v[16:17], v[52:53], v[20:21], v[36:37]
	s_waitcnt vmcnt(0)
	v_pk_fma_f32 v[22:23], v[54:55], v[22:23], v[42:43]
	v_pk_fma_f32 v[20:21], v[52:53], v[58:59], v[40:41]
	v_mul_f32_e32 v26, v17, v17
	v_mul_f32_e32 v27, v19, v19
	v_mul_f32_e32 v28, v21, v21
	v_mul_f32_e32 v29, v23, v23
	v_fmac_f32_e32 v26, v16, v16
	v_fmac_f32_e32 v27, v18, v18
	v_fmac_f32_e32 v28, v20, v20
	v_fmac_f32_e32 v29, v22, v22
	v_add_f32_e32 v26, v26, v27
	v_add_f32_e32 v27, v28, v29
	v_add_f32_e32 v24, v24, v26
	v_add_f32_e32 v25, v25, v27
	ds_bpermute_b32 v26, v162, v24
	ds_bpermute_b32 v27, v162, v25
	global_store_dwordx4 v[56:57], v[16:19], off offset:512 sc1
	global_store_dwordx4 v[60:61], v[20:23], off offset:512 sc1
	s_waitcnt lgkmcnt(1)
	v_add_f32_e32 v26, v24, v26
	s_waitcnt lgkmcnt(0)
	v_add_f32_e32 v27, v25, v27
	ds_bpermute_b32 v28, v133, v26
	ds_bpermute_b32 v29, v133, v27
	v_pk_mul_f32 v[16:17], v[120:121], v[16:17]
	v_pk_mul_f32 v[18:19], v[122:123], v[18:19]
	v_cvt_pk_bf16_f32 v24, v16, v17
	s_waitcnt lgkmcnt(1)
	v_add_f32_e32 v16, v26, v28
	s_waitcnt lgkmcnt(0)
	v_add_f32_e32 v17, v27, v29
	v_cvt_pk_bf16_f32 v25, v18, v19
	ds_bpermute_b32 v18, v132, v16
	ds_bpermute_b32 v19, v132, v17
	v_pk_mul_f32 v[20:21], v[120:121], v[20:21]
	v_pk_mul_f32 v[22:23], v[122:123], v[22:23]
	global_store_dwordx2 v[44:45], v[24:25], off offset:256
	v_cvt_pk_bf16_f32 v20, v20, v21
	v_cvt_pk_bf16_f32 v21, v22, v23
	global_store_dwordx2 v[46:47], v[20:21], off offset:256
	s_and_saveexec_b64 s[28:29], s[18:19]
	s_cbranch_execz .LBB0_557
	v_lshl_add_u64 v[22:23], v[32:33], 2, s[68:69]
	s_waitcnt lgkmcnt(1)
	v_add_f32_e32 v16, v16, v18
	v_lshl_add_u64 v[20:21], v[34:35], 2, s[68:69]
	s_waitcnt lgkmcnt(0)
	v_add_f32_e32 v17, v17, v19
	global_atomic_add_f32 v[22:23], v16, off
	global_atomic_add_f32 v[20:21], v17, off
; __device__ __forceinline__ unsigned cvt_pk_bf16(float lo, float hi) { unsigned r; asm volatile("v_cvt_pk_bf16_f32 %0, %1, %2" : "=v"(r) : "v"(lo), "v"(hi)); return r; }
;     __device__ __forceinline__ void operator()(const f32x4 (&acc)[2][2][4][2], const Unit& u, int wr, int wc, int fr, int fq) const {
;     ...
;             for (int m = 0; m < 4; ++m) { const int ra = rowA + ai * HALF + m * 16, rb = rowB + ai * HALF + m * 16; const size_t offA = (size_t)ra * 1024 + col0, offB = (size_t)rb * 1024 + col0;
;                 float ssa = 0.f, ssb = 0.f;
; #pragma unroll
;                 for (int bj = 0; bj < 2; ++bj) {
;                     const f32x4 x0 = acc[ai][bj][m][0], x1 = acc[ai][bj][m][1]; f32x4 za, zb;
; #pragma unroll
;                     for (int e = 0; e < 4; ++e) { const float s1 = __shfl_xor(x1[e], 8), s0 = __shfl_xor(x0[e], 8); za[e] = hi8 ? s1 : x0[e]; zb[e] = hi8 ? x1[e] : s0; }
;                     const f32x4 ba = *(const f32x4*)(base + offA + bj * HALF), bb = *(const f32x4*)(base + offB + bj * HALF);
;                     const f32x4 oa = ba + gs[bj] * za, ob = bb + gs[bj] * zb;
;                     *(f32x4*)(out + offA + bj * HALF) = oa; *(f32x4*)(out + offB + bj * HALF) = ob;
;                     const f32x4 ha = oa * av[bj], hb = ob * av[bj];
;                     *(unsigned long long*)(Hn + offA + bj * HALF) = (unsigned long long)cvt_pk_bf16(ha[0], ha[1]) | ((unsigned long long)cvt_pk_bf16(ha[2], ha[3]) << 32);
;                     *(unsigned long long*)(Hn + offB + bj * HALF) = (unsigned long long)cvt_pk_bf16(hb[0], hb[1]) | ((unsigned long long)cvt_pk_bf16(hb[2], hb[3]) << 32);
;                     ssa += (oa[0] * oa[0] + oa[1] * oa[1]) + (oa[2] * oa[2] + oa[3] * oa[3]); ssb += (ob[0] * ob[0] + ob[1] * ob[1]) + (ob[2] * ob[2] + ob[3] * ob[3]); }
;                 ssa += __shfl_xor(ssa, 8); ssa += __shfl_xor(ssa, 16); ssa += __shfl_xor(ssa, 32);
;                 ssb += __shfl_xor(ssb, 8); ssb += __shfl_xor(ssb, 16); ssb += __shfl_xor(ssb, 32);
;                 if (fq == 0 && hi8 == 0) { atomicAdd(rowss + ra, ssa); atomicAdd(rowss + rb, ssb); } }
.LBB0_557:
	s_or_b64 exec, exec, s[28:29]
	v_add_u32_e32 v16, 0xb0, v150
	s_waitcnt lgkmcnt(1)
	v_add_u32_e32 v18, 0xb8, v150
	v_ashrrev_i32_e32 v17, 31, v16
	v_lshlrev_b64 v[20:21], 10, v[16:17]
	s_waitcnt lgkmcnt(0)
	v_ashrrev_i32_e32 v19, 31, v18
	v_readlane_b32 s52, v252, 18
	v_lshl_add_u64 v[28:29], v[20:21], 0, v[148:149]
	v_lshlrev_b64 v[20:21], 10, v[18:19]
	v_readlane_b32 s53, v252, 19
	v_lshl_add_u64 v[30:31], v[20:21], 0, v[148:149]
	v_lshlrev_b64 v[32:33], 2, v[28:29]
	s_mov_b64 s[36:37], s[52:53]
	v_lshl_add_u64 v[34:35], s[36:37], 0, v[32:33]
	v_lshlrev_b64 v[36:37], 2, v[30:31]
	global_load_dwordx4 v[20:23], v[34:35], off
	v_lshl_add_u64 v[38:39], s[36:37], 0, v[36:37]
	global_load_dwordx4 v[24:27], v[38:39], off
	ds_bpermute_b32 v40, v162, v8
	ds_bpermute_b32 v41, v162, v12
	ds_bpermute_b32 v42, v162, v9
	ds_bpermute_b32 v43, v162, v13
	ds_bpermute_b32 v44, v162, v10
	ds_bpermute_b32 v46, v162, v11
	ds_bpermute_b32 v45, v162, v14
	ds_bpermute_b32 v47, v162, v15
	v_readlane_b32 s54, v252, 20
	v_readlane_b32 s55, v252, 21
	v_readlane_b32 s56, v252, 22
	v_readlane_b32 s57, v252, 23
	v_readlane_b32 s58, v252, 24
	v_readlane_b32 s59, v252, 25
	v_readlane_b32 s60, v252, 26
	v_readlane_b32 s61, v252, 27
	v_readlane_b32 s62, v252, 28
	v_readlane_b32 s63, v252, 29
	v_readlane_b32 s64, v252, 30
	v_readlane_b32 s65, v252, 31
	v_readlane_b32 s66, v252, 32
	v_readlane_b32 s67, v252, 33
	v_readlane_b32 s52, v252, 2
	s_waitcnt lgkmcnt(7)
	v_cndmask_b32_e64 v12, v40, v12, s[0:1]
	s_waitcnt lgkmcnt(6)
	v_cndmask_b32_e64 v40, v8, v41, s[0:1]
	s_waitcnt lgkmcnt(5)
	v_cndmask_b32_e64 v13, v42, v13, s[0:1]
	s_waitcnt lgkmcnt(4)
	v_cndmask_b32_e64 v41, v9, v43, s[0:1]
	s_waitcnt lgkmcnt(3)
	v_cndmask_b32_e64 v8, v44, v14, s[0:1]
	s_waitcnt lgkmcnt(2)
	v_cndmask_b32_e64 v9, v46, v15, s[0:1]
	v_readlane_b32 s62, v252, 12
	v_readlane_b32 s63, v252, 13
	v_readlane_b32 s66, v252, 16
	v_readlane_b32 s67, v252, 17
	s_waitcnt lgkmcnt(1)
	v_cndmask_b32_e64 v14, v10, v45, s[0:1]
	s_waitcnt lgkmcnt(0)
	v_cndmask_b32_e64 v15, v11, v47, s[0:1]
	s_mov_b64 s[62:63], s[66:67]
	v_lshl_add_u64 v[28:29], v[28:29], 1, s[4:5]
	v_lshl_add_u64 v[30:31], v[30:31], 1, s[4:5]
	v_lshl_add_u64 v[32:33], s[62:63], 0, v[32:33]
	v_lshl_add_u64 v[36:37], s[62:63], 0, v[36:37]
	ds_bpermute_b32 v42, v162, v3
	ds_bpermute_b32 v43, v162, v7
	v_readlane_b32 s53, v252, 3
	v_readlane_b32 s54, v252, 4
	v_readlane_b32 s55, v252, 5
	v_readlane_b32 s56, v252, 6
	v_readlane_b32 s57, v252, 7
	v_readlane_b32 s58, v252, 8
	v_readlane_b32 s59, v252, 9
	v_readlane_b32 s60, v252, 10
	v_readlane_b32 s61, v252, 11
	v_readlane_b32 s64, v252, 14
	v_readlane_b32 s65, v252, 15
	s_waitcnt vmcnt(1)
	v_pk_fma_f32 v[10:11], v[50:51], v[8:9], v[22:23]
	v_pk_fma_f32 v[8:9], v[48:49], v[12:13], v[20:21]
	s_waitcnt vmcnt(0)
	v_pk_fma_f32 v[14:15], v[50:51], v[14:15], v[26:27]
	v_pk_fma_f32 v[12:13], v[48:49], v[40:41], v[24:25]
	v_pk_mul_f32 v[20:21], v[128:129], v[10:11]
	v_pk_mul_f32 v[22:23], v[130:131], v[8:9]
	global_store_dwordx4 v[32:33], v[8:11], off sc1
	global_store_dwordx4 v[36:37], v[12:15], off sc1
	v_pk_mul_f32 v[24:25], v[128:129], v[14:15]
	v_pk_mul_f32 v[26:27], v[130:131], v[12:13]
	v_cvt_pk_bf16_f32 v22, v22, v23
	v_cvt_pk_bf16_f32 v23, v20, v21
	global_store_dwordx2 v[28:29], v[22:23], off
	v_cvt_pk_bf16_f32 v20, v26, v27
	v_cvt_pk_bf16_f32 v21, v24, v25
	global_store_dwordx2 v[30:31], v[20:21], off
	global_load_dwordx4 v[20:23], v[34:35], off offset:512
	s_nop 0
	global_load_dwordx4 v[24:27], v[38:39], off offset:512
	ds_bpermute_b32 v34, v162, v0
	ds_bpermute_b32 v35, v162, v4
	ds_bpermute_b32 v39, v162, v5
	ds_bpermute_b32 v40, v162, v2
	ds_bpermute_b32 v41, v162, v6
	ds_bpermute_b32 v38, v162, v1
	s_waitcnt lgkmcnt(5)
	v_cndmask_b32_e64 v4, v34, v4, s[0:1]
	s_waitcnt lgkmcnt(4)
	v_cndmask_b32_e64 v34, v0, v35, s[0:1]
	s_waitcnt lgkmcnt(3)
	v_cndmask_b32_e64 v35, v1, v39, s[0:1]
	s_waitcnt lgkmcnt(2)
	v_cndmask_b32_e64 v0, v40, v6, s[0:1]
	s_waitcnt lgkmcnt(1)
	v_cndmask_b32_e64 v6, v2, v41, s[0:1]
	v_cndmask_b32_e64 v1, v42, v7, s[0:1]
	v_cndmask_b32_e64 v7, v3, v43, s[0:1]
	v_mul_f32_e32 v2, v9, v9
	v_mul_f32_e32 v3, v11, v11
	s_waitcnt lgkmcnt(0)
	v_cndmask_b32_e64 v5, v38, v5, s[0:1]
	v_mul_f32_e32 v9, v13, v13
	v_mul_f32_e32 v11, v15, v15
	v_fmac_f32_e32 v2, v8, v8
	v_fmac_f32_e32 v3, v10, v10
	v_fmac_f32_e32 v9, v12, v12
	v_fmac_f32_e32 v11, v14, v14
	v_add_f32_e32 v8, v2, v3
	v_add_f32_e32 v9, v9, v11
	s_waitcnt vmcnt(1)
	v_pk_fma_f32 v[2:3], v[54:55], v[0:1], v[22:23]
	v_pk_fma_f32 v[0:1], v[52:53], v[4:5], v[20:21]
	s_waitcnt vmcnt(0)
	v_pk_fma_f32 v[6:7], v[54:55], v[6:7], v[26:27]
	v_pk_fma_f32 v[4:5], v[52:53], v[34:35], v[24:25]
	v_mul_f32_e32 v10, v1, v1
	v_mul_f32_e32 v11, v3, v3
	v_mul_f32_e32 v12, v5, v5
	v_mul_f32_e32 v13, v7, v7
	v_fmac_f32_e32 v10, v0, v0
	v_fmac_f32_e32 v11, v2, v2
	v_fmac_f32_e32 v12, v4, v4
	v_fmac_f32_e32 v13, v6, v6
	v_add_f32_e32 v10, v10, v11
	v_add_f32_e32 v11, v12, v13
	v_add_f32_e32 v8, v8, v10
	v_add_f32_e32 v9, v9, v11
	ds_bpermute_b32 v10, v162, v8
	ds_bpermute_b32 v11, v162, v9
	global_store_dwordx4 v[32:33], v[0:3], off offset:512 sc1
	global_store_dwordx4 v[36:37], v[4:7], off offset:512 sc1
	s_waitcnt lgkmcnt(1)
	v_add_f32_e32 v10, v8, v10
	s_waitcnt lgkmcnt(0)
	v_add_f32_e32 v11, v9, v11
	ds_bpermute_b32 v12, v133, v10
	ds_bpermute_b32 v13, v133, v11
	v_pk_mul_f32 v[0:1], v[120:121], v[0:1]
	v_pk_mul_f32 v[2:3], v[122:123], v[2:3]
	v_cvt_pk_bf16_f32 v8, v0, v1
	s_waitcnt lgkmcnt(1)
	v_add_f32_e32 v0, v10, v12
	s_waitcnt lgkmcnt(0)
	v_add_f32_e32 v1, v11, v13
	v_cvt_pk_bf16_f32 v9, v2, v3
	ds_bpermute_b32 v2, v132, v0
	ds_bpermute_b32 v3, v132, v1
	v_pk_mul_f32 v[4:5], v[120:121], v[4:5]
	v_pk_mul_f32 v[6:7], v[122:123], v[6:7]
	global_store_dwordx2 v[28:29], v[8:9], off offset:256
	v_cvt_pk_bf16_f32 v4, v4, v5
	v_cvt_pk_bf16_f32 v5, v6, v7
	global_store_dwordx2 v[30:31], v[4:5], off offset:256
	s_and_saveexec_b64 s[28:29], s[18:19]
	s_cbranch_execz .LBB0_559
	v_lshl_add_u64 v[6:7], v[16:17], 2, s[68:69]
	s_waitcnt lgkmcnt(1)
	v_add_f32_e32 v0, v0, v2
	v_lshl_add_u64 v[4:5], v[18:19], 2, s[68:69]
	s_waitcnt lgkmcnt(0)
	v_add_f32_e32 v1, v1, v3
	global_atomic_add_f32 v[6:7], v0, off
	global_atomic_add_f32 v[4:5], v1, off

;     __device__ __forceinline__ void operator()(const f32x4 (&acc)[2][2][4][2], const Unit& u, int wr, int wc, int fr, int fq) const {
;         const int hi8 = fr >> 3;
;         const int rowA = u.pm * BM + wr * 64 + (fr & 7), rowB = rowA + 8; const int col0 = u.pn * BM + wc * 32 + 16 * hi8 + 4 * fq;
;         const float* gb = gate + (size_t)((u.pm * BM) / 8192) * 3072 + col0;
;         f32x4 gs[2];
; #pragma unroll
;         for (int bj = 0; bj < 2; ++bj) gs[bj] = *(const f32x4*)(gb + bj * HALF);
; #pragma unroll
;         for (int ai = 0; ai < 2; ++ai)
; #pragma unroll
;             for (int m = 0; m < 4; ++m) { const size_t offA = (size_t)(rowA + ai * HALF + m * 16) * 1024 + col0, offB = (size_t)(rowB + ai * HALF + m * 16) * 1024 + col0;
; #pragma unroll
;                 for (int bj = 0; bj < 2; ++bj) {
;                     const f32x4 x0 = acc[ai][bj][m][0], x1 = acc[ai][bj][m][1]; f32x4 za, zb;
; #pragma unroll
;                     for (int e = 0; e < 4; ++e) {
;                         const float s1 = __shfl_xor(x1[e], 8), s0 = __shfl_xor(x0[e], 8);
;                         za[e] = hi8 ? s1 : x0[e];
;                         zb[e] = hi8 ? x1[e] : s0; }
;                     const f32x4 ba = *(const f32x4*)(base + offA + bj * HALF), bb = *(const f32x4*)(base + offB + bj * HALF);
;                     *(f32x4*)(out + offA + bj * HALF) = ba + gs[bj] * za;
;                     *(f32x4*)(out + offB + bj * HALF) = bb + gs[bj] * zb; } }
.LBB0_819:
	s_ashr_i32 s27, s36, 31
	s_lshr_b32 s27, s27, 27
	s_add_i32 s27, s36, s27
	v_lshl_add_u32 v152, s36, 8, v159
	s_ashr_i32 s27, s27, 5
	v_readlane_b32 s76, v252, 2
	v_lshl_add_u32 v104, s64, 8, v160
	s_mul_hi_i32 s29, s27, 0x3000
	s_mulk_i32 s27, 0x3000
	v_ashrrev_i32_e32 v153, 31, v152
	v_readlane_b32 s90, v252, 16
	v_readlane_b32 s91, v252, 17
	s_add_u32 s38, s49, s27
	v_ashrrev_i32_e32 v105, 31, v104
	v_or_b32_e32 v110, 8, v152
	v_lshlrev_b64 v[148:149], 12, v[152:153]
	s_mov_b64 s[66:67], s[90:91]
	s_addc_u32 s39, s50, s29
	v_lshlrev_b64 v[150:151], 2, v[104:105]
	v_ashrrev_i32_e32 v111, 31, v110
	v_lshl_add_u64 v[148:149], s[66:67], 0, v[148:149]
	v_lshl_add_u64 v[108:109], s[38:39], 0, v[150:151]
	v_lshl_add_u64 v[148:149], v[148:149], 0, v[150:151]
	v_lshlrev_b64 v[110:111], 12, v[110:111]
	global_load_dwordx4 v[104:107], v[108:109], off
	global_load_dwordx4 v[166:169], v[148:149], off
	v_lshl_add_u64 v[110:111], s[66:67], 0, v[110:111]
	v_lshl_add_u64 v[156:157], v[110:111], 0, v[150:151]
	global_load_dwordx4 v[170:173], v[156:157], off
	s_nop 0
	global_load_dwordx4 v[108:111], v[108:109], off offset:512
	s_nop 0
	global_load_dwordx4 v[174:177], v[148:149], off offset:512
	global_load_dwordx4 v[178:181], v[156:157], off offset:512
	v_and_b32_e32 v154, 64, v164
	v_xor_b32_e32 v153, 8, v164
	v_add_u32_e32 v155, 64, v154
	v_or_b32_e32 v154, 16, v152
	v_cmp_lt_i32_e32 vcc, v153, v155
	v_ashrrev_i32_e32 v155, 31, v154
	v_lshlrev_b64 v[154:155], 12, v[154:155]
	v_or_b32_e32 v186, 24, v152
	v_lshl_add_u64 v[154:155], s[66:67], 0, v[154:155]
	v_ashrrev_i32_e32 v187, 31, v186
	v_lshl_add_u64 v[198:199], v[154:155], 0, v[150:151]
	global_load_dwordx4 v[182:185], v[198:199], off
	v_lshlrev_b64 v[154:155], 12, v[186:187]
	v_lshl_add_u64 v[154:155], s[66:67], 0, v[154:155]
	v_lshl_add_u64 v[154:155], v[154:155], 0, v[150:151]
	global_load_dwordx4 v[186:189], v[154:155], off
	global_load_dwordx4 v[190:193], v[198:199], off offset:512
	global_load_dwordx4 v[194:197], v[154:155], off offset:512
	v_cndmask_b32_e32 v153, v164, v153, vcc
	v_lshlrev_b32_e32 v153, 2, v153
	ds_bpermute_b32 v165, v153, v128
	ds_bpermute_b32 v201, v153, v129
	ds_bpermute_b32 v203, v153, v130
	ds_bpermute_b32 v205, v153, v131
	ds_bpermute_b32 v200, v153, v132
	ds_bpermute_b32 v202, v153, v133
	ds_bpermute_b32 v204, v153, v134
	ds_bpermute_b32 v206, v153, v135
	ds_bpermute_b32 v207, v153, v120
	ds_bpermute_b32 v208, v153, v124
	ds_bpermute_b32 v209, v153, v121
	ds_bpermute_b32 v210, v153, v125
	ds_bpermute_b32 v211, v153, v122
	ds_bpermute_b32 v212, v153, v126
	ds_bpermute_b32 v213, v153, v123
	ds_bpermute_b32 v214, v153, v127
	s_waitcnt lgkmcnt(0)
	v_cndmask_b32_e64 v132, v165, v132, s[0:1]
	v_cndmask_b32_e64 v133, v201, v133, s[0:1]
	v_cndmask_b32_e64 v134, v203, v134, s[0:1]
	v_cndmask_b32_e64 v135, v205, v135, s[0:1]
	v_cndmask_b32_e64 v128, v128, v200, s[0:1]
	v_cndmask_b32_e64 v129, v129, v202, s[0:1]
	v_cndmask_b32_e64 v130, v130, v204, s[0:1]
	v_cndmask_b32_e64 v131, v131, v206, s[0:1]
	v_cndmask_b32_e64 v200, v207, v124, s[0:1]
	v_cndmask_b32_e64 v202, v120, v208, s[0:1]
	v_cndmask_b32_e64 v201, v209, v125, s[0:1]
	v_cndmask_b32_e64 v203, v121, v210, s[0:1]
	v_cndmask_b32_e64 v204, v211, v126, s[0:1]
	v_cndmask_b32_e64 v206, v122, v212, s[0:1]
	v_cndmask_b32_e64 v205, v213, v127, s[0:1]
	v_cndmask_b32_e64 v207, v123, v214, s[0:1]
	ds_bpermute_b32 v165, v153, v112
	v_readlane_b32 s77, v252, 3
	v_readlane_b32 s78, v252, 4
	v_readlane_b32 s79, v252, 5
	v_readlane_b32 s80, v252, 6
	v_readlane_b32 s81, v252, 7
	v_readlane_b32 s82, v252, 8
	v_readlane_b32 s83, v252, 9
	v_readlane_b32 s84, v252, 10
	v_readlane_b32 s85, v252, 11
	v_readlane_b32 s86, v252, 12
	v_readlane_b32 s87, v252, 13
	v_readlane_b32 s88, v252, 14
	v_readlane_b32 s89, v252, 15
	s_waitcnt vmcnt(0)
	v_pk_fma_f32 v[122:123], v[106:107], v[134:135], v[168:169]
	v_pk_fma_f32 v[120:121], v[104:105], v[132:133], v[166:167]
	v_pk_fma_f32 v[126:127], v[106:107], v[130:131], v[172:173]
	v_pk_fma_f32 v[124:125], v[104:105], v[128:129], v[170:171]
	v_pk_fma_f32 v[130:131], v[110:111], v[204:205], v[176:177]
	v_pk_fma_f32 v[128:129], v[108:109], v[200:201], v[174:175]
	global_store_dwordx4 v[148:149], v[120:123], off sc1
	global_store_dwordx4 v[156:157], v[124:127], off sc1
	global_store_dwordx4 v[148:149], v[128:131], off offset:512 sc1
	v_or_b32_e32 v120, 32, v152
	v_ashrrev_i32_e32 v121, 31, v120
	v_lshlrev_b64 v[120:121], 12, v[120:121]
	v_or_b32_e32 v126, 40, v152
	v_lshl_add_u64 v[120:121], s[66:67], 0, v[120:121]
	v_ashrrev_i32_e32 v127, 31, v126
	v_lshl_add_u64 v[134:135], v[120:121], 0, v[150:151]
	global_load_dwordx4 v[122:125], v[134:135], off
	v_lshlrev_b64 v[120:121], 12, v[126:127]
	v_lshl_add_u64 v[120:121], s[66:67], 0, v[120:121]
	v_lshl_add_u64 v[120:121], v[120:121], 0, v[150:151]
	ds_bpermute_b32 v166, v153, v116
	global_load_dwordx4 v[126:129], v[120:121], off
	v_pk_fma_f32 v[132:133], v[110:111], v[206:207], v[180:181]
	v_pk_fma_f32 v[130:131], v[108:109], v[202:203], v[178:179]
	ds_bpermute_b32 v167, v153, v113
	global_store_dwordx4 v[156:157], v[130:133], off offset:512 sc1
	s_waitcnt lgkmcnt(1)
	v_cndmask_b32_e64 v156, v112, v166, s[0:1]
	ds_bpermute_b32 v112, v153, v117
	ds_bpermute_b32 v130, v153, v114
	ds_bpermute_b32 v132, v153, v115
	ds_bpermute_b32 v131, v153, v118
	ds_bpermute_b32 v133, v153, v119
	v_cndmask_b32_e64 v116, v165, v116, s[0:1]
	s_waitcnt lgkmcnt(5)
	v_cndmask_b32_e64 v117, v167, v117, s[0:1]
	s_waitcnt lgkmcnt(4)
	v_cndmask_b32_e64 v157, v113, v112, s[0:1]
	s_waitcnt lgkmcnt(3)
	v_cndmask_b32_e64 v112, v130, v118, s[0:1]
	s_waitcnt lgkmcnt(2)
;     __device__ __forceinline__ void operator()(const f32x4 (&acc)[2][2][4][2], const Unit& u, int wr, int wc, int fr, int fq) const {
;     ...
;             for (int m = 0; m < 4; ++m) { const size_t offA = (size_t)(rowA + ai * HALF + m * 16) * 1024 + col0, offB = (size_t)(rowB + ai * HALF + m * 16) * 1024 + col0;
; #pragma unroll
;                 for (int bj = 0; bj < 2; ++bj) {
;                     const f32x4 x0 = acc[ai][bj][m][0], x1 = acc[ai][bj][m][1]; f32x4 za, zb;
; #pragma unroll
;                     for (int e = 0; e < 4; ++e) {
;                         const float s1 = __shfl_xor(x1[e], 8), s0 = __shfl_xor(x0[e], 8);
;                         za[e] = hi8 ? s1 : x0[e];
;                         zb[e] = hi8 ? x1[e] : s0; }
;                     const f32x4 ba = *(const f32x4*)(base + offA + bj * HALF), bb = *(const f32x4*)(base + offB + bj * HALF);
;                     *(f32x4*)(out + offA + bj * HALF) = ba + gs[bj] * za;
;                     *(f32x4*)(out + offB + bj * HALF) = bb + gs[bj] * zb; } }
	v_cndmask_b32_e64 v113, v132, v119, s[0:1]
	s_waitcnt lgkmcnt(1)
	v_cndmask_b32_e64 v130, v114, v131, s[0:1]
	s_waitcnt lgkmcnt(0)
	v_cndmask_b32_e64 v131, v115, v133, s[0:1]
	v_pk_fma_f32 v[114:115], v[106:107], v[112:113], v[184:185]
	v_pk_fma_f32 v[112:113], v[104:105], v[116:117], v[182:183]
	global_load_dwordx4 v[116:119], v[134:135], off offset:512
	ds_bpermute_b32 v166, v153, v100
	global_store_dwordx4 v[198:199], v[112:115], off sc1
	ds_bpermute_b32 v165, v153, v96
	s_waitcnt lgkmcnt(0)
	v_cndmask_b32_e64 v100, v165, v100, s[0:1]
	v_pk_fma_f32 v[114:115], v[106:107], v[130:131], v[188:189]
	global_load_dwordx4 v[130:133], v[120:121], off offset:512
	v_pk_fma_f32 v[112:113], v[104:105], v[156:157], v[186:187]
	ds_bpermute_b32 v157, v153, v97
	global_store_dwordx4 v[154:155], v[112:115], off sc1
	v_cndmask_b32_e64 v156, v96, v166, s[0:1]
	ds_bpermute_b32 v96, v153, v101
	ds_bpermute_b32 v112, v153, v98
	ds_bpermute_b32 v114, v153, v99
	ds_bpermute_b32 v113, v153, v102
	ds_bpermute_b32 v115, v153, v103
	s_waitcnt lgkmcnt(5)
	v_cndmask_b32_e64 v101, v157, v101, s[0:1]
	s_waitcnt lgkmcnt(4)
	v_cndmask_b32_e64 v157, v97, v96, s[0:1]
	s_waitcnt lgkmcnt(3)
	v_cndmask_b32_e64 v96, v112, v102, s[0:1]
	s_waitcnt lgkmcnt(2)
	v_cndmask_b32_e64 v97, v114, v103, s[0:1]
	s_waitcnt lgkmcnt(1)
	v_cndmask_b32_e64 v102, v98, v113, s[0:1]
	s_waitcnt lgkmcnt(0)
	v_cndmask_b32_e64 v103, v99, v115, s[0:1]
	v_pk_fma_f32 v[98:99], v[110:111], v[96:97], v[192:193]
	v_pk_fma_f32 v[96:97], v[108:109], v[100:101], v[190:191]
	global_store_dwordx4 v[198:199], v[96:99], off offset:512 sc1
	v_pk_fma_f32 v[100:101], v[110:111], v[102:103], v[196:197]
	s_nop 0
	v_or_b32_e32 v96, 48, v152
	v_ashrrev_i32_e32 v97, 31, v96
	v_or_b32_e32 v98, 56, v152
	v_lshlrev_b64 v[96:97], 12, v[96:97]
	v_lshl_add_u64 v[96:97], s[66:67], 0, v[96:97]
	v_ashrrev_i32_e32 v99, 31, v98
	v_lshl_add_u64 v[102:103], v[96:97], 0, v[150:151]
	v_lshlrev_b64 v[96:97], 12, v[98:99]
	v_lshl_add_u64 v[96:97], s[66:67], 0, v[96:97]
	global_load_dwordx4 v[112:115], v[102:103], off
	v_lshl_add_u64 v[96:97], v[96:97], 0, v[150:151]
	ds_bpermute_b32 v150, v153, v88
	ds_bpermute_b32 v151, v153, v92
	global_load_dwordx4 v[166:169], v[96:97], off
	v_pk_fma_f32 v[98:99], v[108:109], v[156:157], v[194:195]
	ds_bpermute_b32 v152, v153, v89
	global_store_dwordx4 v[154:155], v[98:101], off offset:512 sc1
	s_waitcnt lgkmcnt(2)
	v_cndmask_b32_e64 v92, v150, v92, s[0:1]
	s_waitcnt lgkmcnt(1)
	v_cndmask_b32_e64 v150, v88, v151, s[0:1]
	ds_bpermute_b32 v88, v153, v93
	ds_bpermute_b32 v98, v153, v90
	ds_bpermute_b32 v100, v153, v91
	ds_bpermute_b32 v99, v153, v94
	ds_bpermute_b32 v101, v153, v95
	s_waitcnt lgkmcnt(5)
	v_cndmask_b32_e64 v93, v152, v93, s[0:1]
	s_waitcnt lgkmcnt(4)
	v_cndmask_b32_e64 v151, v89, v88, s[0:1]
	s_waitcnt lgkmcnt(3)
	v_cndmask_b32_e64 v88, v98, v94, s[0:1]
	s_waitcnt lgkmcnt(2)
	v_cndmask_b32_e64 v89, v100, v95, s[0:1]
	s_waitcnt lgkmcnt(1)
	v_cndmask_b32_e64 v98, v90, v99, s[0:1]
	s_waitcnt lgkmcnt(0)
	v_cndmask_b32_e64 v99, v91, v101, s[0:1]
	s_waitcnt vmcnt(10)
	v_pk_fma_f32 v[90:91], v[106:107], v[88:89], v[124:125]
	v_pk_fma_f32 v[88:89], v[104:105], v[92:93], v[122:123]
	global_load_dwordx4 v[92:95], v[102:103], off offset:512
	ds_bpermute_b32 v122, v153, v80
	ds_bpermute_b32 v123, v153, v84
	global_store_dwordx4 v[134:135], v[88:91], off sc1
	ds_bpermute_b32 v124, v153, v81
	ds_bpermute_b32 v125, v153, v76
	s_waitcnt vmcnt(11)
	v_pk_fma_f32 v[90:91], v[106:107], v[98:99], v[128:129]
	global_load_dwordx4 v[98:101], v[96:97], off offset:512
	v_pk_fma_f32 v[88:89], v[104:105], v[150:151], v[126:127]
	global_store_dwordx4 v[120:121], v[88:91], off sc1
	s_waitcnt lgkmcnt(3)
	v_cndmask_b32_e64 v84, v122, v84, s[0:1]
	s_waitcnt lgkmcnt(2)
	v_cndmask_b32_e64 v122, v80, v123, s[0:1]
	ds_bpermute_b32 v80, v153, v85
	ds_bpermute_b32 v88, v153, v82
	ds_bpermute_b32 v90, v153, v83
	ds_bpermute_b32 v89, v153, v86
	ds_bpermute_b32 v91, v153, v87
	s_waitcnt lgkmcnt(6)
	v_cndmask_b32_e64 v85, v124, v85, s[0:1]
	s_waitcnt lgkmcnt(4)
	v_cndmask_b32_e64 v123, v81, v80, s[0:1]
	s_waitcnt lgkmcnt(3)
	v_cndmask_b32_e64 v80, v88, v86, s[0:1]
	s_waitcnt lgkmcnt(2)
	v_cndmask_b32_e64 v81, v90, v87, s[0:1]
	s_waitcnt lgkmcnt(1)
	v_cndmask_b32_e64 v86, v82, v89, s[0:1]
	s_waitcnt lgkmcnt(0)
	v_cndmask_b32_e64 v87, v83, v91, s[0:1]
	s_waitcnt vmcnt(11)
	v_pk_fma_f32 v[82:83], v[110:111], v[80:81], v[118:119]
	v_pk_fma_f32 v[80:81], v[108:109], v[84:85], v[116:117]
	v_add_co_u32_e32 v116, vcc, s56, v148
	global_store_dwordx4 v[134:135], v[80:83], off offset:512 sc1
	s_nop 0
	v_addc_co_u32_e32 v117, vcc, 0, v149, vcc
	v_add_co_u32_e32 v118, vcc, s57, v148
	s_waitcnt vmcnt(10)
	v_pk_fma_f32 v[82:83], v[110:111], v[86:87], v[132:133]
	global_load_dwordx4 v[84:87], v[116:117], off
	v_addc_co_u32_e32 v119, vcc, 0, v149, vcc
	global_load_dwordx4 v[88:91], v[118:119], off
	v_pk_fma_f32 v[80:81], v[108:109], v[122:123], v[130:131]
	ds_bpermute_b32 v124, v153, v72
	ds_bpermute_b32 v122, v153, v73
	global_store_dwordx4 v[120:121], v[80:83], off offset:512 sc1
	v_cndmask_b32_e64 v120, v72, v125, s[0:1]
	ds_bpermute_b32 v72, v153, v77
	ds_bpermute_b32 v80, v153, v74
	ds_bpermute_b32 v82, v153, v75
	ds_bpermute_b32 v81, v153, v78
	ds_bpermute_b32 v83, v153, v79
	s_waitcnt lgkmcnt(6)
	v_cndmask_b32_e64 v76, v124, v76, s[0:1]
	s_waitcnt lgkmcnt(5)
	v_cndmask_b32_e64 v77, v122, v77, s[0:1]
	s_waitcnt lgkmcnt(4)
	v_cndmask_b32_e64 v121, v73, v72, s[0:1]
	s_waitcnt lgkmcnt(3)
	v_cndmask_b32_e64 v72, v80, v78, s[0:1]
	s_waitcnt lgkmcnt(2)
	v_cndmask_b32_e64 v73, v82, v79, s[0:1]
	s_waitcnt lgkmcnt(1)
;     __device__ __forceinline__ void operator()(const f32x4 (&acc)[2][2][4][2], const Unit& u, int wr, int wc, int fr, int fq) const {
;     ...
;             for (int m = 0; m < 4; ++m) { const size_t offA = (size_t)(rowA + ai * HALF + m * 16) * 1024 + col0, offB = (size_t)(rowB + ai * HALF + m * 16) * 1024 + col0;
; #pragma unroll
;                 for (int bj = 0; bj < 2; ++bj) {
;                     const f32x4 x0 = acc[ai][bj][m][0], x1 = acc[ai][bj][m][1]; f32x4 za, zb;
; #pragma unroll
;                     for (int e = 0; e < 4; ++e) {
;                         const float s1 = __shfl_xor(x1[e], 8), s0 = __shfl_xor(x0[e], 8);
;                         za[e] = hi8 ? s1 : x0[e];
;                         zb[e] = hi8 ? x1[e] : s0; }
;                     const f32x4 ba = *(const f32x4*)(base + offA + bj * HALF), bb = *(const f32x4*)(base + offB + bj * HALF);
;                     *(f32x4*)(out + offA + bj * HALF) = ba + gs[bj] * za;
;                     *(f32x4*)(out + offB + bj * HALF) = bb + gs[bj] * zb; } }
	v_cndmask_b32_e64 v78, v74, v81, s[0:1]
	s_waitcnt lgkmcnt(0)
	v_cndmask_b32_e64 v79, v75, v83, s[0:1]
	ds_bpermute_b32 v123, v153, v68
	ds_bpermute_b32 v122, v153, v64
	s_waitcnt vmcnt(10)
	v_pk_fma_f32 v[74:75], v[106:107], v[72:73], v[114:115]
	v_pk_fma_f32 v[72:73], v[104:105], v[76:77], v[112:113]
	v_lshl_add_u64 v[112:113], v[148:149], 0, s[10:11]
	global_store_dwordx4 v[102:103], v[72:75], off sc1
	global_load_dwordx4 v[72:75], v[112:113], off offset:512
	v_lshl_add_u64 v[114:115], v[148:149], 0, s[12:13]
	global_load_dwordx4 v[80:83], v[114:115], off offset:512
	s_waitcnt vmcnt(12)
	v_pk_fma_f32 v[78:79], v[106:107], v[78:79], v[168:169]
	v_pk_fma_f32 v[76:77], v[104:105], v[120:121], v[166:167]
	ds_bpermute_b32 v121, v153, v65
	global_store_dwordx4 v[96:97], v[76:79], off sc1
	s_waitcnt lgkmcnt(2)
	v_cndmask_b32_e64 v120, v64, v123, s[0:1]
	ds_bpermute_b32 v64, v153, v69
	ds_bpermute_b32 v76, v153, v66
	ds_bpermute_b32 v78, v153, v67
	ds_bpermute_b32 v77, v153, v70
	ds_bpermute_b32 v79, v153, v71
	s_waitcnt lgkmcnt(6)
	v_cndmask_b32_e64 v68, v122, v68, s[0:1]
	s_waitcnt lgkmcnt(5)
	v_cndmask_b32_e64 v69, v121, v69, s[0:1]
	s_waitcnt lgkmcnt(4)
	v_cndmask_b32_e64 v121, v65, v64, s[0:1]
	s_waitcnt lgkmcnt(3)
	v_cndmask_b32_e64 v64, v76, v70, s[0:1]
	s_waitcnt lgkmcnt(2)
	v_cndmask_b32_e64 v65, v78, v71, s[0:1]
	s_waitcnt lgkmcnt(1)
	v_cndmask_b32_e64 v70, v66, v77, s[0:1]
	s_waitcnt lgkmcnt(0)
	v_cndmask_b32_e64 v71, v67, v79, s[0:1]
	s_waitcnt vmcnt(11)
	v_pk_fma_f32 v[66:67], v[110:111], v[64:65], v[94:95]
	v_pk_fma_f32 v[64:65], v[108:109], v[68:69], v[92:93]
	v_add_co_u32_e32 v92, vcc, s58, v148
	global_store_dwordx4 v[102:103], v[64:67], off offset:512 sc1
	s_nop 0
	v_addc_co_u32_e32 v93, vcc, 0, v149, vcc
	v_add_co_u32_e32 v94, vcc, s59, v148
	s_waitcnt vmcnt(10)
	v_pk_fma_f32 v[66:67], v[110:111], v[70:71], v[100:101]
	global_load_dwordx4 v[68:71], v[92:93], off
	v_addc_co_u32_e32 v95, vcc, 0, v149, vcc
	global_load_dwordx4 v[76:79], v[94:95], off
	ds_bpermute_b32 v101, v153, v60
	v_pk_fma_f32 v[64:65], v[108:109], v[120:121], v[98:99]
	ds_bpermute_b32 v100, v153, v56
	ds_bpermute_b32 v98, v153, v57
	global_store_dwordx4 v[96:97], v[64:67], off offset:512 sc1
	ds_bpermute_b32 v66, v153, v58
	ds_bpermute_b32 v96, v153, v59
	s_waitcnt lgkmcnt(4)
	v_cndmask_b32_e64 v64, v56, v101, s[0:1]
	ds_bpermute_b32 v56, v153, v61
	ds_bpermute_b32 v67, v153, v62
	ds_bpermute_b32 v97, v153, v63
	s_waitcnt lgkmcnt(6)
	v_cndmask_b32_e64 v60, v100, v60, s[0:1]
	s_waitcnt lgkmcnt(5)
	v_cndmask_b32_e64 v61, v98, v61, s[0:1]
	s_waitcnt lgkmcnt(2)
	v_cndmask_b32_e64 v65, v57, v56, s[0:1]
	v_cndmask_b32_e64 v56, v66, v62, s[0:1]
	v_cndmask_b32_e64 v57, v96, v63, s[0:1]
	s_waitcnt lgkmcnt(1)
	v_cndmask_b32_e64 v62, v58, v67, s[0:1]
	s_waitcnt lgkmcnt(0)
	v_cndmask_b32_e64 v63, v59, v97, s[0:1]
	s_waitcnt vmcnt(10)
	v_pk_fma_f32 v[58:59], v[106:107], v[56:57], v[86:87]
	v_pk_fma_f32 v[56:57], v[104:105], v[60:61], v[84:85]
	global_store_dwordx4 v[116:117], v[56:59], off sc1
	ds_bpermute_b32 v60, v153, v48
	ds_bpermute_b32 v61, v153, v52
	s_waitcnt vmcnt(10)
	v_pk_fma_f32 v[58:59], v[106:107], v[62:63], v[90:91]
	ds_bpermute_b32 v62, v153, v49
	v_pk_fma_f32 v[56:57], v[104:105], v[64:65], v[88:89]
	s_waitcnt lgkmcnt(2)
	v_cndmask_b32_e64 v64, v60, v52, s[0:1]
	s_waitcnt lgkmcnt(1)
	v_cndmask_b32_e64 v66, v48, v61, s[0:1]
	ds_bpermute_b32 v48, v153, v53
	s_waitcnt lgkmcnt(1)
	v_cndmask_b32_e64 v65, v62, v53, s[0:1]
	v_lshl_add_u64 v[52:53], v[148:149], 0, s[14:15]
	global_store_dwordx4 v[118:119], v[56:59], off sc1
	global_load_dwordx4 v[56:59], v[52:53], off offset:512
	v_lshl_add_u64 v[84:85], v[148:149], 0, s[16:17]
	global_load_dwordx4 v[60:63], v[84:85], off offset:512
	ds_bpermute_b32 v86, v153, v50
	ds_bpermute_b32 v88, v153, v51
	ds_bpermute_b32 v87, v153, v54
	ds_bpermute_b32 v89, v153, v55
	s_waitcnt lgkmcnt(4)
	v_cndmask_b32_e64 v67, v49, v48, s[0:1]
	s_waitcnt lgkmcnt(3)
	v_cndmask_b32_e64 v48, v86, v54, s[0:1]
	s_waitcnt lgkmcnt(2)
	v_cndmask_b32_e64 v49, v88, v55, s[0:1]
	s_waitcnt lgkmcnt(1)
	v_cndmask_b32_e64 v54, v50, v87, s[0:1]
	s_waitcnt lgkmcnt(0)
	v_cndmask_b32_e64 v55, v51, v89, s[0:1]
	ds_bpermute_b32 v86, v153, v41
	ds_bpermute_b32 v90, v153, v34
	s_waitcnt vmcnt(10)
	v_pk_fma_f32 v[50:51], v[110:111], v[48:49], v[74:75]
	v_pk_fma_f32 v[48:49], v[108:109], v[64:65], v[72:73]
	global_store_dwordx4 v[112:113], v[48:51], off offset:512 sc1
	ds_bpermute_b32 v91, v153, v38
	s_waitcnt vmcnt(10)
	v_pk_fma_f32 v[50:51], v[110:111], v[54:55], v[82:83]
	v_add_co_u32_e32 v54, vcc, s60, v148
	ds_bpermute_b32 v82, v153, v40
	ds_bpermute_b32 v83, v153, v44
	v_addc_co_u32_e32 v55, vcc, 0, v149, vcc
	v_pk_fma_f32 v[48:49], v[108:109], v[66:67], v[80:81]
	global_load_dwordx4 v[64:67], v[54:55], off
	v_add_co_u32_e32 v80, vcc, s61, v148
	global_store_dwordx4 v[114:115], v[48:51], off offset:512 sc1
	s_nop 0
	v_addc_co_u32_e32 v81, vcc, 0, v149, vcc
	global_load_dwordx4 v[72:75], v[80:81], off
	s_waitcnt lgkmcnt(1)
	v_cndmask_b32_e64 v44, v82, v44, s[0:1]
	s_waitcnt lgkmcnt(0)
	v_cndmask_b32_e64 v82, v40, v83, s[0:1]
	ds_bpermute_b32 v40, v153, v45
	ds_bpermute_b32 v48, v153, v42
	ds_bpermute_b32 v50, v153, v43
	ds_bpermute_b32 v49, v153, v46
	ds_bpermute_b32 v51, v153, v47
	v_cndmask_b32_e64 v45, v86, v45, s[0:1]
	s_waitcnt lgkmcnt(4)
	v_cndmask_b32_e64 v83, v41, v40, s[0:1]
	s_waitcnt lgkmcnt(3)
	v_cndmask_b32_e64 v40, v48, v46, s[0:1]
	s_waitcnt lgkmcnt(2)
	v_cndmask_b32_e64 v41, v50, v47, s[0:1]
	s_waitcnt lgkmcnt(1)
	v_cndmask_b32_e64 v46, v42, v49, s[0:1]
	s_waitcnt lgkmcnt(0)
	v_cndmask_b32_e64 v47, v43, v51, s[0:1]
	s_waitcnt vmcnt(10)
;     __device__ __forceinline__ void operator()(const f32x4 (&acc)[2][2][4][2], const Unit& u, int wr, int wc, int fr, int fq) const {
;     ...
;             for (int m = 0; m < 4; ++m) { const size_t offA = (size_t)(rowA + ai * HALF + m * 16) * 1024 + col0, offB = (size_t)(rowB + ai * HALF + m * 16) * 1024 + col0;
; #pragma unroll
;                 for (int bj = 0; bj < 2; ++bj) {
;                     const f32x4 x0 = acc[ai][bj][m][0], x1 = acc[ai][bj][m][1]; f32x4 za, zb;
; #pragma unroll
;                     for (int e = 0; e < 4; ++e) {
;                         const float s1 = __shfl_xor(x1[e], 8), s0 = __shfl_xor(x0[e], 8);
;                         za[e] = hi8 ? s1 : x0[e];
;                         zb[e] = hi8 ? x1[e] : s0; }
;                     const f32x4 ba = *(const f32x4*)(base + offA + bj * HALF), bb = *(const f32x4*)(base + offB + bj * HALF);
;                     *(f32x4*)(out + offA + bj * HALF) = ba + gs[bj] * za;
;                     *(f32x4*)(out + offB + bj * HALF) = bb + gs[bj] * zb; } }
	v_pk_fma_f32 v[42:43], v[106:107], v[40:41], v[70:71]
	v_pk_fma_f32 v[40:41], v[104:105], v[44:45], v[68:69]
	v_lshl_add_u64 v[86:87], v[148:149], 0, s[18:19]
	global_store_dwordx4 v[92:93], v[40:43], off sc1
	global_load_dwordx4 v[40:43], v[86:87], off offset:512
	s_waitcnt vmcnt(11)
	v_pk_fma_f32 v[46:47], v[106:107], v[46:47], v[78:79]
	v_lshl_add_u64 v[78:79], v[148:149], 0, s[20:21]
	global_load_dwordx4 v[48:51], v[78:79], off offset:512
	ds_bpermute_b32 v68, v153, v32
	ds_bpermute_b32 v69, v153, v36
	ds_bpermute_b32 v70, v153, v33
	v_pk_fma_f32 v[44:45], v[104:105], v[82:83], v[76:77]
	v_add_co_u32_e32 v82, vcc, s62, v148
	global_store_dwordx4 v[94:95], v[44:47], off sc1
	s_nop 0
	v_addc_co_u32_e32 v83, vcc, 0, v149, vcc
	v_add_co_u32_e32 v88, vcc, s63, v148
	global_load_dwordx4 v[44:47], v[82:83], off
	s_nop 0
	v_addc_co_u32_e32 v89, vcc, 0, v149, vcc
	s_waitcnt lgkmcnt(2)
	v_cndmask_b32_e64 v36, v68, v36, s[0:1]
	s_waitcnt lgkmcnt(1)
	v_cndmask_b32_e64 v76, v32, v69, s[0:1]
	ds_bpermute_b32 v32, v153, v37
	s_waitcnt lgkmcnt(1)
	v_cndmask_b32_e64 v37, v70, v37, s[0:1]
	global_load_dwordx4 v[68:71], v[88:89], off
	ds_bpermute_b32 v92, v153, v35
	ds_bpermute_b32 v93, v153, v39
	s_waitcnt lgkmcnt(2)
	v_cndmask_b32_e64 v77, v33, v32, s[0:1]
	v_cndmask_b32_e64 v32, v90, v38, s[0:1]
	v_cndmask_b32_e64 v38, v34, v91, s[0:1]
	s_waitcnt lgkmcnt(1)
	v_cndmask_b32_e64 v33, v92, v39, s[0:1]
	s_waitcnt lgkmcnt(0)
	v_cndmask_b32_e64 v39, v35, v93, s[0:1]
	s_waitcnt vmcnt(11)
	v_pk_fma_f32 v[34:35], v[110:111], v[32:33], v[58:59]
	v_pk_fma_f32 v[32:33], v[108:109], v[36:37], v[56:57]
	ds_bpermute_b32 v36, v153, v24
	ds_bpermute_b32 v37, v153, v28
	global_store_dwordx4 v[52:53], v[32:35], off offset:512 sc1
	v_lshl_add_u64 v[56:57], v[148:149], 0, s[22:23]
	v_lshl_add_u64 v[58:59], v[148:149], 0, s[24:25]
	s_waitcnt vmcnt(11)
	v_pk_fma_f32 v[34:35], v[110:111], v[38:39], v[62:63]
	v_pk_fma_f32 v[32:33], v[108:109], v[76:77], v[60:61]
	global_store_dwordx4 v[84:85], v[32:35], off offset:512 sc1
	global_load_dwordx4 v[32:35], v[56:57], off offset:512
	s_waitcnt lgkmcnt(1)
	v_cndmask_b32_e64 v28, v36, v28, s[0:1]
	s_waitcnt lgkmcnt(0)
	v_cndmask_b32_e64 v52, v24, v37, s[0:1]
	global_load_dwordx4 v[36:39], v[58:59], off offset:512
	ds_bpermute_b32 v24, v153, v25
	ds_bpermute_b32 v53, v153, v29
	ds_bpermute_b32 v61, v153, v27
	ds_bpermute_b32 v60, v153, v30
	ds_bpermute_b32 v62, v153, v31
	s_waitcnt lgkmcnt(4)
	v_cndmask_b32_e64 v29, v24, v29, s[0:1]
	ds_bpermute_b32 v24, v153, v26
	s_waitcnt lgkmcnt(4)
	v_cndmask_b32_e64 v53, v25, v53, s[0:1]
	s_waitcnt lgkmcnt(3)
	v_cndmask_b32_e64 v25, v61, v31, s[0:1]
	s_waitcnt lgkmcnt(1)
	v_cndmask_b32_e64 v31, v27, v62, s[0:1]
	s_andn2_b64 vcc, exec, s[2:3]
	s_waitcnt lgkmcnt(0)
	v_cndmask_b32_e64 v24, v24, v30, s[0:1]
	v_cndmask_b32_e64 v30, v26, v60, s[0:1]
	s_waitcnt vmcnt(12)
	v_pk_fma_f32 v[26:27], v[106:107], v[24:25], v[66:67]
	v_pk_fma_f32 v[24:25], v[104:105], v[28:29], v[64:65]
	ds_bpermute_b32 v28, v153, v8
	ds_bpermute_b32 v29, v153, v16
	global_store_dwordx4 v[54:55], v[24:27], off sc1
	s_mov_b64 s[2:3], -1
	s_waitcnt lgkmcnt(1)
	v_cndmask_b32_e64 v16, v28, v16, s[0:1]
	s_waitcnt vmcnt(11)
	v_pk_fma_f32 v[26:27], v[106:107], v[30:31], v[74:75]
	v_pk_fma_f32 v[24:25], v[104:105], v[52:53], v[72:73]
	ds_bpermute_b32 v30, v153, v9
	global_store_dwordx4 v[80:81], v[24:27], off sc1
	ds_bpermute_b32 v26, v153, v10
	ds_bpermute_b32 v28, v153, v11
	s_waitcnt lgkmcnt(3)
	v_cndmask_b32_e64 v24, v8, v29, s[0:1]
	ds_bpermute_b32 v8, v153, v17
	ds_bpermute_b32 v27, v153, v18
	ds_bpermute_b32 v29, v153, v19
	s_waitcnt lgkmcnt(5)
	v_cndmask_b32_e64 v17, v30, v17, s[0:1]
	s_waitcnt lgkmcnt(2)
	v_cndmask_b32_e64 v25, v9, v8, s[0:1]
	v_cndmask_b32_e64 v8, v26, v18, s[0:1]
	v_cndmask_b32_e64 v9, v28, v19, s[0:1]
	s_waitcnt lgkmcnt(1)
	v_cndmask_b32_e64 v18, v10, v27, s[0:1]
	s_waitcnt lgkmcnt(0)
	v_cndmask_b32_e64 v19, v11, v29, s[0:1]
	s_waitcnt vmcnt(10)
	v_pk_fma_f32 v[10:11], v[110:111], v[8:9], v[42:43]
	v_pk_fma_f32 v[8:9], v[108:109], v[16:17], v[40:41]
	ds_bpermute_b32 v17, v153, v20
	global_store_dwordx4 v[86:87], v[8:11], off offset:512 sc1
	ds_bpermute_b32 v16, v153, v12
	s_waitcnt lgkmcnt(1)
	v_cndmask_b32_e64 v12, v12, v17, s[0:1]
	s_waitcnt vmcnt(10)
	v_pk_fma_f32 v[10:11], v[110:111], v[18:19], v[50:51]
	ds_bpermute_b32 v18, v153, v13
	v_pk_fma_f32 v[8:9], v[108:109], v[24:25], v[48:49]
	global_store_dwordx4 v[78:79], v[8:11], off offset:512 sc1
	ds_bpermute_b32 v10, v153, v21
	ds_bpermute_b32 v11, v153, v14
	ds_bpermute_b32 v17, v153, v15
	s_waitcnt lgkmcnt(4)
	v_cndmask_b32_e64 v8, v16, v20, s[0:1]
	s_waitcnt lgkmcnt(3)
	v_cndmask_b32_e64 v9, v18, v21, s[0:1]
	ds_bpermute_b32 v16, v153, v22
	ds_bpermute_b32 v18, v153, v23
	s_waitcnt lgkmcnt(4)
	v_cndmask_b32_e64 v13, v13, v10, s[0:1]
	s_waitcnt lgkmcnt(3)
	v_cndmask_b32_e64 v10, v11, v22, s[0:1]
	s_waitcnt lgkmcnt(2)
	v_cndmask_b32_e64 v11, v17, v23, s[0:1]
	s_waitcnt lgkmcnt(1)
	v_cndmask_b32_e64 v14, v14, v16, s[0:1]
	s_waitcnt lgkmcnt(0)
	v_cndmask_b32_e64 v15, v15, v18, s[0:1]
	s_waitcnt vmcnt(9)
	v_pk_fma_f32 v[10:11], v[106:107], v[10:11], v[46:47]
	v_pk_fma_f32 v[8:9], v[104:105], v[8:9], v[44:45]
	global_store_dwordx4 v[82:83], v[8:11], off sc1
	s_waitcnt vmcnt(9)
	s_nop 0
	v_pk_fma_f32 v[10:11], v[106:107], v[14:15], v[70:71]
	ds_bpermute_b32 v15, v153, v4
	v_pk_fma_f32 v[8:9], v[104:105], v[12:13], v[68:69]
	ds_bpermute_b32 v12, v153, v1
	ds_bpermute_b32 v14, v153, v0
	global_store_dwordx4 v[88:89], v[8:11], off sc1
	ds_bpermute_b32 v10, v153, v2
	ds_bpermute_b32 v11, v153, v6
	s_waitcnt lgkmcnt(4)
	v_cndmask_b32_e64 v8, v0, v15, s[0:1]
	ds_bpermute_b32 v0, v153, v5
	s_waitcnt lgkmcnt(4)
	v_cndmask_b32_e64 v5, v12, v5, s[0:1]
	ds_bpermute_b32 v12, v153, v3
	ds_bpermute_b32 v13, v153, v7
	s_waitcnt lgkmcnt(5)
	v_cndmask_b32_e64 v4, v14, v4, s[0:1]
	s_waitcnt lgkmcnt(2)
	v_cndmask_b32_e64 v9, v1, v0, s[0:1]
	v_cndmask_b32_e64 v0, v10, v6, s[0:1]
	s_waitcnt lgkmcnt(1)
	v_cndmask_b32_e64 v1, v12, v7, s[0:1]
	v_cndmask_b32_e64 v6, v2, v11, s[0:1]
	s_waitcnt lgkmcnt(0)
	v_cndmask_b32_e64 v7, v3, v13, s[0:1]
	s_waitcnt vmcnt(7)
	v_pk_fma_f32 v[2:3], v[110:111], v[0:1], v[34:35]
	v_pk_fma_f32 v[0:1], v[108:109], v[4:5], v[32:33]
	global_store_dwordx4 v[56:57], v[0:3], off offset:512 sc1
	s_waitcnt vmcnt(7)
	s_nop 0
	v_pk_fma_f32 v[2:3], v[110:111], v[6:7], v[38:39]
	v_pk_fma_f32 v[0:1], v[108:109], v[8:9], v[36:37]
	global_store_dwordx4 v[58:59], v[0:3], off offset:512 sc1
	s_cbranch_vccnz .LBB0_808
	s_andn2_b64 vcc, exec, s[4:5]
	s_cbranch_vccnz .LBB0_807
	s_barrier
	s_branch .LBB0_807
